# ATT: K/V staging loads and q fragments prefetched; interior units use a hand-written path over the 17 live key blocks with ALiBi and window mask folded into the MFMA C operand
# speedup vs baseline: 1.0550x; 1.0008x over previous
; __device__ void att_phase(int wv, const Params& p, unsigned char* lds) {
;     ...
;     for (int unit = blockIdx.x; unit < 1024; unit += gridDim.x) {
;         const int B = unit >> 2, kh = unit & 3;
;         const int sb = B < 64 ? 0 : (B < 128 ? 64 : 128), se = B < 64 ? 64 : (B < 128 ? 128 : 256);
; #pragma unroll
;         for (int ps = 0; ps < 6; ++ps) { const int idx = tid + ps * NTHR, s = idx >> 3, c8 = (idx & 7) * 8; const int kb = B - 1 + (s >> 7);
;             bf16x8 kv = {0, 0, 0, 0, 0, 0, 0, 0}, vv = {0, 0, 0, 0, 0, 0, 0, 0};
;             if (kb >= sb && kb < se) { const bf16_t* rp = qkv + (size_t)(kb * 128 + (s & 127)) * 1536 + 64 * kh + c8; kv = *(const bf16x8*)(rp + 1024); vv = *(const bf16x8*)(rp + 1280); }
;             *(bf16x8*)(KL + s * KP + c8) = kv;
; #pragma unroll
;             for (int e = 0; e < 8; ++e) VTL[(c8 + e) * VP + s] = (bf16_t)vv[e]; }
;         __syncthreads();
;         const int gq = w >> 1, h = 4 * kh + gq;
;         const float slope = exp2f(-0.5f * (float)(h + 1)), sink = p.b_sinks[h];
.LBB0_293:
	s_ashr_i32 s23, s21, 2
	s_and_b32 s6, s21, 3
	s_cmpk_lt_i32 s23, 0x80
	s_movk_i32 s1, 0x100
	s_cselect_b32 s0, 64, 0x80
	s_cselect_b32 s1, 0x80, s1
	s_cmp_lt_i32 s23, 64
	s_cselect_b32 s11, 0, s0
	s_cselect_b32 s10, 64, s1
	s_add_i32 s7, s23, -1
	s_lshl_b32 s36, s6, 7
	v_lshl_add_u64 v[12:13], v[102:103], 0, s[36:37]
	v_add_u32_e32 v10, s7, v115
	v_cmp_le_i32_e32 vcc, s11, v10
	v_cmp_gt_i32_e64 s[0:1], s10, v10
	s_and_b64 s[14:15], vcc, s[0:1]
	v_mov_b32_e32 v180, 0
	v_mov_b32_e32 v181, 0
	v_mov_b32_e32 v182, 0
	v_mov_b32_e32 v183, 0
	v_mov_b32_e32 v184, 0
	v_mov_b32_e32 v185, 0
	v_mov_b32_e32 v186, 0
	v_mov_b32_e32 v187, 0
	s_and_saveexec_b64 s[0:1], s[14:15]
	s_cbranch_execz .Latt_ld_0
	v_lshl_or_b32 v2, v10, 7, v116
	s_movk_i32 s14, 0xc00
	v_mad_u64_u32 v[2:3], s[14:15], v2, s14, v[12:13]
	global_load_dwordx4 v[180:183], v[2:3], off offset:2048
	global_load_dwordx4 v[184:187], v[2:3], off offset:2560
.Latt_ld_0:
	s_or_b64 exec, exec, s[0:1]
	v_add_u32_e32 v10, s7, v117
	v_cmp_le_i32_e32 vcc, s11, v10
	v_cmp_gt_i32_e64 s[0:1], s10, v10
	s_and_b64 s[14:15], vcc, s[0:1]
	v_mov_b32_e32 v188, 0
	v_mov_b32_e32 v189, 0
	v_mov_b32_e32 v190, 0
	v_mov_b32_e32 v191, 0
	v_mov_b32_e32 v192, 0
	v_mov_b32_e32 v193, 0
	v_mov_b32_e32 v194, 0
	v_mov_b32_e32 v195, 0
	s_and_saveexec_b64 s[0:1], s[14:15]
	s_cbranch_execz .Latt_ld_1
	v_lshl_or_b32 v2, v10, 7, v118
	s_movk_i32 s14, 0xc00
	v_mad_u64_u32 v[2:3], s[14:15], v2, s14, v[12:13]
	global_load_dwordx4 v[188:191], v[2:3], off offset:2048
	global_load_dwordx4 v[192:195], v[2:3], off offset:2560
.Latt_ld_1:
	s_or_b64 exec, exec, s[0:1]
	v_add_u32_e32 v10, s7, v119
	v_cmp_le_i32_e32 vcc, s11, v10
	v_cmp_gt_i32_e64 s[0:1], s10, v10
	s_and_b64 s[14:15], vcc, s[0:1]
	v_mov_b32_e32 v196, 0
	v_mov_b32_e32 v197, 0
	v_mov_b32_e32 v198, 0
	v_mov_b32_e32 v199, 0
	v_mov_b32_e32 v200, 0
	v_mov_b32_e32 v201, 0
	v_mov_b32_e32 v202, 0
	v_mov_b32_e32 v203, 0
	s_and_saveexec_b64 s[0:1], s[14:15]
	s_cbranch_execz .Latt_ld_2
	v_lshl_or_b32 v2, v10, 7, v120
	s_movk_i32 s14, 0xc00
	v_mad_u64_u32 v[2:3], s[14:15], v2, s14, v[12:13]
	global_load_dwordx4 v[196:199], v[2:3], off offset:2048
	global_load_dwordx4 v[200:203], v[2:3], off offset:2560
.Latt_ld_2:
	s_or_b64 exec, exec, s[0:1]
	v_add_u32_e32 v10, s7, v121
	v_cmp_le_i32_e32 vcc, s11, v10
	v_cmp_gt_i32_e64 s[0:1], s10, v10
	s_and_b64 s[14:15], vcc, s[0:1]
	v_mov_b32_e32 v204, 0
	v_mov_b32_e32 v205, 0
	v_mov_b32_e32 v206, 0
	v_mov_b32_e32 v207, 0
	v_mov_b32_e32 v208, 0
	v_mov_b32_e32 v209, 0
	v_mov_b32_e32 v210, 0
	v_mov_b32_e32 v211, 0
	s_and_saveexec_b64 s[0:1], s[14:15]
	s_cbranch_execz .Latt_ld_3
	v_lshl_or_b32 v2, v10, 7, v122
	s_movk_i32 s14, 0xc00
	v_mad_u64_u32 v[2:3], s[14:15], v2, s14, v[12:13]
	global_load_dwordx4 v[204:207], v[2:3], off offset:2048
	global_load_dwordx4 v[208:211], v[2:3], off offset:2560
.Latt_ld_3:
	s_or_b64 exec, exec, s[0:1]
	v_add_u32_e32 v10, s7, v123
	v_cmp_le_i32_e32 vcc, s11, v10
	v_cmp_gt_i32_e64 s[0:1], s10, v10
	s_and_b64 s[14:15], vcc, s[0:1]
	v_mov_b32_e32 v212, 0
	v_mov_b32_e32 v213, 0
	v_mov_b32_e32 v214, 0
	v_mov_b32_e32 v215, 0
	v_mov_b32_e32 v216, 0
	v_mov_b32_e32 v217, 0
	v_mov_b32_e32 v218, 0
	v_mov_b32_e32 v219, 0
	s_and_saveexec_b64 s[0:1], s[14:15]
	s_cbranch_execz .Latt_ld_4
	v_lshl_or_b32 v2, v10, 7, v124
	s_movk_i32 s14, 0xc00
	v_mad_u64_u32 v[2:3], s[14:15], v2, s14, v[12:13]
	global_load_dwordx4 v[212:215], v[2:3], off offset:2048
	global_load_dwordx4 v[216:219], v[2:3], off offset:2560
.Latt_ld_4:
	s_or_b64 exec, exec, s[0:1]
	v_add_u32_e32 v10, s7, v125
	v_cmp_le_i32_e32 vcc, s11, v10
	v_cmp_gt_i32_e64 s[0:1], s10, v10
	s_and_b64 s[14:15], vcc, s[0:1]
	v_mov_b32_e32 v220, 0
	v_mov_b32_e32 v221, 0
	v_mov_b32_e32 v222, 0
	v_mov_b32_e32 v223, 0
	v_mov_b32_e32 v224, 0
	v_mov_b32_e32 v225, 0
	v_mov_b32_e32 v226, 0
	v_mov_b32_e32 v227, 0
	s_and_saveexec_b64 s[0:1], s[14:15]
	s_cbranch_execz .Latt_ld_5
	v_lshl_or_b32 v2, v10, 7, v126
	s_movk_i32 s14, 0xc00
	v_mad_u64_u32 v[2:3], s[14:15], v2, s14, v[12:13]
	global_load_dwordx4 v[220:223], v[2:3], off offset:2048
	global_load_dwordx4 v[224:227], v[2:3], off offset:2560
.Latt_ld_5:
	s_or_b64 exec, exec, s[0:1]
	s_mov_b32 s22, 0
	s_lshl_b32 s6, s6, 2
	s_add_i32 s6, s6, s16
	s_add_i32 s7, s6, 1
	s_waitcnt vmcnt(0)
	ds_write_b128 v129, v[180:183]
	ds_write_b16 v130, v184 offset:55296
	ds_write_b16_d16_hi v130, v184 offset:56080
	ds_write_b16 v130, v185 offset:56864
	ds_write_b16_d16_hi v130, v185 offset:57648
	ds_write_b16 v130, v186 offset:58432
	ds_write_b16_d16_hi v130, v186 offset:59216
	ds_write_b16 v130, v187 offset:60000
	ds_write_b16_d16_hi v130, v187 offset:60784
	ds_write_b128 v131, v[188:191]
	ds_write_b16 v132, v192 offset:55296
	ds_write_b16_d16_hi v132, v192 offset:56080
	ds_write_b16 v132, v193 offset:56864
	ds_write_b16_d16_hi v132, v193 offset:57648
	ds_write_b16 v132, v194 offset:58432
	ds_write_b16_d16_hi v132, v194 offset:59216
	ds_write_b16 v132, v195 offset:60000
	ds_write_b16_d16_hi v132, v195 offset:60784
	ds_write_b128 v133, v[196:199]
	ds_write_b16 v134, v200 offset:55296
	ds_write_b16_d16_hi v134, v200 offset:56080
	ds_write_b16 v134, v201 offset:56864
	ds_write_b16_d16_hi v134, v201 offset:57648
	ds_write_b16 v134, v202 offset:58432
	ds_write_b16_d16_hi v134, v202 offset:59216
	ds_write_b16 v134, v203 offset:60000
	ds_write_b16_d16_hi v134, v203 offset:60784
	ds_write_b128 v135, v[204:207]
	ds_write_b16 v136, v208 offset:55296
	ds_write_b16_d16_hi v136, v208 offset:56080
	ds_write_b16 v136, v209 offset:56864
	ds_write_b16_d16_hi v136, v209 offset:57648
	ds_write_b16 v136, v210 offset:58432
	ds_write_b16_d16_hi v136, v210 offset:59216
	ds_write_b16 v136, v211 offset:60000
	ds_write_b16_d16_hi v136, v211 offset:60784
	ds_write_b128 v137, v[212:215]
	ds_write_b16 v138, v216 offset:55296
	ds_write_b16_d16_hi v138, v216 offset:56080
	ds_write_b16 v138, v217 offset:56864
	ds_write_b16_d16_hi v138, v217 offset:57648
	ds_write_b16 v138, v218 offset:58432
	ds_write_b16_d16_hi v138, v218 offset:59216
	ds_write_b16 v138, v219 offset:60000
	ds_write_b16_d16_hi v138, v219 offset:60784
	ds_write_b128 v139, v[220:223]
	ds_write_b16 v140, v224 offset:55296
	ds_write_b16_d16_hi v140, v224 offset:56080
	ds_write_b16 v140, v225 offset:56864
	ds_write_b16_d16_hi v140, v225 offset:57648
	ds_write_b16 v140, v226 offset:58432
	ds_write_b16_d16_hi v140, v226 offset:59216
	ds_write_b16 v140, v227 offset:60000
	ds_write_b16_d16_hi v140, v227 offset:60784
	v_cvt_f32_i32_e32 v2, s7
	s_and_b32 s0, s20, 3
	s_lshl_b32 s0, s0, 8
	s_add_i32 s0, s17, s0
	s_ashr_i32 s1, s0, 31
	v_mul_f32_e32 v3, -0.5, v2
	s_mov_b32 s7, 0xc2fc0000
	s_lshl_b64 s[0:1], s[0:1], 1
	v_cmp_gt_f32_e32 vcc, s7, v3
	s_and_b64 s[14:15], vcc, exec
	s_cselect_b32 s14, 0xffffffc0, 0
	s_ashr_i32 s7, s6, 31
	s_lshl_b64 s[6:7], s[6:7], 2
	s_add_u32 s6, s58, s6
	s_addc_u32 s7, s59, s7
	s_waitcnt lgkmcnt(0)
	s_barrier
; __device__ __forceinline__ f32x4 mfma16(bf16x8 a, bf16x8 b, f32x4 c) { return __builtin_amdgcn_mfma_f32_16x16x32_bf16(a, b, c, 0, 0, 0); }
; __device__ void att_phase(int wv, const Params& p, unsigned char* lds) {
;     ...
;         const int gq = w >> 1, h = 4 * kh + gq;
;         const float slope = exp2f(-0.5f * (float)(h + 1)), sink = p.b_sinks[h];
;         for (int rb = 0; rb < 4; ++rb) {
;             const int qrow = 64 * (w & 1) + 16 * rb + lr;
;             const size_t tokq = (size_t)B * 128 + qrow;
;             bf16x8 qf[2];
; #pragma unroll
;             for (int kk = 0; kk < 2; ++kk) qf[kk] = *(const bf16x8*)(qkv + tokq * 1536 + 64 * h + 32 * kk + 8 * lq);
;             f32x4 sc[24];
; #pragma unroll
;             for (int cb = 0; cb < 24; ++cb) { f32x4 a = {0, 0, 0, 0};
; #pragma unroll
;                 for (int kk = 0; kk < 2; ++kk) { const bf16x8 kf = *(const bf16x8*)(KL + (16 * cb + lr) * KP + 32 * kk + 8 * lq); a = mfma16(kf, qf[kk], a); }
;                 sc[cb] = a; }
;             float mx = sink;
; #pragma unroll
;             for (int cb = 0; cb < 24; ++cb) { const int kb = B - 1 + (cb >> 3); const bool bval = (kb >= sb && kb < se);
; #pragma unroll
;                 for (int j = 0; j < 4; ++j) { const int krel = 16 * cb + 4 * lq + j - 128;
;                     int dist = qrow - krel; dist = dist < 0 ? -dist : dist;
;                     const float v = (bval && dist <= 128) ? sc[cb][j] * 0.125f - slope * (float)dist : -1e30f;
;                     sc[cb][j] = v; mx = fmaxf(mx, v); } }
	global_load_dword v146, v0, s[6:7]
	v_mov_b32_e32 v3, 0x42800000
	v_cndmask_b32_e32 v3, 0, v3, vcc
	v_fmac_f32_e32 v3, -0.5, v2
	v_exp_f32_e32 v2, v3
	s_cmp_gt_i32 s23, s11
	s_cselect_b64 s[6:7], -1, 0
	s_cmp_le_i32 s23, s10
	v_ldexp_f32 v109, v2, s14
	s_cselect_b64 s[14:15], -1, 0
	s_and_b64 s[6:7], s[6:7], s[14:15]
	s_cmp_ge_i32 s23, s11
	s_cselect_b64 s[14:15], -1, 0
	s_cmp_lt_i32 s23, s10
	s_cselect_b64 s[46:47], -1, 0
	s_and_b64 s[14:15], s[14:15], s[46:47]
	s_add_i32 s36, s23, 1
	s_cmp_ge_i32 s36, s11
	s_cselect_b64 s[46:47], -1, 0
	s_cmp_lt_i32 s36, s10
	s_cselect_b64 s[10:11], -1, 0
	v_mov_b32_e32 v2, 0x60000
	s_and_b64 s[10:11], s[46:47], s[10:11]
	v_mad_i64_i32 v[110:111], s[46:47], s23, v2, v[104:105]
	v_mad_i64_i32 v[112:113], s[46:47], s23, v2, v[106:107]
	v_mov_b32_e32 v147, v128
	s_mov_b64 s[48:49], 0xc000
	v_lshl_add_u64 v[174:175], v[110:111], 0, s[0:1]
	v_add_co_u32_e32 v174, vcc, 0x83ec000, v174
	s_nop 1
	v_addc_co_u32_e32 v175, vcc, 0, v175, vcc
	global_load_dwordx4 v[180:183], v[174:175], off offset:1536
	global_load_dwordx4 v[184:187], v[174:175], off offset:1600
	v_lshl_add_u64 v[174:175], v[174:175], 0, s[48:49]
	global_load_dwordx4 v[188:191], v[174:175], off offset:1536
	global_load_dwordx4 v[192:195], v[174:175], off offset:1600
	v_lshl_add_u64 v[174:175], v[174:175], 0, s[48:49]
	global_load_dwordx4 v[196:199], v[174:175], off offset:1536
	global_load_dwordx4 v[200:203], v[174:175], off offset:1600
	v_lshl_add_u64 v[174:175], v[174:175], 0, s[48:49]
	global_load_dwordx4 v[204:207], v[174:175], off offset:1536
	global_load_dwordx4 v[208:211], v[174:175], off offset:1600
	s_and_b64 vcc, s[6:7], s[10:11]
	s_cbranch_vccz .LBB0_306
	s_waitcnt vmcnt(0)
	s_mov_b32 s46, 0x3e38aa3b
	s_and_b32 s47, s33, 1
	s_mul_i32 s22, s47, 0x2400
	v_add_u32_e32 v164, s22, v141
	s_lshl_b32 s22, s47, 7
	s_add_i32 s22, s22, 0xd800
	v_add_u32_e32 v165, s22, v142
	v_add_u32_e32 v166, s22, v143
	v_add_u32_e32 v167, s22, v144
	v_add_u32_e32 v168, s22, v145
	v_and_b32_e32 v172, 15, v250
	v_lshrrev_b32_e32 v173, 4, v250
	v_lshlrev_b32_e32 v173, 2, v173
	v_sub_u32_e32 v108, v172, v173
	v_subrev_u32_e32 v110, 1, v108
	v_subrev_u32_e32 v111, 2, v108
	v_subrev_u32_e32 v177, 3, v108
	v_mul_f32_e32 v147, 0xc1000000, v109
	v_mul_f32_e32 v174, 0x43000000, v109
	v_mul_f32_e32 v176, 0x44800000, v109
	v_cvt_f32_i32_e32 v179, v108
	v_mul_f32_e32 v94, v147, v179
	v_mul_f32_e64 v98, v147, |v179|
	v_cvt_f32_i32_e32 v179, v110
	v_mul_f32_e32 v95, v147, v179
	v_mul_f32_e64 v99, v147, |v179|
	v_cvt_f32_i32_e32 v179, v111
	v_mul_f32_e32 v96, v147, v179
	v_mul_f32_e64 v100, v147, |v179|
	v_cvt_f32_i32_e32 v179, v177
	v_mul_f32_e32 v97, v147, v179
	v_mul_f32_e64 v101, v147, |v179|
	v_lshl_add_u64 v[248:249], v[112:113], 0, s[0:1]
	v_sub_f32_e32 v86, v94, v176
	v_sub_f32_e32 v87, v95, v176
	v_sub_f32_e32 v88, v96, v176
	v_sub_f32_e32 v89, v97, v176
	v_cmp_ge_i32_e32 vcc, 0, v108
	s_nop 1
	v_cndmask_b32_e32 v212, v252, v86, vcc
	v_cmp_ge_i32_e32 vcc, 0, v110
	s_nop 1
	v_cndmask_b32_e32 v213, v252, v87, vcc
	v_cmp_ge_i32_e32 vcc, 0, v111
	s_nop 1
	v_cndmask_b32_e32 v214, v252, v88, vcc
	v_cmp_ge_i32_e32 vcc, 0, v177
	s_nop 1
	v_cndmask_b32_e32 v215, v252, v89, vcc
	ds_read_b128 v[148:151], v164 offset:0
	ds_read_b128 v[152:155], v164 offset:64
	ds_read_b128 v[156:159], v164 offset:2304
	ds_read_b128 v[160:163], v164 offset:2368
	v_add_f32_e32 v90, v86, v174
	v_add_f32_e32 v91, v87, v174
	v_add_f32_e32 v92, v88, v174
	v_add_f32_e32 v93, v89, v174
	s_waitcnt lgkmcnt(2)
	v_mfma_f32_16x16x32_bf16 v[2:5], v[148:151], v[180:183], v[212:215]
	v_mfma_f32_16x16x32_bf16 v[2:5], v[152:155], v[184:187], v[2:5]
	ds_read_b128 v[148:151], v164 offset:4608
	ds_read_b128 v[152:155], v164 offset:4672
	v_add_f32_e32 v86, v90, v174
	v_add_f32_e32 v87, v91, v174
	v_add_f32_e32 v88, v92, v174
	v_add_f32_e32 v89, v93, v174
	s_waitcnt lgkmcnt(2)
	v_mfma_f32_16x16x32_bf16 v[6:9], v[156:159], v[180:183], v[90:93]
	v_mfma_f32_16x16x32_bf16 v[6:9], v[160:163], v[184:187], v[6:9]
	ds_read_b128 v[156:159], v164 offset:6912
	ds_read_b128 v[160:163], v164 offset:6976
	v_add_f32_e32 v90, v86, v174
	v_add_f32_e32 v91, v87, v174
	v_add_f32_e32 v92, v88, v174
	v_add_f32_e32 v93, v89, v174
	s_waitcnt lgkmcnt(2)
	v_mfma_f32_16x16x32_bf16 v[10:13], v[148:151], v[180:183], v[86:89]
	v_mfma_f32_16x16x32_bf16 v[10:13], v[152:155], v[184:187], v[10:13]
	ds_read_b128 v[148:151], v164 offset:9216
	ds_read_b128 v[152:155], v164 offset:9280
	v_add_f32_e32 v86, v90, v174
	v_add_f32_e32 v87, v91, v174
	v_add_f32_e32 v88, v92, v174
	v_add_f32_e32 v89, v93, v174
	s_waitcnt lgkmcnt(2)
	v_mfma_f32_16x16x32_bf16 v[14:17], v[156:159], v[180:183], v[90:93]
	v_mfma_f32_16x16x32_bf16 v[14:17], v[160:163], v[184:187], v[14:17]
	ds_read_b128 v[156:159], v164 offset:11520
	ds_read_b128 v[160:163], v164 offset:11584
	v_add_f32_e32 v90, v86, v174
	v_add_f32_e32 v91, v87, v174
	v_add_f32_e32 v92, v88, v174
	v_add_f32_e32 v93, v89, v174
	s_waitcnt lgkmcnt(2)
	v_mfma_f32_16x16x32_bf16 v[18:21], v[148:151], v[180:183], v[86:89]
	v_mfma_f32_16x16x32_bf16 v[18:21], v[152:155], v[184:187], v[18:21]
	ds_read_b128 v[148:151], v164 offset:13824
	ds_read_b128 v[152:155], v164 offset:13888
	v_add_f32_e32 v86, v90, v174
	v_add_f32_e32 v87, v91, v174
	v_add_f32_e32 v88, v92, v174
	v_add_f32_e32 v89, v93, v174
	s_waitcnt lgkmcnt(2)
	v_mfma_f32_16x16x32_bf16 v[22:25], v[156:159], v[180:183], v[90:93]
	v_mfma_f32_16x16x32_bf16 v[22:25], v[160:163], v[184:187], v[22:25]
	ds_read_b128 v[156:159], v164 offset:16128
	ds_read_b128 v[160:163], v164 offset:16192
	v_add_f32_e32 v90, v86, v174
	v_add_f32_e32 v91, v87, v174
	v_add_f32_e32 v92, v88, v174
	v_add_f32_e32 v93, v89, v174
	s_waitcnt lgkmcnt(2)
; __device__ __forceinline__ f32x4 mfma16(bf16x8 a, bf16x8 b, f32x4 c) { return __builtin_amdgcn_mfma_f32_16x16x32_bf16(a, b, c, 0, 0, 0); }
; __device__ void att_phase(int wv, const Params& p, unsigned char* lds) {
;     ...
;             for (int cb = 0; cb < 24; ++cb) { f32x4 a = {0, 0, 0, 0};
; #pragma unroll
;                 for (int kk = 0; kk < 2; ++kk) { const bf16x8 kf = *(const bf16x8*)(KL + (16 * cb + lr) * KP + 32 * kk + 8 * lq); a = mfma16(kf, qf[kk], a); }
;                 sc[cb] = a; }
;             float mx = sink;
; #pragma unroll
;             for (int cb = 0; cb < 24; ++cb) { const int kb = B - 1 + (cb >> 3); const bool bval = (kb >= sb && kb < se);
; #pragma unroll
;                 for (int j = 0; j < 4; ++j) { const int krel = 16 * cb + 4 * lq + j - 128;
;                     int dist = qrow - krel; dist = dist < 0 ? -dist : dist;
;                     const float v = (bval && dist <= 128) ? sc[cb][j] * 0.125f - slope * (float)dist : -1e30f;
;                     sc[cb][j] = v; mx = fmaxf(mx, v); } }
;             mx = fmaxf(mx, __shfl_xor(mx, 16)); mx = fmaxf(mx, __shfl_xor(mx, 32));
	v_mfma_f32_16x16x32_bf16 v[26:29], v[148:151], v[180:183], v[86:89]
	v_mfma_f32_16x16x32_bf16 v[26:29], v[152:155], v[184:187], v[26:29]
	ds_read_b128 v[148:151], v164 offset:18432
	ds_read_b128 v[152:155], v164 offset:18496
	s_waitcnt lgkmcnt(2)
	v_mfma_f32_16x16x32_bf16 v[30:33], v[156:159], v[180:183], v[90:93]
	v_mfma_f32_16x16x32_bf16 v[30:33], v[160:163], v[184:187], v[30:33]
	ds_read_b128 v[156:159], v164 offset:20736
	ds_read_b128 v[160:163], v164 offset:20800
	v_sub_f32_e64 v86, -v94, v174
	v_sub_f32_e64 v87, -v95, v174
	v_sub_f32_e64 v88, -v96, v174
	v_sub_f32_e64 v89, -v97, v174
	s_waitcnt lgkmcnt(2)
	v_mfma_f32_16x16x32_bf16 v[34:37], v[148:151], v[180:183], v[98:101]
	v_mfma_f32_16x16x32_bf16 v[34:37], v[152:155], v[184:187], v[34:37]
	ds_read_b128 v[148:151], v164 offset:23040
	ds_read_b128 v[152:155], v164 offset:23104
	v_sub_f32_e32 v90, v86, v174
	v_sub_f32_e32 v91, v87, v174
	v_sub_f32_e32 v92, v88, v174
	v_sub_f32_e32 v93, v89, v174
	s_waitcnt lgkmcnt(2)
	v_mfma_f32_16x16x32_bf16 v[38:41], v[156:159], v[180:183], v[86:89]
	v_mfma_f32_16x16x32_bf16 v[38:41], v[160:163], v[184:187], v[38:41]
	ds_read_b128 v[156:159], v164 offset:25344
	ds_read_b128 v[160:163], v164 offset:25408
	v_sub_f32_e32 v86, v90, v174
	v_sub_f32_e32 v87, v91, v174
	v_sub_f32_e32 v88, v92, v174
	v_sub_f32_e32 v89, v93, v174
	s_waitcnt lgkmcnt(2)
	v_mfma_f32_16x16x32_bf16 v[42:45], v[148:151], v[180:183], v[90:93]
	v_mfma_f32_16x16x32_bf16 v[42:45], v[152:155], v[184:187], v[42:45]
	ds_read_b128 v[148:151], v164 offset:27648
	ds_read_b128 v[152:155], v164 offset:27712
	v_sub_f32_e32 v90, v86, v174
	v_sub_f32_e32 v91, v87, v174
	v_sub_f32_e32 v92, v88, v174
	v_sub_f32_e32 v93, v89, v174
	s_waitcnt lgkmcnt(2)
	v_mfma_f32_16x16x32_bf16 v[46:49], v[156:159], v[180:183], v[86:89]
	v_mfma_f32_16x16x32_bf16 v[46:49], v[160:163], v[184:187], v[46:49]
	ds_read_b128 v[156:159], v164 offset:29952
	ds_read_b128 v[160:163], v164 offset:30016
	v_sub_f32_e32 v86, v90, v174
	v_sub_f32_e32 v87, v91, v174
	v_sub_f32_e32 v88, v92, v174
	v_sub_f32_e32 v89, v93, v174
	s_waitcnt lgkmcnt(2)
	v_mfma_f32_16x16x32_bf16 v[50:53], v[148:151], v[180:183], v[90:93]
	v_mfma_f32_16x16x32_bf16 v[50:53], v[152:155], v[184:187], v[50:53]
	ds_read_b128 v[148:151], v164 offset:32256
	ds_read_b128 v[152:155], v164 offset:32320
	v_sub_f32_e32 v90, v86, v174
	v_sub_f32_e32 v91, v87, v174
	v_sub_f32_e32 v92, v88, v174
	v_sub_f32_e32 v93, v89, v174
	s_waitcnt lgkmcnt(2)
	v_mfma_f32_16x16x32_bf16 v[54:57], v[156:159], v[180:183], v[86:89]
	v_mfma_f32_16x16x32_bf16 v[54:57], v[160:163], v[184:187], v[54:57]
	ds_read_b128 v[156:159], v164 offset:34560
	ds_read_b128 v[160:163], v164 offset:34624
	v_sub_f32_e32 v86, v90, v174
	v_sub_f32_e32 v87, v91, v174
	v_sub_f32_e32 v88, v92, v174
	v_sub_f32_e32 v89, v93, v174
	s_waitcnt lgkmcnt(2)
	v_mfma_f32_16x16x32_bf16 v[58:61], v[148:151], v[180:183], v[90:93]
	v_mfma_f32_16x16x32_bf16 v[58:61], v[152:155], v[184:187], v[58:61]
	ds_read_b128 v[148:151], v164 offset:36864
	ds_read_b128 v[152:155], v164 offset:36928
	v_sub_f32_e32 v90, v86, v174
	v_sub_f32_e32 v91, v87, v174
	v_sub_f32_e32 v92, v88, v174
	v_sub_f32_e32 v93, v89, v174
	v_cmp_le_i32_e32 vcc, 0, v108
	s_nop 1
	v_cndmask_b32_e32 v212, v252, v90, vcc
	v_cmp_le_i32_e32 vcc, 0, v110
	s_nop 1
	v_cndmask_b32_e32 v213, v252, v91, vcc
	v_cmp_le_i32_e32 vcc, 0, v111
	s_nop 1
	v_cndmask_b32_e32 v214, v252, v92, vcc
	v_cmp_le_i32_e32 vcc, 0, v177
	s_nop 1
	v_cndmask_b32_e32 v215, v252, v93, vcc
	s_waitcnt lgkmcnt(2)
	v_mfma_f32_16x16x32_bf16 v[62:65], v[156:159], v[180:183], v[86:89]
	v_mfma_f32_16x16x32_bf16 v[62:65], v[160:163], v[184:187], v[62:65]
	s_waitcnt lgkmcnt(0)
	v_mfma_f32_16x16x32_bf16 v[66:69], v[148:151], v[180:183], v[212:215]
	v_mfma_f32_16x16x32_bf16 v[66:69], v[152:155], v[184:187], v[66:69]
	ds_read2_b64 v[216:219], v165 offset0:0 offset1:4
	ds_read2_b64 v[220:223], v166 offset0:0 offset1:4
	ds_read2_b64 v[224:227], v167 offset0:0 offset1:4
	ds_read2_b64 v[228:231], v168 offset0:0 offset1:4
	v_max3_f32 v169, v2, v3, v4
	v_max3_f32 v172, v5, v6, v7
	v_max3_f32 v169, v8, v9, v169
	v_max3_f32 v172, v10, v11, v172
	v_max3_f32 v169, v12, v13, v169
	v_max3_f32 v172, v14, v15, v172
	v_max3_f32 v169, v16, v17, v169
	v_max3_f32 v172, v18, v19, v172
	v_max3_f32 v169, v20, v21, v169
	v_max3_f32 v172, v22, v23, v172
	v_max3_f32 v169, v24, v25, v169
	v_max3_f32 v172, v26, v27, v172
	v_max3_f32 v169, v28, v29, v169
	v_max3_f32 v172, v30, v31, v172
	v_max3_f32 v169, v32, v33, v169
	v_max3_f32 v172, v34, v35, v172
	v_max3_f32 v169, v36, v37, v169
	v_max3_f32 v172, v38, v39, v172
	v_max3_f32 v169, v40, v41, v169
	v_max3_f32 v172, v42, v43, v172
	v_max3_f32 v169, v44, v45, v169
	v_max3_f32 v172, v46, v47, v172
	v_max3_f32 v169, v48, v49, v169
	v_max3_f32 v172, v50, v51, v172
	v_max3_f32 v169, v52, v53, v169
	v_max3_f32 v172, v54, v55, v172
	v_max3_f32 v169, v56, v57, v169
	v_max3_f32 v172, v58, v59, v172
	v_max3_f32 v169, v60, v61, v169
	v_max3_f32 v172, v62, v63, v172
	v_max3_f32 v169, v64, v65, v169
	v_max3_f32 v172, v66, v67, v172
	v_max3_f32 v169, v68, v69, v169
	v_max_f32_e32 v169, v169, v172
	v_mul_f32_e32 v169, 0x3e000000, v169
	v_max_f32_e32 v169, v169, v146
	ds_bpermute_b32 v172, v1, v169
	s_waitcnt lgkmcnt(0)
	v_max_f32_e32 v169, v169, v172
	ds_bpermute_b32 v172, v114, v169
	s_waitcnt lgkmcnt(0)
; __device__ void att_phase(int wv, const Params& p, unsigned char* lds) {
;     ...
;             float sum = 0.f;
; #pragma unroll
;             for (int cb = 0; cb < 24; ++cb)
; #pragma unroll
;                 for (int j = 0; j < 4; ++j) { const float e = __expf(sc[cb][j] - mx); sc[cb][j] = e; sum += e; }
	v_max_f32_e32 v169, v169, v172
	v_mul_f32_e32 v175, 0xbfb8aa3b, v169
	v_mov_b32_e32 v170, 0
	v_mov_b32_e32 v171, 0
	v_fma_f32 v2, v2, s46, v175
	v_fma_f32 v3, v3, s46, v175
	v_fma_f32 v4, v4, s46, v175
	v_fma_f32 v5, v5, s46, v175
	v_exp_f32_e32 v2, v2
	v_exp_f32_e32 v3, v3
	v_exp_f32_e32 v4, v4
	v_exp_f32_e32 v5, v5
	v_fma_f32 v6, v6, s46, v175
	v_fma_f32 v7, v7, s46, v175
	v_fma_f32 v8, v8, s46, v175
	v_fma_f32 v9, v9, s46, v175
	v_exp_f32_e32 v6, v6
	v_exp_f32_e32 v7, v7
	v_exp_f32_e32 v8, v8
	v_exp_f32_e32 v9, v9
	v_add_f32_e32 v171, v171, v2
	v_add_f32_e32 v170, v170, v3
	v_add_f32_e32 v171, v171, v4
	v_add_f32_e32 v170, v170, v5
	v_fma_f32 v10, v10, s46, v175
	v_fma_f32 v11, v11, s46, v175
	v_fma_f32 v12, v12, s46, v175
	v_fma_f32 v13, v13, s46, v175
	v_exp_f32_e32 v10, v10
	v_exp_f32_e32 v11, v11
	v_exp_f32_e32 v12, v12
	v_exp_f32_e32 v13, v13
	v_add_f32_e32 v171, v171, v6
	v_add_f32_e32 v170, v170, v7
	v_add_f32_e32 v171, v171, v8
	v_add_f32_e32 v170, v170, v9
	v_fma_f32 v14, v14, s46, v175
	v_fma_f32 v15, v15, s46, v175
	v_fma_f32 v16, v16, s46, v175
	v_fma_f32 v17, v17, s46, v175
	v_exp_f32_e32 v14, v14
	v_exp_f32_e32 v15, v15
	v_exp_f32_e32 v16, v16
	v_exp_f32_e32 v17, v17
	v_add_f32_e32 v171, v171, v10
	v_add_f32_e32 v170, v170, v11
	v_add_f32_e32 v171, v171, v12
	v_add_f32_e32 v170, v170, v13
	v_fma_f32 v18, v18, s46, v175
	v_fma_f32 v19, v19, s46, v175
	v_fma_f32 v20, v20, s46, v175
	v_fma_f32 v21, v21, s46, v175
	v_exp_f32_e32 v18, v18
	v_exp_f32_e32 v19, v19
	v_exp_f32_e32 v20, v20
	v_exp_f32_e32 v21, v21
	v_add_f32_e32 v171, v171, v14
	v_add_f32_e32 v170, v170, v15
	v_add_f32_e32 v171, v171, v16
	v_add_f32_e32 v170, v170, v17
	v_fma_f32 v22, v22, s46, v175
	v_fma_f32 v23, v23, s46, v175
	v_fma_f32 v24, v24, s46, v175
	v_fma_f32 v25, v25, s46, v175
	v_exp_f32_e32 v22, v22
	v_exp_f32_e32 v23, v23
	v_exp_f32_e32 v24, v24
	v_exp_f32_e32 v25, v25
	v_add_f32_e32 v171, v171, v18
	v_add_f32_e32 v170, v170, v19
	v_add_f32_e32 v171, v171, v20
	v_add_f32_e32 v170, v170, v21
	v_fma_f32 v26, v26, s46, v175
	v_fma_f32 v27, v27, s46, v175
	v_fma_f32 v28, v28, s46, v175
	v_fma_f32 v29, v29, s46, v175
	v_exp_f32_e32 v26, v26
	v_exp_f32_e32 v27, v27
	v_exp_f32_e32 v28, v28
	v_exp_f32_e32 v29, v29
	v_add_f32_e32 v171, v171, v22
	v_add_f32_e32 v170, v170, v23
	v_add_f32_e32 v171, v171, v24
	v_add_f32_e32 v170, v170, v25
	v_fma_f32 v30, v30, s46, v175
	v_fma_f32 v31, v31, s46, v175
	v_fma_f32 v32, v32, s46, v175
	v_fma_f32 v33, v33, s46, v175
	v_exp_f32_e32 v30, v30
	v_exp_f32_e32 v31, v31
	v_exp_f32_e32 v32, v32
	v_exp_f32_e32 v33, v33
	v_add_f32_e32 v171, v171, v26
	v_add_f32_e32 v170, v170, v27
	v_add_f32_e32 v171, v171, v28
	v_add_f32_e32 v170, v170, v29
	v_fma_f32 v34, v34, s46, v175
	v_fma_f32 v35, v35, s46, v175
	v_fma_f32 v36, v36, s46, v175
	v_fma_f32 v37, v37, s46, v175
	v_exp_f32_e32 v34, v34
	v_exp_f32_e32 v35, v35
	v_exp_f32_e32 v36, v36
	v_exp_f32_e32 v37, v37
	v_add_f32_e32 v171, v171, v30
	v_add_f32_e32 v170, v170, v31
	v_add_f32_e32 v171, v171, v32
	v_add_f32_e32 v170, v170, v33
	v_fma_f32 v38, v38, s46, v175
	v_fma_f32 v39, v39, s46, v175
	v_fma_f32 v40, v40, s46, v175
	v_fma_f32 v41, v41, s46, v175
	v_exp_f32_e32 v38, v38
	v_exp_f32_e32 v39, v39
	v_exp_f32_e32 v40, v40
	v_exp_f32_e32 v41, v41
	v_add_f32_e32 v171, v171, v34
	v_add_f32_e32 v170, v170, v35
	v_add_f32_e32 v171, v171, v36
	v_add_f32_e32 v170, v170, v37
	v_fma_f32 v42, v42, s46, v175
	v_fma_f32 v43, v43, s46, v175
	v_fma_f32 v44, v44, s46, v175
	v_fma_f32 v45, v45, s46, v175
	v_exp_f32_e32 v42, v42
	v_exp_f32_e32 v43, v43
	v_exp_f32_e32 v44, v44
	v_exp_f32_e32 v45, v45
	v_add_f32_e32 v171, v171, v38
	v_add_f32_e32 v170, v170, v39
	v_add_f32_e32 v171, v171, v40
	v_add_f32_e32 v170, v170, v41
	v_fma_f32 v46, v46, s46, v175
	v_fma_f32 v47, v47, s46, v175
	v_fma_f32 v48, v48, s46, v175
	v_fma_f32 v49, v49, s46, v175
	v_exp_f32_e32 v46, v46
	v_exp_f32_e32 v47, v47
	v_exp_f32_e32 v48, v48
	v_exp_f32_e32 v49, v49
	v_add_f32_e32 v171, v171, v42
	v_add_f32_e32 v170, v170, v43
	v_add_f32_e32 v171, v171, v44
	v_add_f32_e32 v170, v170, v45
	v_fma_f32 v50, v50, s46, v175
	v_fma_f32 v51, v51, s46, v175
	v_fma_f32 v52, v52, s46, v175
	v_fma_f32 v53, v53, s46, v175
	v_exp_f32_e32 v50, v50
	v_exp_f32_e32 v51, v51
	v_exp_f32_e32 v52, v52
	v_exp_f32_e32 v53, v53
	v_add_f32_e32 v171, v171, v46
	v_add_f32_e32 v170, v170, v47
	v_add_f32_e32 v171, v171, v48
	v_add_f32_e32 v170, v170, v49
	v_fma_f32 v54, v54, s46, v175
	v_fma_f32 v55, v55, s46, v175
	v_fma_f32 v56, v56, s46, v175
	v_fma_f32 v57, v57, s46, v175
	v_exp_f32_e32 v54, v54
	v_exp_f32_e32 v55, v55
	v_exp_f32_e32 v56, v56
	v_exp_f32_e32 v57, v57
	v_add_f32_e32 v171, v171, v50
	v_add_f32_e32 v170, v170, v51
	v_add_f32_e32 v171, v171, v52
	v_add_f32_e32 v170, v170, v53
	v_fma_f32 v58, v58, s46, v175
	v_fma_f32 v59, v59, s46, v175
	v_fma_f32 v60, v60, s46, v175
	v_fma_f32 v61, v61, s46, v175
	v_exp_f32_e32 v58, v58
	v_exp_f32_e32 v59, v59
	v_exp_f32_e32 v60, v60
	v_exp_f32_e32 v61, v61
	v_add_f32_e32 v171, v171, v54
	v_add_f32_e32 v170, v170, v55
	v_add_f32_e32 v171, v171, v56
	v_add_f32_e32 v170, v170, v57
	v_fma_f32 v62, v62, s46, v175
	v_fma_f32 v63, v63, s46, v175
	v_fma_f32 v64, v64, s46, v175
	v_fma_f32 v65, v65, s46, v175
	v_exp_f32_e32 v62, v62
	v_exp_f32_e32 v63, v63
	v_exp_f32_e32 v64, v64
	v_exp_f32_e32 v65, v65
	v_add_f32_e32 v171, v171, v58
	v_add_f32_e32 v170, v170, v59
	v_add_f32_e32 v171, v171, v60
	v_add_f32_e32 v170, v170, v61
	v_fma_f32 v66, v66, s46, v175
	v_fma_f32 v67, v67, s46, v175
	v_fma_f32 v68, v68, s46, v175
	v_fma_f32 v69, v69, s46, v175
	v_exp_f32_e32 v66, v66
	v_exp_f32_e32 v67, v67
; __device__ __forceinline__ unsigned cvt_pk_bf16_asm(float lo, float hi) { unsigned r; asm volatile("v_cvt_pk_bf16_f32 %0, %1, %2" : "=v"(r) : "v"(lo), "v"(hi)); return r; }
; __device__ __forceinline__ f32x4 mfma16(bf16x8 a, bf16x8 b, f32x4 c) { return __builtin_amdgcn_mfma_f32_16x16x32_bf16(a, b, c, 0, 0, 0); }
; __device__ void att_phase(int wv, const Params& p, unsigned char* lds) {
;     ...
;             for (int cb = 0; cb < 24; ++cb)
; #pragma unroll
;                 for (int j = 0; j < 4; ++j) { const float e = __expf(sc[cb][j] - mx); sc[cb][j] = e; sum += e; }
;             sum += __shfl_xor(sum, 16); sum += __shfl_xor(sum, 32);
;             sum += __expf(sink - mx);
;             const float inv = 1.0f / sum;
;             f32x4 oa[4];
; #pragma unroll
;             for (int db = 0; db < 4; ++db) oa[db] = (f32x4){0, 0, 0, 0};
; #pragma unroll
;             for (int ks = 0; ks < 12; ++ks) {
;                 union { bf16x8 v; unsigned u[4]; } pf;
;                 pf.u[0] = cvt_pk_bf16_asm(sc[2 * ks][0], sc[2 * ks][1]); pf.u[1] = cvt_pk_bf16_asm(sc[2 * ks][2], sc[2 * ks][3]);
;                 pf.u[2] = cvt_pk_bf16_asm(sc[2 * ks + 1][0], sc[2 * ks + 1][1]); pf.u[3] = cvt_pk_bf16_asm(sc[2 * ks + 1][2], sc[2 * ks + 1][3]);
; #pragma unroll
;                 for (int db = 0; db < 4; ++db) {
;                     union { bf16x8 v; u32x2 h2[2]; } vf;
;                     const bf16_t* vp = VTL + (16 * db + lr) * VP + 32 * ks + 4 * lq;
;                     vf.h2[0] = *(const u32x2*)vp; vf.h2[1] = *(const u32x2*)(vp + 16);
;                     oa[db] = mfma16(vf.v, pf.v, oa[db]); } }
	v_exp_f32_e32 v68, v68
	v_exp_f32_e32 v69, v69
	v_add_f32_e32 v171, v171, v62
	v_add_f32_e32 v170, v170, v63
	v_add_f32_e32 v171, v171, v64
	v_add_f32_e32 v170, v170, v65
	v_add_f32_e32 v171, v171, v66
	v_add_f32_e32 v170, v170, v67
	v_add_f32_e32 v171, v171, v68
	v_add_f32_e32 v170, v170, v69
	v_add_f32_e32 v170, v170, v171
	v_cvt_pk_bf16_f32 v2, v2, v3
	v_cvt_pk_bf16_f32 v3, v4, v5
	v_cvt_pk_bf16_f32 v4, v6, v7
	v_cvt_pk_bf16_f32 v5, v8, v9
	v_cvt_pk_bf16_f32 v10, v10, v11
	v_cvt_pk_bf16_f32 v11, v12, v13
	v_cvt_pk_bf16_f32 v12, v14, v15
	v_cvt_pk_bf16_f32 v13, v16, v17
	v_cvt_pk_bf16_f32 v18, v18, v19
	v_cvt_pk_bf16_f32 v19, v20, v21
	v_cvt_pk_bf16_f32 v20, v22, v23
	v_cvt_pk_bf16_f32 v21, v24, v25
	v_cvt_pk_bf16_f32 v26, v26, v27
	v_cvt_pk_bf16_f32 v27, v28, v29
	v_cvt_pk_bf16_f32 v28, v30, v31
	v_cvt_pk_bf16_f32 v29, v32, v33
	v_cvt_pk_bf16_f32 v34, v34, v35
	v_cvt_pk_bf16_f32 v35, v36, v37
	v_cvt_pk_bf16_f32 v36, v38, v39
	v_cvt_pk_bf16_f32 v37, v40, v41
	v_cvt_pk_bf16_f32 v42, v42, v43
	v_cvt_pk_bf16_f32 v43, v44, v45
	v_cvt_pk_bf16_f32 v44, v46, v47
	v_cvt_pk_bf16_f32 v45, v48, v49
	v_cvt_pk_bf16_f32 v50, v50, v51
	v_cvt_pk_bf16_f32 v51, v52, v53
	v_cvt_pk_bf16_f32 v52, v54, v55
	v_cvt_pk_bf16_f32 v53, v56, v57
	v_cvt_pk_bf16_f32 v58, v58, v59
	v_cvt_pk_bf16_f32 v59, v60, v61
	v_cvt_pk_bf16_f32 v60, v62, v63
	v_cvt_pk_bf16_f32 v61, v64, v65
	v_cvt_pk_bf16_f32 v66, v66, v67
	v_cvt_pk_bf16_f32 v67, v68, v69
	v_mov_b32_e32 v68, 0
	v_mov_b32_e32 v69, 0
	ds_bpermute_b32 v172, v1, v170
	v_sub_f32_e32 v173, v146, v169
	v_mul_f32_e32 v173, 0x3fb8aa3b, v173
	v_exp_f32_e32 v173, v173
	s_waitcnt lgkmcnt(0)
	v_add_f32_e32 v170, v170, v172
	ds_bpermute_b32 v172, v114, v170
	ds_read2_b64 v[232:235], v165 offset0:8 offset1:12
	ds_read2_b64 v[236:239], v166 offset0:8 offset1:12
	ds_read2_b64 v[240:243], v167 offset0:8 offset1:12
	ds_read2_b64 v[244:247], v168 offset0:8 offset1:12
	s_waitcnt lgkmcnt(4)
	v_mfma_f32_16x16x32_bf16 v[70:73], v[216:219], v[2:5], 0
	v_mfma_f32_16x16x32_bf16 v[74:77], v[220:223], v[2:5], 0
	v_mfma_f32_16x16x32_bf16 v[78:81], v[224:227], v[2:5], 0
	v_mfma_f32_16x16x32_bf16 v[82:85], v[228:231], v[2:5], 0
	v_add_f32_e32 v170, v170, v172
	v_add_f32_e32 v170, v170, v173
	v_rcp_f32_e32 v147, v170
	s_nop 0
	v_fma_f32 v179, -v170, v147, 1.0
	v_fmac_f32_e32 v147, v179, v147
	ds_read2_b64 v[216:219], v165 offset0:16 offset1:20
	ds_read2_b64 v[220:223], v166 offset0:16 offset1:20
	ds_read2_b64 v[224:227], v167 offset0:16 offset1:20
	ds_read2_b64 v[228:231], v168 offset0:16 offset1:20
	s_waitcnt lgkmcnt(4)
	v_mfma_f32_16x16x32_bf16 v[70:73], v[232:235], v[10:13], v[70:73]
	v_mfma_f32_16x16x32_bf16 v[74:77], v[236:239], v[10:13], v[74:77]
	v_mfma_f32_16x16x32_bf16 v[78:81], v[240:243], v[10:13], v[78:81]
	v_mfma_f32_16x16x32_bf16 v[82:85], v[244:247], v[10:13], v[82:85]
	ds_read2_b64 v[232:235], v165 offset0:24 offset1:28
	ds_read2_b64 v[236:239], v166 offset0:24 offset1:28
	ds_read2_b64 v[240:243], v167 offset0:24 offset1:28
	ds_read2_b64 v[244:247], v168 offset0:24 offset1:28
	s_waitcnt lgkmcnt(4)
	v_mfma_f32_16x16x32_bf16 v[70:73], v[216:219], v[18:21], v[70:73]
	v_mfma_f32_16x16x32_bf16 v[74:77], v[220:223], v[18:21], v[74:77]
	v_mfma_f32_16x16x32_bf16 v[78:81], v[224:227], v[18:21], v[78:81]
	v_mfma_f32_16x16x32_bf16 v[82:85], v[228:231], v[18:21], v[82:85]
	ds_read2_b64 v[216:219], v165 offset0:32 offset1:36
	ds_read2_b64 v[220:223], v166 offset0:32 offset1:36
	ds_read2_b64 v[224:227], v167 offset0:32 offset1:36
	ds_read2_b64 v[228:231], v168 offset0:32 offset1:36
	s_waitcnt lgkmcnt(4)
	v_mfma_f32_16x16x32_bf16 v[70:73], v[232:235], v[26:29], v[70:73]
	v_mfma_f32_16x16x32_bf16 v[74:77], v[236:239], v[26:29], v[74:77]
	v_mfma_f32_16x16x32_bf16 v[78:81], v[240:243], v[26:29], v[78:81]
	v_mfma_f32_16x16x32_bf16 v[82:85], v[244:247], v[26:29], v[82:85]
	ds_read2_b64 v[232:235], v165 offset0:40 offset1:44
	ds_read2_b64 v[236:239], v166 offset0:40 offset1:44
	ds_read2_b64 v[240:243], v167 offset0:40 offset1:44
	ds_read2_b64 v[244:247], v168 offset0:40 offset1:44
	s_waitcnt lgkmcnt(4)
	v_mfma_f32_16x16x32_bf16 v[70:73], v[216:219], v[34:37], v[70:73]
	v_mfma_f32_16x16x32_bf16 v[74:77], v[220:223], v[34:37], v[74:77]
	v_mfma_f32_16x16x32_bf16 v[78:81], v[224:227], v[34:37], v[78:81]
	v_mfma_f32_16x16x32_bf16 v[82:85], v[228:231], v[34:37], v[82:85]
	ds_read2_b64 v[216:219], v165 offset0:48 offset1:52
	ds_read2_b64 v[220:223], v166 offset0:48 offset1:52
	ds_read2_b64 v[224:227], v167 offset0:48 offset1:52
	ds_read2_b64 v[228:231], v168 offset0:48 offset1:52
	s_waitcnt lgkmcnt(4)
	v_mfma_f32_16x16x32_bf16 v[70:73], v[232:235], v[42:45], v[70:73]
	v_mfma_f32_16x16x32_bf16 v[74:77], v[236:239], v[42:45], v[74:77]
	v_mfma_f32_16x16x32_bf16 v[78:81], v[240:243], v[42:45], v[78:81]
	v_mfma_f32_16x16x32_bf16 v[82:85], v[244:247], v[42:45], v[82:85]
	ds_read2_b64 v[232:235], v165 offset0:56 offset1:60
	ds_read2_b64 v[236:239], v166 offset0:56 offset1:60
	ds_read2_b64 v[240:243], v167 offset0:56 offset1:60
	ds_read2_b64 v[244:247], v168 offset0:56 offset1:60
	s_waitcnt lgkmcnt(4)
	v_mfma_f32_16x16x32_bf16 v[70:73], v[216:219], v[50:53], v[70:73]
	v_mfma_f32_16x16x32_bf16 v[74:77], v[220:223], v[50:53], v[74:77]
	v_mfma_f32_16x16x32_bf16 v[78:81], v[224:227], v[50:53], v[78:81]
	v_mfma_f32_16x16x32_bf16 v[82:85], v[228:231], v[50:53], v[82:85]
	ds_read2_b64 v[216:219], v165 offset0:64 offset1:64
	ds_read2_b64 v[220:223], v166 offset0:64 offset1:64
	ds_read2_b64 v[224:227], v167 offset0:64 offset1:64
	ds_read2_b64 v[228:231], v168 offset0:64 offset1:64
	s_waitcnt lgkmcnt(4)
; __device__ void att_phase(int wv, const Params& p, unsigned char* lds) {
;     ...
;         for (int rb = 0; rb < 4; ++rb) {
;             const int qrow = 64 * (w & 1) + 16 * rb + lr;
;             const size_t tokq = (size_t)B * 128 + qrow;
;             bf16x8 qf[2];
; #pragma unroll
;             for (int kk = 0; kk < 2; ++kk) qf[kk] = *(const bf16x8*)(qkv + tokq * 1536 + 64 * h + 32 * kk + 8 * lq);
;             f32x4 sc[24];
; #pragma unroll
;             for (int cb = 0; cb < 24; ++cb) { f32x4 a = {0, 0, 0, 0};
; #pragma unroll
;                 for (int kk = 0; kk < 2; ++kk) { const bf16x8 kf = *(const bf16x8*)(KL + (16 * cb + lr) * KP + 32 * kk + 8 * lq); a = mfma16(kf, qf[kk], a); }
;                 sc[cb] = a; }
;             float mx = sink;
; #pragma unroll
;             for (int cb = 0; cb < 24; ++cb) { const int kb = B - 1 + (cb >> 3); const bool bval = (kb >= sb && kb < se);
; #pragma unroll
;                 for (int j = 0; j < 4; ++j) { const int krel = 16 * cb + 4 * lq + j - 128;
;                     int dist = qrow - krel; dist = dist < 0 ? -dist : dist;
;                     const float v = (bval && dist <= 128) ? sc[cb][j] * 0.125f - slope * (float)dist : -1e30f;
;                     sc[cb][j] = v; mx = fmaxf(mx, v); } }
;     ...
;             for (int ks = 0; ks < 12; ++ks) {
;                 union { bf16x8 v; unsigned u[4]; } pf;
;                 pf.u[0] = cvt_pk_bf16_asm(sc[2 * ks][0], sc[2 * ks][1]); pf.u[1] = cvt_pk_bf16_asm(sc[2 * ks][2], sc[2 * ks][3]);
;                 pf.u[2] = cvt_pk_bf16_asm(sc[2 * ks + 1][0], sc[2 * ks + 1][1]); pf.u[3] = cvt_pk_bf16_asm(sc[2 * ks + 1][2], sc[2 * ks + 1][3]);
; #pragma unroll
;                 for (int db = 0; db < 4; ++db) {
;                     union { bf16x8 v; u32x2 h2[2]; } vf;
;                     const bf16_t* vp = VTL + (16 * db + lr) * VP + 32 * ks + 4 * lq;
;                     vf.h2[0] = *(const u32x2*)vp; vf.h2[1] = *(const u32x2*)(vp + 16);
;                     oa[db] = mfma16(vf.v, pf.v, oa[db]); } }
; #pragma unroll
;             for (int db = 0; db < 4; ++db) { const f32x4 o = oa[db] * inv; u32x2 wv; wv.x = cvt_pk_bf16_asm(o[0], o[1]); wv.y = cvt_pk_bf16_asm(o[2], o[3]);
;                 *(u32x2*)(qkv + tokq * 1536 + 64 * h + 16 * db + 4 * lq) = wv; }
	v_mfma_f32_16x16x32_bf16 v[70:73], v[232:235], v[58:61], v[70:73]
	v_mfma_f32_16x16x32_bf16 v[74:77], v[236:239], v[58:61], v[74:77]
	v_mfma_f32_16x16x32_bf16 v[78:81], v[240:243], v[58:61], v[78:81]
	v_mfma_f32_16x16x32_bf16 v[82:85], v[244:247], v[58:61], v[82:85]
	s_waitcnt lgkmcnt(0)
	v_mfma_f32_16x16x32_bf16 v[70:73], v[216:219], v[66:69], v[70:73]
	v_mfma_f32_16x16x32_bf16 v[74:77], v[220:223], v[66:69], v[74:77]
	v_mfma_f32_16x16x32_bf16 v[78:81], v[224:227], v[66:69], v[78:81]
	v_mfma_f32_16x16x32_bf16 v[82:85], v[228:231], v[66:69], v[82:85]
	s_nop 7
	s_nop 1
	v_mul_f32_e32 v70, v70, v147
	v_mul_f32_e32 v71, v71, v147
	v_mul_f32_e32 v72, v72, v147
	v_mul_f32_e32 v73, v73, v147
	v_mul_f32_e32 v74, v74, v147
	v_mul_f32_e32 v75, v75, v147
	v_mul_f32_e32 v76, v76, v147
	v_mul_f32_e32 v77, v77, v147
	v_mul_f32_e32 v78, v78, v147
	v_mul_f32_e32 v79, v79, v147
	v_mul_f32_e32 v80, v80, v147
	v_mul_f32_e32 v81, v81, v147
	v_mul_f32_e32 v82, v82, v147
	v_mul_f32_e32 v83, v83, v147
	v_mul_f32_e32 v84, v84, v147
	v_mul_f32_e32 v85, v85, v147
	v_cvt_pk_bf16_f32 v70, v70, v71
	v_cvt_pk_bf16_f32 v71, v72, v73
	v_cvt_pk_bf16_f32 v74, v74, v75
	v_cvt_pk_bf16_f32 v75, v76, v77
	v_cvt_pk_bf16_f32 v78, v78, v79
	v_cvt_pk_bf16_f32 v79, v80, v81
	v_cvt_pk_bf16_f32 v82, v82, v83
	v_cvt_pk_bf16_f32 v83, v84, v85
	global_store_dwordx2 v[248:249], v[70:71], off offset:-64
	global_store_dwordx2 v[248:249], v[74:75], off offset:-32
	global_store_dwordx2 v[248:249], v[78:79], off
	global_store_dwordx2 v[248:249], v[82:83], off offset:32
	v_lshl_add_u64 v[248:249], v[248:249], 0, s[48:49]
	v_sub_f32_e32 v86, v94, v176
	v_sub_f32_e32 v87, v95, v176
	v_sub_f32_e32 v88, v96, v176
	v_sub_f32_e32 v89, v97, v176
	v_cmp_ge_i32_e32 vcc, 0, v108
	s_nop 1
	v_cndmask_b32_e32 v212, v252, v86, vcc
	v_cmp_ge_i32_e32 vcc, 0, v110
	s_nop 1
	v_cndmask_b32_e32 v213, v252, v87, vcc
	v_cmp_ge_i32_e32 vcc, 0, v111
	s_nop 1
	v_cndmask_b32_e32 v214, v252, v88, vcc
	v_cmp_ge_i32_e32 vcc, 0, v177
	s_nop 1
	v_cndmask_b32_e32 v215, v252, v89, vcc
	ds_read_b128 v[148:151], v164 offset:2304
	ds_read_b128 v[152:155], v164 offset:2368
	ds_read_b128 v[156:159], v164 offset:4608
	ds_read_b128 v[160:163], v164 offset:4672
	v_add_f32_e32 v90, v86, v174
	v_add_f32_e32 v91, v87, v174
	v_add_f32_e32 v92, v88, v174
	v_add_f32_e32 v93, v89, v174
	s_waitcnt lgkmcnt(2)
	v_mfma_f32_16x16x32_bf16 v[2:5], v[148:151], v[188:191], v[212:215]
	v_mfma_f32_16x16x32_bf16 v[2:5], v[152:155], v[192:195], v[2:5]
	ds_read_b128 v[148:151], v164 offset:6912
	ds_read_b128 v[152:155], v164 offset:6976
	v_add_f32_e32 v86, v90, v174
	v_add_f32_e32 v87, v91, v174
	v_add_f32_e32 v88, v92, v174
	v_add_f32_e32 v89, v93, v174
	s_waitcnt lgkmcnt(2)
	v_mfma_f32_16x16x32_bf16 v[6:9], v[156:159], v[188:191], v[90:93]
	v_mfma_f32_16x16x32_bf16 v[6:9], v[160:163], v[192:195], v[6:9]
	ds_read_b128 v[156:159], v164 offset:9216
	ds_read_b128 v[160:163], v164 offset:9280
	v_add_f32_e32 v90, v86, v174
	v_add_f32_e32 v91, v87, v174
	v_add_f32_e32 v92, v88, v174
	v_add_f32_e32 v93, v89, v174
	s_waitcnt lgkmcnt(2)
	v_mfma_f32_16x16x32_bf16 v[10:13], v[148:151], v[188:191], v[86:89]
	v_mfma_f32_16x16x32_bf16 v[10:13], v[152:155], v[192:195], v[10:13]
	ds_read_b128 v[148:151], v164 offset:11520
	ds_read_b128 v[152:155], v164 offset:11584
	v_add_f32_e32 v86, v90, v174
	v_add_f32_e32 v87, v91, v174
	v_add_f32_e32 v88, v92, v174
	v_add_f32_e32 v89, v93, v174
	s_waitcnt lgkmcnt(2)
	v_mfma_f32_16x16x32_bf16 v[14:17], v[156:159], v[188:191], v[90:93]
	v_mfma_f32_16x16x32_bf16 v[14:17], v[160:163], v[192:195], v[14:17]
	ds_read_b128 v[156:159], v164 offset:13824
	ds_read_b128 v[160:163], v164 offset:13888
	v_add_f32_e32 v90, v86, v174
	v_add_f32_e32 v91, v87, v174
	v_add_f32_e32 v92, v88, v174
	v_add_f32_e32 v93, v89, v174
	s_waitcnt lgkmcnt(2)
	v_mfma_f32_16x16x32_bf16 v[18:21], v[148:151], v[188:191], v[86:89]
	v_mfma_f32_16x16x32_bf16 v[18:21], v[152:155], v[192:195], v[18:21]
	ds_read_b128 v[148:151], v164 offset:16128
	ds_read_b128 v[152:155], v164 offset:16192
	v_add_f32_e32 v86, v90, v174
	v_add_f32_e32 v87, v91, v174
	v_add_f32_e32 v88, v92, v174
	v_add_f32_e32 v89, v93, v174
	s_waitcnt lgkmcnt(2)
	v_mfma_f32_16x16x32_bf16 v[22:25], v[156:159], v[188:191], v[90:93]
	v_mfma_f32_16x16x32_bf16 v[22:25], v[160:163], v[192:195], v[22:25]
	ds_read_b128 v[156:159], v164 offset:18432
	ds_read_b128 v[160:163], v164 offset:18496
	v_add_f32_e32 v90, v86, v174
	v_add_f32_e32 v91, v87, v174
	v_add_f32_e32 v92, v88, v174
	v_add_f32_e32 v93, v89, v174
	s_waitcnt lgkmcnt(2)
	v_mfma_f32_16x16x32_bf16 v[26:29], v[148:151], v[188:191], v[86:89]
	v_mfma_f32_16x16x32_bf16 v[26:29], v[152:155], v[192:195], v[26:29]
	ds_read_b128 v[148:151], v164 offset:20736
	ds_read_b128 v[152:155], v164 offset:20800
	s_waitcnt lgkmcnt(2)
	v_mfma_f32_16x16x32_bf16 v[30:33], v[156:159], v[188:191], v[90:93]
	v_mfma_f32_16x16x32_bf16 v[30:33], v[160:163], v[192:195], v[30:33]
	ds_read_b128 v[156:159], v164 offset:23040
	ds_read_b128 v[160:163], v164 offset:23104
	v_sub_f32_e64 v86, -v94, v174
	v_sub_f32_e64 v87, -v95, v174
	v_sub_f32_e64 v88, -v96, v174
	v_sub_f32_e64 v89, -v97, v174
	s_waitcnt lgkmcnt(2)
	v_mfma_f32_16x16x32_bf16 v[34:37], v[148:151], v[188:191], v[98:101]
	v_mfma_f32_16x16x32_bf16 v[34:37], v[152:155], v[192:195], v[34:37]
	ds_read_b128 v[148:151], v164 offset:25344
	ds_read_b128 v[152:155], v164 offset:25408
	v_sub_f32_e32 v90, v86, v174
	v_sub_f32_e32 v91, v87, v174
	v_sub_f32_e32 v92, v88, v174
	v_sub_f32_e32 v93, v89, v174
	s_waitcnt lgkmcnt(2)
; __device__ __forceinline__ f32x4 mfma16(bf16x8 a, bf16x8 b, f32x4 c) { return __builtin_amdgcn_mfma_f32_16x16x32_bf16(a, b, c, 0, 0, 0); }
; __device__ void att_phase(int wv, const Params& p, unsigned char* lds) {
;     ...
;             for (int cb = 0; cb < 24; ++cb) { f32x4 a = {0, 0, 0, 0};
; #pragma unroll
;                 for (int kk = 0; kk < 2; ++kk) { const bf16x8 kf = *(const bf16x8*)(KL + (16 * cb + lr) * KP + 32 * kk + 8 * lq); a = mfma16(kf, qf[kk], a); }
;                 sc[cb] = a; }
;             float mx = sink;
; #pragma unroll
;             for (int cb = 0; cb < 24; ++cb) { const int kb = B - 1 + (cb >> 3); const bool bval = (kb >= sb && kb < se);
; #pragma unroll
;                 for (int j = 0; j < 4; ++j) { const int krel = 16 * cb + 4 * lq + j - 128;
;                     int dist = qrow - krel; dist = dist < 0 ? -dist : dist;
;                     const float v = (bval && dist <= 128) ? sc[cb][j] * 0.125f - slope * (float)dist : -1e30f;
;                     sc[cb][j] = v; mx = fmaxf(mx, v); } }
;             mx = fmaxf(mx, __shfl_xor(mx, 16)); mx = fmaxf(mx, __shfl_xor(mx, 32));
	v_mfma_f32_16x16x32_bf16 v[38:41], v[156:159], v[188:191], v[86:89]
	v_mfma_f32_16x16x32_bf16 v[38:41], v[160:163], v[192:195], v[38:41]
	ds_read_b128 v[156:159], v164 offset:27648
	ds_read_b128 v[160:163], v164 offset:27712
	v_sub_f32_e32 v86, v90, v174
	v_sub_f32_e32 v87, v91, v174
	v_sub_f32_e32 v88, v92, v174
	v_sub_f32_e32 v89, v93, v174
	s_waitcnt lgkmcnt(2)
	v_mfma_f32_16x16x32_bf16 v[42:45], v[148:151], v[188:191], v[90:93]
	v_mfma_f32_16x16x32_bf16 v[42:45], v[152:155], v[192:195], v[42:45]
	ds_read_b128 v[148:151], v164 offset:29952
	ds_read_b128 v[152:155], v164 offset:30016
	v_sub_f32_e32 v90, v86, v174
	v_sub_f32_e32 v91, v87, v174
	v_sub_f32_e32 v92, v88, v174
	v_sub_f32_e32 v93, v89, v174
	s_waitcnt lgkmcnt(2)
	v_mfma_f32_16x16x32_bf16 v[46:49], v[156:159], v[188:191], v[86:89]
	v_mfma_f32_16x16x32_bf16 v[46:49], v[160:163], v[192:195], v[46:49]
	ds_read_b128 v[156:159], v164 offset:32256
	ds_read_b128 v[160:163], v164 offset:32320
	v_sub_f32_e32 v86, v90, v174
	v_sub_f32_e32 v87, v91, v174
	v_sub_f32_e32 v88, v92, v174
	v_sub_f32_e32 v89, v93, v174
	s_waitcnt lgkmcnt(2)
	v_mfma_f32_16x16x32_bf16 v[50:53], v[148:151], v[188:191], v[90:93]
	v_mfma_f32_16x16x32_bf16 v[50:53], v[152:155], v[192:195], v[50:53]
	ds_read_b128 v[148:151], v164 offset:34560
	ds_read_b128 v[152:155], v164 offset:34624
	v_sub_f32_e32 v90, v86, v174
	v_sub_f32_e32 v91, v87, v174
	v_sub_f32_e32 v92, v88, v174
	v_sub_f32_e32 v93, v89, v174
	s_waitcnt lgkmcnt(2)
	v_mfma_f32_16x16x32_bf16 v[54:57], v[156:159], v[188:191], v[86:89]
	v_mfma_f32_16x16x32_bf16 v[54:57], v[160:163], v[192:195], v[54:57]
	ds_read_b128 v[156:159], v164 offset:36864
	ds_read_b128 v[160:163], v164 offset:36928
	v_sub_f32_e32 v86, v90, v174
	v_sub_f32_e32 v87, v91, v174
	v_sub_f32_e32 v88, v92, v174
	v_sub_f32_e32 v89, v93, v174
	s_waitcnt lgkmcnt(2)
	v_mfma_f32_16x16x32_bf16 v[58:61], v[148:151], v[188:191], v[90:93]
	v_mfma_f32_16x16x32_bf16 v[58:61], v[152:155], v[192:195], v[58:61]
	ds_read_b128 v[148:151], v164 offset:39168
	ds_read_b128 v[152:155], v164 offset:39232
	v_sub_f32_e32 v90, v86, v174
	v_sub_f32_e32 v91, v87, v174
	v_sub_f32_e32 v92, v88, v174
	v_sub_f32_e32 v93, v89, v174
	v_cmp_le_i32_e32 vcc, 0, v108
	s_nop 1
	v_cndmask_b32_e32 v212, v252, v90, vcc
	v_cmp_le_i32_e32 vcc, 0, v110
	s_nop 1
	v_cndmask_b32_e32 v213, v252, v91, vcc
	v_cmp_le_i32_e32 vcc, 0, v111
	s_nop 1
	v_cndmask_b32_e32 v214, v252, v92, vcc
	v_cmp_le_i32_e32 vcc, 0, v177
	s_nop 1
	v_cndmask_b32_e32 v215, v252, v93, vcc
	s_waitcnt lgkmcnt(2)
	v_mfma_f32_16x16x32_bf16 v[62:65], v[156:159], v[188:191], v[86:89]
	v_mfma_f32_16x16x32_bf16 v[62:65], v[160:163], v[192:195], v[62:65]
	s_waitcnt lgkmcnt(0)
	v_mfma_f32_16x16x32_bf16 v[66:69], v[148:151], v[188:191], v[212:215]
	v_mfma_f32_16x16x32_bf16 v[66:69], v[152:155], v[192:195], v[66:69]
	ds_read2_b64 v[216:219], v165 offset0:4 offset1:8
	ds_read2_b64 v[220:223], v166 offset0:4 offset1:8
	ds_read2_b64 v[224:227], v167 offset0:4 offset1:8
	ds_read2_b64 v[228:231], v168 offset0:4 offset1:8
	v_max3_f32 v169, v2, v3, v4
	v_max3_f32 v172, v5, v6, v7
	v_max3_f32 v169, v8, v9, v169
	v_max3_f32 v172, v10, v11, v172
	v_max3_f32 v169, v12, v13, v169
	v_max3_f32 v172, v14, v15, v172
	v_max3_f32 v169, v16, v17, v169
	v_max3_f32 v172, v18, v19, v172
	v_max3_f32 v169, v20, v21, v169
	v_max3_f32 v172, v22, v23, v172
	v_max3_f32 v169, v24, v25, v169
	v_max3_f32 v172, v26, v27, v172
	v_max3_f32 v169, v28, v29, v169
	v_max3_f32 v172, v30, v31, v172
	v_max3_f32 v169, v32, v33, v169
	v_max3_f32 v172, v34, v35, v172
	v_max3_f32 v169, v36, v37, v169
	v_max3_f32 v172, v38, v39, v172
	v_max3_f32 v169, v40, v41, v169
	v_max3_f32 v172, v42, v43, v172
	v_max3_f32 v169, v44, v45, v169
	v_max3_f32 v172, v46, v47, v172
	v_max3_f32 v169, v48, v49, v169
	v_max3_f32 v172, v50, v51, v172
	v_max3_f32 v169, v52, v53, v169
	v_max3_f32 v172, v54, v55, v172
	v_max3_f32 v169, v56, v57, v169
	v_max3_f32 v172, v58, v59, v172
	v_max3_f32 v169, v60, v61, v169
	v_max3_f32 v172, v62, v63, v172
	v_max3_f32 v169, v64, v65, v169
	v_max3_f32 v172, v66, v67, v172
	v_max3_f32 v169, v68, v69, v169
	v_max_f32_e32 v169, v169, v172
	v_mul_f32_e32 v169, 0x3e000000, v169
	v_max_f32_e32 v169, v169, v146
	ds_bpermute_b32 v172, v1, v169
	s_waitcnt lgkmcnt(0)
	v_max_f32_e32 v169, v169, v172
	ds_bpermute_b32 v172, v114, v169
	s_waitcnt lgkmcnt(0)
; __device__ void att_phase(int wv, const Params& p, unsigned char* lds) {
;     ...
;             float sum = 0.f;
; #pragma unroll
;             for (int cb = 0; cb < 24; ++cb)
; #pragma unroll
;                 for (int j = 0; j < 4; ++j) { const float e = __expf(sc[cb][j] - mx); sc[cb][j] = e; sum += e; }
	v_max_f32_e32 v169, v169, v172
	v_mul_f32_e32 v175, 0xbfb8aa3b, v169
	v_mov_b32_e32 v170, 0
	v_mov_b32_e32 v171, 0
	v_fma_f32 v2, v2, s46, v175
	v_fma_f32 v3, v3, s46, v175
	v_fma_f32 v4, v4, s46, v175
	v_fma_f32 v5, v5, s46, v175
	v_exp_f32_e32 v2, v2
	v_exp_f32_e32 v3, v3
	v_exp_f32_e32 v4, v4
	v_exp_f32_e32 v5, v5
	v_fma_f32 v6, v6, s46, v175
	v_fma_f32 v7, v7, s46, v175
	v_fma_f32 v8, v8, s46, v175
	v_fma_f32 v9, v9, s46, v175
	v_exp_f32_e32 v6, v6
	v_exp_f32_e32 v7, v7
	v_exp_f32_e32 v8, v8
	v_exp_f32_e32 v9, v9
	v_add_f32_e32 v171, v171, v2
	v_add_f32_e32 v170, v170, v3
	v_add_f32_e32 v171, v171, v4
	v_add_f32_e32 v170, v170, v5
	v_fma_f32 v10, v10, s46, v175
	v_fma_f32 v11, v11, s46, v175
	v_fma_f32 v12, v12, s46, v175
	v_fma_f32 v13, v13, s46, v175
	v_exp_f32_e32 v10, v10
	v_exp_f32_e32 v11, v11
	v_exp_f32_e32 v12, v12
	v_exp_f32_e32 v13, v13
	v_add_f32_e32 v171, v171, v6
	v_add_f32_e32 v170, v170, v7
	v_add_f32_e32 v171, v171, v8
	v_add_f32_e32 v170, v170, v9
	v_fma_f32 v14, v14, s46, v175
	v_fma_f32 v15, v15, s46, v175
	v_fma_f32 v16, v16, s46, v175
	v_fma_f32 v17, v17, s46, v175
	v_exp_f32_e32 v14, v14
	v_exp_f32_e32 v15, v15
	v_exp_f32_e32 v16, v16
	v_exp_f32_e32 v17, v17
	v_add_f32_e32 v171, v171, v10
	v_add_f32_e32 v170, v170, v11
	v_add_f32_e32 v171, v171, v12
	v_add_f32_e32 v170, v170, v13
	v_fma_f32 v18, v18, s46, v175
	v_fma_f32 v19, v19, s46, v175
	v_fma_f32 v20, v20, s46, v175
	v_fma_f32 v21, v21, s46, v175
	v_exp_f32_e32 v18, v18
	v_exp_f32_e32 v19, v19
	v_exp_f32_e32 v20, v20
	v_exp_f32_e32 v21, v21
	v_add_f32_e32 v171, v171, v14
	v_add_f32_e32 v170, v170, v15
	v_add_f32_e32 v171, v171, v16
	v_add_f32_e32 v170, v170, v17
	v_fma_f32 v22, v22, s46, v175
	v_fma_f32 v23, v23, s46, v175
	v_fma_f32 v24, v24, s46, v175
	v_fma_f32 v25, v25, s46, v175
	v_exp_f32_e32 v22, v22
	v_exp_f32_e32 v23, v23
	v_exp_f32_e32 v24, v24
	v_exp_f32_e32 v25, v25
	v_add_f32_e32 v171, v171, v18
	v_add_f32_e32 v170, v170, v19
	v_add_f32_e32 v171, v171, v20
	v_add_f32_e32 v170, v170, v21
	v_fma_f32 v26, v26, s46, v175
	v_fma_f32 v27, v27, s46, v175
	v_fma_f32 v28, v28, s46, v175
	v_fma_f32 v29, v29, s46, v175
	v_exp_f32_e32 v26, v26
	v_exp_f32_e32 v27, v27
	v_exp_f32_e32 v28, v28
	v_exp_f32_e32 v29, v29
	v_add_f32_e32 v171, v171, v22
	v_add_f32_e32 v170, v170, v23
	v_add_f32_e32 v171, v171, v24
	v_add_f32_e32 v170, v170, v25
	v_fma_f32 v30, v30, s46, v175
	v_fma_f32 v31, v31, s46, v175
	v_fma_f32 v32, v32, s46, v175
	v_fma_f32 v33, v33, s46, v175
	v_exp_f32_e32 v30, v30
	v_exp_f32_e32 v31, v31
	v_exp_f32_e32 v32, v32
	v_exp_f32_e32 v33, v33
	v_add_f32_e32 v171, v171, v26
	v_add_f32_e32 v170, v170, v27
	v_add_f32_e32 v171, v171, v28
	v_add_f32_e32 v170, v170, v29
	v_fma_f32 v34, v34, s46, v175
	v_fma_f32 v35, v35, s46, v175
	v_fma_f32 v36, v36, s46, v175
	v_fma_f32 v37, v37, s46, v175
	v_exp_f32_e32 v34, v34
	v_exp_f32_e32 v35, v35
	v_exp_f32_e32 v36, v36
	v_exp_f32_e32 v37, v37
	v_add_f32_e32 v171, v171, v30
	v_add_f32_e32 v170, v170, v31
	v_add_f32_e32 v171, v171, v32
	v_add_f32_e32 v170, v170, v33
	v_fma_f32 v38, v38, s46, v175
	v_fma_f32 v39, v39, s46, v175
	v_fma_f32 v40, v40, s46, v175
	v_fma_f32 v41, v41, s46, v175
	v_exp_f32_e32 v38, v38
	v_exp_f32_e32 v39, v39
	v_exp_f32_e32 v40, v40
	v_exp_f32_e32 v41, v41
	v_add_f32_e32 v171, v171, v34
	v_add_f32_e32 v170, v170, v35
	v_add_f32_e32 v171, v171, v36
	v_add_f32_e32 v170, v170, v37
	v_fma_f32 v42, v42, s46, v175
	v_fma_f32 v43, v43, s46, v175
	v_fma_f32 v44, v44, s46, v175
	v_fma_f32 v45, v45, s46, v175
	v_exp_f32_e32 v42, v42
	v_exp_f32_e32 v43, v43
	v_exp_f32_e32 v44, v44
	v_exp_f32_e32 v45, v45
	v_add_f32_e32 v171, v171, v38
	v_add_f32_e32 v170, v170, v39
	v_add_f32_e32 v171, v171, v40
	v_add_f32_e32 v170, v170, v41
	v_fma_f32 v46, v46, s46, v175
	v_fma_f32 v47, v47, s46, v175
	v_fma_f32 v48, v48, s46, v175
	v_fma_f32 v49, v49, s46, v175
	v_exp_f32_e32 v46, v46
	v_exp_f32_e32 v47, v47
	v_exp_f32_e32 v48, v48
	v_exp_f32_e32 v49, v49
	v_add_f32_e32 v171, v171, v42
	v_add_f32_e32 v170, v170, v43
	v_add_f32_e32 v171, v171, v44
	v_add_f32_e32 v170, v170, v45
	v_fma_f32 v50, v50, s46, v175
	v_fma_f32 v51, v51, s46, v175
	v_fma_f32 v52, v52, s46, v175
	v_fma_f32 v53, v53, s46, v175
	v_exp_f32_e32 v50, v50
	v_exp_f32_e32 v51, v51
	v_exp_f32_e32 v52, v52
	v_exp_f32_e32 v53, v53
	v_add_f32_e32 v171, v171, v46
	v_add_f32_e32 v170, v170, v47
	v_add_f32_e32 v171, v171, v48
	v_add_f32_e32 v170, v170, v49
	v_fma_f32 v54, v54, s46, v175
	v_fma_f32 v55, v55, s46, v175
	v_fma_f32 v56, v56, s46, v175
	v_fma_f32 v57, v57, s46, v175
	v_exp_f32_e32 v54, v54
	v_exp_f32_e32 v55, v55
	v_exp_f32_e32 v56, v56
	v_exp_f32_e32 v57, v57
	v_add_f32_e32 v171, v171, v50
	v_add_f32_e32 v170, v170, v51
	v_add_f32_e32 v171, v171, v52
	v_add_f32_e32 v170, v170, v53
	v_fma_f32 v58, v58, s46, v175
	v_fma_f32 v59, v59, s46, v175
	v_fma_f32 v60, v60, s46, v175
	v_fma_f32 v61, v61, s46, v175
	v_exp_f32_e32 v58, v58
	v_exp_f32_e32 v59, v59
	v_exp_f32_e32 v60, v60
	v_exp_f32_e32 v61, v61
	v_add_f32_e32 v171, v171, v54
	v_add_f32_e32 v170, v170, v55
	v_add_f32_e32 v171, v171, v56
	v_add_f32_e32 v170, v170, v57
	v_fma_f32 v62, v62, s46, v175
	v_fma_f32 v63, v63, s46, v175
	v_fma_f32 v64, v64, s46, v175
	v_fma_f32 v65, v65, s46, v175
	v_exp_f32_e32 v62, v62
	v_exp_f32_e32 v63, v63
	v_exp_f32_e32 v64, v64
	v_exp_f32_e32 v65, v65
	v_add_f32_e32 v171, v171, v58
	v_add_f32_e32 v170, v170, v59
	v_add_f32_e32 v171, v171, v60
	v_add_f32_e32 v170, v170, v61
	v_fma_f32 v66, v66, s46, v175
	v_fma_f32 v67, v67, s46, v175
	v_fma_f32 v68, v68, s46, v175
	v_fma_f32 v69, v69, s46, v175
	v_exp_f32_e32 v66, v66
	v_exp_f32_e32 v67, v67
; __device__ __forceinline__ unsigned cvt_pk_bf16_asm(float lo, float hi) { unsigned r; asm volatile("v_cvt_pk_bf16_f32 %0, %1, %2" : "=v"(r) : "v"(lo), "v"(hi)); return r; }
; __device__ __forceinline__ f32x4 mfma16(bf16x8 a, bf16x8 b, f32x4 c) { return __builtin_amdgcn_mfma_f32_16x16x32_bf16(a, b, c, 0, 0, 0); }
; __device__ void att_phase(int wv, const Params& p, unsigned char* lds) {
;     ...
;             for (int cb = 0; cb < 24; ++cb)
; #pragma unroll
;                 for (int j = 0; j < 4; ++j) { const float e = __expf(sc[cb][j] - mx); sc[cb][j] = e; sum += e; }
;             sum += __shfl_xor(sum, 16); sum += __shfl_xor(sum, 32);
;             sum += __expf(sink - mx);
;             const float inv = 1.0f / sum;
;             f32x4 oa[4];
; #pragma unroll
;             for (int db = 0; db < 4; ++db) oa[db] = (f32x4){0, 0, 0, 0};
; #pragma unroll
;             for (int ks = 0; ks < 12; ++ks) {
;                 union { bf16x8 v; unsigned u[4]; } pf;
;                 pf.u[0] = cvt_pk_bf16_asm(sc[2 * ks][0], sc[2 * ks][1]); pf.u[1] = cvt_pk_bf16_asm(sc[2 * ks][2], sc[2 * ks][3]);
;                 pf.u[2] = cvt_pk_bf16_asm(sc[2 * ks + 1][0], sc[2 * ks + 1][1]); pf.u[3] = cvt_pk_bf16_asm(sc[2 * ks + 1][2], sc[2 * ks + 1][3]);
; #pragma unroll
;                 for (int db = 0; db < 4; ++db) {
;                     union { bf16x8 v; u32x2 h2[2]; } vf;
;                     const bf16_t* vp = VTL + (16 * db + lr) * VP + 32 * ks + 4 * lq;
;                     vf.h2[0] = *(const u32x2*)vp; vf.h2[1] = *(const u32x2*)(vp + 16);
;                     oa[db] = mfma16(vf.v, pf.v, oa[db]); } }
	v_exp_f32_e32 v68, v68
	v_exp_f32_e32 v69, v69
	v_add_f32_e32 v171, v171, v62
	v_add_f32_e32 v170, v170, v63
	v_add_f32_e32 v171, v171, v64
	v_add_f32_e32 v170, v170, v65
	v_add_f32_e32 v171, v171, v66
	v_add_f32_e32 v170, v170, v67
	v_add_f32_e32 v171, v171, v68
	v_add_f32_e32 v170, v170, v69
	v_add_f32_e32 v170, v170, v171
	v_cvt_pk_bf16_f32 v2, v2, v3
	v_cvt_pk_bf16_f32 v3, v4, v5
	v_cvt_pk_bf16_f32 v4, v6, v7
	v_cvt_pk_bf16_f32 v5, v8, v9
	v_cvt_pk_bf16_f32 v10, v10, v11
	v_cvt_pk_bf16_f32 v11, v12, v13
	v_cvt_pk_bf16_f32 v12, v14, v15
	v_cvt_pk_bf16_f32 v13, v16, v17
	v_cvt_pk_bf16_f32 v18, v18, v19
	v_cvt_pk_bf16_f32 v19, v20, v21
	v_cvt_pk_bf16_f32 v20, v22, v23
	v_cvt_pk_bf16_f32 v21, v24, v25
	v_cvt_pk_bf16_f32 v26, v26, v27
	v_cvt_pk_bf16_f32 v27, v28, v29
	v_cvt_pk_bf16_f32 v28, v30, v31
	v_cvt_pk_bf16_f32 v29, v32, v33
	v_cvt_pk_bf16_f32 v34, v34, v35
	v_cvt_pk_bf16_f32 v35, v36, v37
	v_cvt_pk_bf16_f32 v36, v38, v39
	v_cvt_pk_bf16_f32 v37, v40, v41
	v_cvt_pk_bf16_f32 v42, v42, v43
	v_cvt_pk_bf16_f32 v43, v44, v45
	v_cvt_pk_bf16_f32 v44, v46, v47
	v_cvt_pk_bf16_f32 v45, v48, v49
	v_cvt_pk_bf16_f32 v50, v50, v51
	v_cvt_pk_bf16_f32 v51, v52, v53
	v_cvt_pk_bf16_f32 v52, v54, v55
	v_cvt_pk_bf16_f32 v53, v56, v57
	v_cvt_pk_bf16_f32 v58, v58, v59
	v_cvt_pk_bf16_f32 v59, v60, v61
	v_cvt_pk_bf16_f32 v60, v62, v63
	v_cvt_pk_bf16_f32 v61, v64, v65
	v_cvt_pk_bf16_f32 v66, v66, v67
	v_cvt_pk_bf16_f32 v67, v68, v69
	v_mov_b32_e32 v68, 0
	v_mov_b32_e32 v69, 0
	ds_bpermute_b32 v172, v1, v170
	v_sub_f32_e32 v173, v146, v169
	v_mul_f32_e32 v173, 0x3fb8aa3b, v173
	v_exp_f32_e32 v173, v173
	s_waitcnt lgkmcnt(0)
	v_add_f32_e32 v170, v170, v172
	ds_bpermute_b32 v172, v114, v170
	ds_read2_b64 v[232:235], v165 offset0:12 offset1:16
	ds_read2_b64 v[236:239], v166 offset0:12 offset1:16
	ds_read2_b64 v[240:243], v167 offset0:12 offset1:16
	ds_read2_b64 v[244:247], v168 offset0:12 offset1:16
	s_waitcnt lgkmcnt(4)
	v_mfma_f32_16x16x32_bf16 v[70:73], v[216:219], v[2:5], 0
	v_mfma_f32_16x16x32_bf16 v[74:77], v[220:223], v[2:5], 0
	v_mfma_f32_16x16x32_bf16 v[78:81], v[224:227], v[2:5], 0
	v_mfma_f32_16x16x32_bf16 v[82:85], v[228:231], v[2:5], 0
	v_add_f32_e32 v170, v170, v172
	v_add_f32_e32 v170, v170, v173
	v_rcp_f32_e32 v147, v170
	s_nop 0
	v_fma_f32 v179, -v170, v147, 1.0
	v_fmac_f32_e32 v147, v179, v147
	ds_read2_b64 v[216:219], v165 offset0:20 offset1:24
	ds_read2_b64 v[220:223], v166 offset0:20 offset1:24
	ds_read2_b64 v[224:227], v167 offset0:20 offset1:24
	ds_read2_b64 v[228:231], v168 offset0:20 offset1:24
	s_waitcnt lgkmcnt(4)
	v_mfma_f32_16x16x32_bf16 v[70:73], v[232:235], v[10:13], v[70:73]
	v_mfma_f32_16x16x32_bf16 v[74:77], v[236:239], v[10:13], v[74:77]
	v_mfma_f32_16x16x32_bf16 v[78:81], v[240:243], v[10:13], v[78:81]
	v_mfma_f32_16x16x32_bf16 v[82:85], v[244:247], v[10:13], v[82:85]
	ds_read2_b64 v[232:235], v165 offset0:28 offset1:32
	ds_read2_b64 v[236:239], v166 offset0:28 offset1:32
	ds_read2_b64 v[240:243], v167 offset0:28 offset1:32
	ds_read2_b64 v[244:247], v168 offset0:28 offset1:32
	s_waitcnt lgkmcnt(4)
	v_mfma_f32_16x16x32_bf16 v[70:73], v[216:219], v[18:21], v[70:73]
	v_mfma_f32_16x16x32_bf16 v[74:77], v[220:223], v[18:21], v[74:77]
	v_mfma_f32_16x16x32_bf16 v[78:81], v[224:227], v[18:21], v[78:81]
	v_mfma_f32_16x16x32_bf16 v[82:85], v[228:231], v[18:21], v[82:85]
	ds_read2_b64 v[216:219], v165 offset0:36 offset1:40
	ds_read2_b64 v[220:223], v166 offset0:36 offset1:40
	ds_read2_b64 v[224:227], v167 offset0:36 offset1:40
	ds_read2_b64 v[228:231], v168 offset0:36 offset1:40
	s_waitcnt lgkmcnt(4)
	v_mfma_f32_16x16x32_bf16 v[70:73], v[232:235], v[26:29], v[70:73]
	v_mfma_f32_16x16x32_bf16 v[74:77], v[236:239], v[26:29], v[74:77]
	v_mfma_f32_16x16x32_bf16 v[78:81], v[240:243], v[26:29], v[78:81]
	v_mfma_f32_16x16x32_bf16 v[82:85], v[244:247], v[26:29], v[82:85]
	ds_read2_b64 v[232:235], v165 offset0:44 offset1:48
	ds_read2_b64 v[236:239], v166 offset0:44 offset1:48
	ds_read2_b64 v[240:243], v167 offset0:44 offset1:48
	ds_read2_b64 v[244:247], v168 offset0:44 offset1:48
	s_waitcnt lgkmcnt(4)
	v_mfma_f32_16x16x32_bf16 v[70:73], v[216:219], v[34:37], v[70:73]
	v_mfma_f32_16x16x32_bf16 v[74:77], v[220:223], v[34:37], v[74:77]
	v_mfma_f32_16x16x32_bf16 v[78:81], v[224:227], v[34:37], v[78:81]
	v_mfma_f32_16x16x32_bf16 v[82:85], v[228:231], v[34:37], v[82:85]
	ds_read2_b64 v[216:219], v165 offset0:52 offset1:56
	ds_read2_b64 v[220:223], v166 offset0:52 offset1:56
	ds_read2_b64 v[224:227], v167 offset0:52 offset1:56
	ds_read2_b64 v[228:231], v168 offset0:52 offset1:56
	s_waitcnt lgkmcnt(4)
	v_mfma_f32_16x16x32_bf16 v[70:73], v[232:235], v[42:45], v[70:73]
	v_mfma_f32_16x16x32_bf16 v[74:77], v[236:239], v[42:45], v[74:77]
	v_mfma_f32_16x16x32_bf16 v[78:81], v[240:243], v[42:45], v[78:81]
	v_mfma_f32_16x16x32_bf16 v[82:85], v[244:247], v[42:45], v[82:85]
	ds_read2_b64 v[232:235], v165 offset0:60 offset1:64
	ds_read2_b64 v[236:239], v166 offset0:60 offset1:64
	ds_read2_b64 v[240:243], v167 offset0:60 offset1:64
	ds_read2_b64 v[244:247], v168 offset0:60 offset1:64
	s_waitcnt lgkmcnt(4)
	v_mfma_f32_16x16x32_bf16 v[70:73], v[216:219], v[50:53], v[70:73]
	v_mfma_f32_16x16x32_bf16 v[74:77], v[220:223], v[50:53], v[74:77]
	v_mfma_f32_16x16x32_bf16 v[78:81], v[224:227], v[50:53], v[78:81]
	v_mfma_f32_16x16x32_bf16 v[82:85], v[228:231], v[50:53], v[82:85]
	ds_read2_b64 v[216:219], v165 offset0:68 offset1:68
	ds_read2_b64 v[220:223], v166 offset0:68 offset1:68
	ds_read2_b64 v[224:227], v167 offset0:68 offset1:68
	ds_read2_b64 v[228:231], v168 offset0:68 offset1:68
	s_waitcnt lgkmcnt(4)
; __device__ void att_phase(int wv, const Params& p, unsigned char* lds) {
;     ...
;         for (int rb = 0; rb < 4; ++rb) {
;             const int qrow = 64 * (w & 1) + 16 * rb + lr;
;             const size_t tokq = (size_t)B * 128 + qrow;
;             bf16x8 qf[2];
; #pragma unroll
;             for (int kk = 0; kk < 2; ++kk) qf[kk] = *(const bf16x8*)(qkv + tokq * 1536 + 64 * h + 32 * kk + 8 * lq);
;             f32x4 sc[24];
; #pragma unroll
;             for (int cb = 0; cb < 24; ++cb) { f32x4 a = {0, 0, 0, 0};
; #pragma unroll
;                 for (int kk = 0; kk < 2; ++kk) { const bf16x8 kf = *(const bf16x8*)(KL + (16 * cb + lr) * KP + 32 * kk + 8 * lq); a = mfma16(kf, qf[kk], a); }
;                 sc[cb] = a; }
;             float mx = sink;
; #pragma unroll
;             for (int cb = 0; cb < 24; ++cb) { const int kb = B - 1 + (cb >> 3); const bool bval = (kb >= sb && kb < se);
; #pragma unroll
;                 for (int j = 0; j < 4; ++j) { const int krel = 16 * cb + 4 * lq + j - 128;
;                     int dist = qrow - krel; dist = dist < 0 ? -dist : dist;
;                     const float v = (bval && dist <= 128) ? sc[cb][j] * 0.125f - slope * (float)dist : -1e30f;
;                     sc[cb][j] = v; mx = fmaxf(mx, v); } }
;     ...
;             for (int ks = 0; ks < 12; ++ks) {
;                 union { bf16x8 v; unsigned u[4]; } pf;
;                 pf.u[0] = cvt_pk_bf16_asm(sc[2 * ks][0], sc[2 * ks][1]); pf.u[1] = cvt_pk_bf16_asm(sc[2 * ks][2], sc[2 * ks][3]);
;                 pf.u[2] = cvt_pk_bf16_asm(sc[2 * ks + 1][0], sc[2 * ks + 1][1]); pf.u[3] = cvt_pk_bf16_asm(sc[2 * ks + 1][2], sc[2 * ks + 1][3]);
; #pragma unroll
;                 for (int db = 0; db < 4; ++db) {
;                     union { bf16x8 v; u32x2 h2[2]; } vf;
;                     const bf16_t* vp = VTL + (16 * db + lr) * VP + 32 * ks + 4 * lq;
;                     vf.h2[0] = *(const u32x2*)vp; vf.h2[1] = *(const u32x2*)(vp + 16);
;                     oa[db] = mfma16(vf.v, pf.v, oa[db]); } }
; #pragma unroll
;             for (int db = 0; db < 4; ++db) { const f32x4 o = oa[db] * inv; u32x2 wv; wv.x = cvt_pk_bf16_asm(o[0], o[1]); wv.y = cvt_pk_bf16_asm(o[2], o[3]);
;                 *(u32x2*)(qkv + tokq * 1536 + 64 * h + 16 * db + 4 * lq) = wv; }
	v_mfma_f32_16x16x32_bf16 v[70:73], v[232:235], v[58:61], v[70:73]
	v_mfma_f32_16x16x32_bf16 v[74:77], v[236:239], v[58:61], v[74:77]
	v_mfma_f32_16x16x32_bf16 v[78:81], v[240:243], v[58:61], v[78:81]
	v_mfma_f32_16x16x32_bf16 v[82:85], v[244:247], v[58:61], v[82:85]
	s_waitcnt lgkmcnt(0)
	v_mfma_f32_16x16x32_bf16 v[70:73], v[216:219], v[66:69], v[70:73]
	v_mfma_f32_16x16x32_bf16 v[74:77], v[220:223], v[66:69], v[74:77]
	v_mfma_f32_16x16x32_bf16 v[78:81], v[224:227], v[66:69], v[78:81]
	v_mfma_f32_16x16x32_bf16 v[82:85], v[228:231], v[66:69], v[82:85]
	s_nop 7
	s_nop 1
	v_mul_f32_e32 v70, v70, v147
	v_mul_f32_e32 v71, v71, v147
	v_mul_f32_e32 v72, v72, v147
	v_mul_f32_e32 v73, v73, v147
	v_mul_f32_e32 v74, v74, v147
	v_mul_f32_e32 v75, v75, v147
	v_mul_f32_e32 v76, v76, v147
	v_mul_f32_e32 v77, v77, v147
	v_mul_f32_e32 v78, v78, v147
	v_mul_f32_e32 v79, v79, v147
	v_mul_f32_e32 v80, v80, v147
	v_mul_f32_e32 v81, v81, v147
	v_mul_f32_e32 v82, v82, v147
	v_mul_f32_e32 v83, v83, v147
	v_mul_f32_e32 v84, v84, v147
	v_mul_f32_e32 v85, v85, v147
	v_cvt_pk_bf16_f32 v70, v70, v71
	v_cvt_pk_bf16_f32 v71, v72, v73
	v_cvt_pk_bf16_f32 v74, v74, v75
	v_cvt_pk_bf16_f32 v75, v76, v77
	v_cvt_pk_bf16_f32 v78, v78, v79
	v_cvt_pk_bf16_f32 v79, v80, v81
	v_cvt_pk_bf16_f32 v82, v82, v83
	v_cvt_pk_bf16_f32 v83, v84, v85
	global_store_dwordx2 v[248:249], v[70:71], off offset:-64
	global_store_dwordx2 v[248:249], v[74:75], off offset:-32
	global_store_dwordx2 v[248:249], v[78:79], off
	global_store_dwordx2 v[248:249], v[82:83], off offset:32
	v_lshl_add_u64 v[248:249], v[248:249], 0, s[48:49]
	v_sub_f32_e32 v86, v94, v176
	v_sub_f32_e32 v87, v95, v176
	v_sub_f32_e32 v88, v96, v176
	v_sub_f32_e32 v89, v97, v176
	v_cmp_ge_i32_e32 vcc, 0, v108
	s_nop 1
	v_cndmask_b32_e32 v212, v252, v86, vcc
	v_cmp_ge_i32_e32 vcc, 0, v110
	s_nop 1
	v_cndmask_b32_e32 v213, v252, v87, vcc
	v_cmp_ge_i32_e32 vcc, 0, v111
	s_nop 1
	v_cndmask_b32_e32 v214, v252, v88, vcc
	v_cmp_ge_i32_e32 vcc, 0, v177
	s_nop 1
	v_cndmask_b32_e32 v215, v252, v89, vcc
	ds_read_b128 v[148:151], v164 offset:4608
	ds_read_b128 v[152:155], v164 offset:4672
	ds_read_b128 v[156:159], v164 offset:6912
	ds_read_b128 v[160:163], v164 offset:6976
	v_add_f32_e32 v90, v86, v174
	v_add_f32_e32 v91, v87, v174
	v_add_f32_e32 v92, v88, v174
	v_add_f32_e32 v93, v89, v174
	s_waitcnt lgkmcnt(2)
	v_mfma_f32_16x16x32_bf16 v[2:5], v[148:151], v[196:199], v[212:215]
	v_mfma_f32_16x16x32_bf16 v[2:5], v[152:155], v[200:203], v[2:5]
	ds_read_b128 v[148:151], v164 offset:9216
	ds_read_b128 v[152:155], v164 offset:9280
	v_add_f32_e32 v86, v90, v174
	v_add_f32_e32 v87, v91, v174
	v_add_f32_e32 v88, v92, v174
	v_add_f32_e32 v89, v93, v174
	s_waitcnt lgkmcnt(2)
	v_mfma_f32_16x16x32_bf16 v[6:9], v[156:159], v[196:199], v[90:93]
	v_mfma_f32_16x16x32_bf16 v[6:9], v[160:163], v[200:203], v[6:9]
	ds_read_b128 v[156:159], v164 offset:11520
	ds_read_b128 v[160:163], v164 offset:11584
	v_add_f32_e32 v90, v86, v174
	v_add_f32_e32 v91, v87, v174
	v_add_f32_e32 v92, v88, v174
	v_add_f32_e32 v93, v89, v174
	s_waitcnt lgkmcnt(2)
	v_mfma_f32_16x16x32_bf16 v[10:13], v[148:151], v[196:199], v[86:89]
	v_mfma_f32_16x16x32_bf16 v[10:13], v[152:155], v[200:203], v[10:13]
	ds_read_b128 v[148:151], v164 offset:13824
	ds_read_b128 v[152:155], v164 offset:13888
	v_add_f32_e32 v86, v90, v174
	v_add_f32_e32 v87, v91, v174
	v_add_f32_e32 v88, v92, v174
	v_add_f32_e32 v89, v93, v174
	s_waitcnt lgkmcnt(2)
	v_mfma_f32_16x16x32_bf16 v[14:17], v[156:159], v[196:199], v[90:93]
	v_mfma_f32_16x16x32_bf16 v[14:17], v[160:163], v[200:203], v[14:17]
	ds_read_b128 v[156:159], v164 offset:16128
	ds_read_b128 v[160:163], v164 offset:16192
	v_add_f32_e32 v90, v86, v174
	v_add_f32_e32 v91, v87, v174
	v_add_f32_e32 v92, v88, v174
	v_add_f32_e32 v93, v89, v174
	s_waitcnt lgkmcnt(2)
	v_mfma_f32_16x16x32_bf16 v[18:21], v[148:151], v[196:199], v[86:89]
	v_mfma_f32_16x16x32_bf16 v[18:21], v[152:155], v[200:203], v[18:21]
	ds_read_b128 v[148:151], v164 offset:18432
	ds_read_b128 v[152:155], v164 offset:18496
	v_add_f32_e32 v86, v90, v174
	v_add_f32_e32 v87, v91, v174
	v_add_f32_e32 v88, v92, v174
	v_add_f32_e32 v89, v93, v174
	s_waitcnt lgkmcnt(2)
	v_mfma_f32_16x16x32_bf16 v[22:25], v[156:159], v[196:199], v[90:93]
	v_mfma_f32_16x16x32_bf16 v[22:25], v[160:163], v[200:203], v[22:25]
	ds_read_b128 v[156:159], v164 offset:20736
	ds_read_b128 v[160:163], v164 offset:20800
	v_add_f32_e32 v90, v86, v174
	v_add_f32_e32 v91, v87, v174
	v_add_f32_e32 v92, v88, v174
	v_add_f32_e32 v93, v89, v174
	s_waitcnt lgkmcnt(2)
	v_mfma_f32_16x16x32_bf16 v[26:29], v[148:151], v[196:199], v[86:89]
	v_mfma_f32_16x16x32_bf16 v[26:29], v[152:155], v[200:203], v[26:29]
	ds_read_b128 v[148:151], v164 offset:23040
	ds_read_b128 v[152:155], v164 offset:23104
	s_waitcnt lgkmcnt(2)
	v_mfma_f32_16x16x32_bf16 v[30:33], v[156:159], v[196:199], v[90:93]
	v_mfma_f32_16x16x32_bf16 v[30:33], v[160:163], v[200:203], v[30:33]
	ds_read_b128 v[156:159], v164 offset:25344
	ds_read_b128 v[160:163], v164 offset:25408
	v_sub_f32_e64 v86, -v94, v174
	v_sub_f32_e64 v87, -v95, v174
	v_sub_f32_e64 v88, -v96, v174
	v_sub_f32_e64 v89, -v97, v174
	s_waitcnt lgkmcnt(2)
	v_mfma_f32_16x16x32_bf16 v[34:37], v[148:151], v[196:199], v[98:101]
	v_mfma_f32_16x16x32_bf16 v[34:37], v[152:155], v[200:203], v[34:37]
	ds_read_b128 v[148:151], v164 offset:27648
	ds_read_b128 v[152:155], v164 offset:27712
	v_sub_f32_e32 v90, v86, v174
	v_sub_f32_e32 v91, v87, v174
	v_sub_f32_e32 v92, v88, v174
	v_sub_f32_e32 v93, v89, v174
	s_waitcnt lgkmcnt(2)
; __device__ __forceinline__ f32x4 mfma16(bf16x8 a, bf16x8 b, f32x4 c) { return __builtin_amdgcn_mfma_f32_16x16x32_bf16(a, b, c, 0, 0, 0); }
; __device__ void att_phase(int wv, const Params& p, unsigned char* lds) {
;     ...
;             for (int cb = 0; cb < 24; ++cb) { f32x4 a = {0, 0, 0, 0};
; #pragma unroll
;                 for (int kk = 0; kk < 2; ++kk) { const bf16x8 kf = *(const bf16x8*)(KL + (16 * cb + lr) * KP + 32 * kk + 8 * lq); a = mfma16(kf, qf[kk], a); }
;                 sc[cb] = a; }
;             float mx = sink;
; #pragma unroll
;             for (int cb = 0; cb < 24; ++cb) { const int kb = B - 1 + (cb >> 3); const bool bval = (kb >= sb && kb < se);
; #pragma unroll
;                 for (int j = 0; j < 4; ++j) { const int krel = 16 * cb + 4 * lq + j - 128;
;                     int dist = qrow - krel; dist = dist < 0 ? -dist : dist;
;                     const float v = (bval && dist <= 128) ? sc[cb][j] * 0.125f - slope * (float)dist : -1e30f;
;                     sc[cb][j] = v; mx = fmaxf(mx, v); } }
;             mx = fmaxf(mx, __shfl_xor(mx, 16)); mx = fmaxf(mx, __shfl_xor(mx, 32));
	v_mfma_f32_16x16x32_bf16 v[38:41], v[156:159], v[196:199], v[86:89]
	v_mfma_f32_16x16x32_bf16 v[38:41], v[160:163], v[200:203], v[38:41]
	ds_read_b128 v[156:159], v164 offset:29952
	ds_read_b128 v[160:163], v164 offset:30016
	v_sub_f32_e32 v86, v90, v174
	v_sub_f32_e32 v87, v91, v174
	v_sub_f32_e32 v88, v92, v174
	v_sub_f32_e32 v89, v93, v174
	s_waitcnt lgkmcnt(2)
	v_mfma_f32_16x16x32_bf16 v[42:45], v[148:151], v[196:199], v[90:93]
	v_mfma_f32_16x16x32_bf16 v[42:45], v[152:155], v[200:203], v[42:45]
	ds_read_b128 v[148:151], v164 offset:32256
	ds_read_b128 v[152:155], v164 offset:32320
	v_sub_f32_e32 v90, v86, v174
	v_sub_f32_e32 v91, v87, v174
	v_sub_f32_e32 v92, v88, v174
	v_sub_f32_e32 v93, v89, v174
	s_waitcnt lgkmcnt(2)
	v_mfma_f32_16x16x32_bf16 v[46:49], v[156:159], v[196:199], v[86:89]
	v_mfma_f32_16x16x32_bf16 v[46:49], v[160:163], v[200:203], v[46:49]
	ds_read_b128 v[156:159], v164 offset:34560
	ds_read_b128 v[160:163], v164 offset:34624
	v_sub_f32_e32 v86, v90, v174
	v_sub_f32_e32 v87, v91, v174
	v_sub_f32_e32 v88, v92, v174
	v_sub_f32_e32 v89, v93, v174
	s_waitcnt lgkmcnt(2)
	v_mfma_f32_16x16x32_bf16 v[50:53], v[148:151], v[196:199], v[90:93]
	v_mfma_f32_16x16x32_bf16 v[50:53], v[152:155], v[200:203], v[50:53]
	ds_read_b128 v[148:151], v164 offset:36864
	ds_read_b128 v[152:155], v164 offset:36928
	v_sub_f32_e32 v90, v86, v174
	v_sub_f32_e32 v91, v87, v174
	v_sub_f32_e32 v92, v88, v174
	v_sub_f32_e32 v93, v89, v174
	s_waitcnt lgkmcnt(2)
	v_mfma_f32_16x16x32_bf16 v[54:57], v[156:159], v[196:199], v[86:89]
	v_mfma_f32_16x16x32_bf16 v[54:57], v[160:163], v[200:203], v[54:57]
	ds_read_b128 v[156:159], v164 offset:39168
	ds_read_b128 v[160:163], v164 offset:39232
	v_sub_f32_e32 v86, v90, v174
	v_sub_f32_e32 v87, v91, v174
	v_sub_f32_e32 v88, v92, v174
	v_sub_f32_e32 v89, v93, v174
	s_waitcnt lgkmcnt(2)
	v_mfma_f32_16x16x32_bf16 v[58:61], v[148:151], v[196:199], v[90:93]
	v_mfma_f32_16x16x32_bf16 v[58:61], v[152:155], v[200:203], v[58:61]
	ds_read_b128 v[148:151], v164 offset:41472
	ds_read_b128 v[152:155], v164 offset:41536
	v_sub_f32_e32 v90, v86, v174
	v_sub_f32_e32 v91, v87, v174
	v_sub_f32_e32 v92, v88, v174
	v_sub_f32_e32 v93, v89, v174
	v_cmp_le_i32_e32 vcc, 0, v108
	s_nop 1
	v_cndmask_b32_e32 v212, v252, v90, vcc
	v_cmp_le_i32_e32 vcc, 0, v110
	s_nop 1
	v_cndmask_b32_e32 v213, v252, v91, vcc
	v_cmp_le_i32_e32 vcc, 0, v111
	s_nop 1
	v_cndmask_b32_e32 v214, v252, v92, vcc
	v_cmp_le_i32_e32 vcc, 0, v177
	s_nop 1
	v_cndmask_b32_e32 v215, v252, v93, vcc
	s_waitcnt lgkmcnt(2)
	v_mfma_f32_16x16x32_bf16 v[62:65], v[156:159], v[196:199], v[86:89]
	v_mfma_f32_16x16x32_bf16 v[62:65], v[160:163], v[200:203], v[62:65]
	s_waitcnt lgkmcnt(0)
	v_mfma_f32_16x16x32_bf16 v[66:69], v[148:151], v[196:199], v[212:215]
	v_mfma_f32_16x16x32_bf16 v[66:69], v[152:155], v[200:203], v[66:69]
	ds_read2_b64 v[216:219], v165 offset0:8 offset1:12
	ds_read2_b64 v[220:223], v166 offset0:8 offset1:12
	ds_read2_b64 v[224:227], v167 offset0:8 offset1:12
	ds_read2_b64 v[228:231], v168 offset0:8 offset1:12
	v_max3_f32 v169, v2, v3, v4
	v_max3_f32 v172, v5, v6, v7
	v_max3_f32 v169, v8, v9, v169
	v_max3_f32 v172, v10, v11, v172
	v_max3_f32 v169, v12, v13, v169
	v_max3_f32 v172, v14, v15, v172
	v_max3_f32 v169, v16, v17, v169
	v_max3_f32 v172, v18, v19, v172
	v_max3_f32 v169, v20, v21, v169
	v_max3_f32 v172, v22, v23, v172
	v_max3_f32 v169, v24, v25, v169
	v_max3_f32 v172, v26, v27, v172
	v_max3_f32 v169, v28, v29, v169
	v_max3_f32 v172, v30, v31, v172
	v_max3_f32 v169, v32, v33, v169
	v_max3_f32 v172, v34, v35, v172
	v_max3_f32 v169, v36, v37, v169
	v_max3_f32 v172, v38, v39, v172
	v_max3_f32 v169, v40, v41, v169
	v_max3_f32 v172, v42, v43, v172
	v_max3_f32 v169, v44, v45, v169
	v_max3_f32 v172, v46, v47, v172
	v_max3_f32 v169, v48, v49, v169
	v_max3_f32 v172, v50, v51, v172
	v_max3_f32 v169, v52, v53, v169
	v_max3_f32 v172, v54, v55, v172
	v_max3_f32 v169, v56, v57, v169
	v_max3_f32 v172, v58, v59, v172
	v_max3_f32 v169, v60, v61, v169
	v_max3_f32 v172, v62, v63, v172
	v_max3_f32 v169, v64, v65, v169
	v_max3_f32 v172, v66, v67, v172
	v_max3_f32 v169, v68, v69, v169
	v_max_f32_e32 v169, v169, v172
	v_mul_f32_e32 v169, 0x3e000000, v169
	v_max_f32_e32 v169, v169, v146
	ds_bpermute_b32 v172, v1, v169
	s_waitcnt lgkmcnt(0)
	v_max_f32_e32 v169, v169, v172
	ds_bpermute_b32 v172, v114, v169
	s_waitcnt lgkmcnt(0)
; __device__ void att_phase(int wv, const Params& p, unsigned char* lds) {
;     ...
;             float sum = 0.f;
; #pragma unroll
;             for (int cb = 0; cb < 24; ++cb)
; #pragma unroll
;                 for (int j = 0; j < 4; ++j) { const float e = __expf(sc[cb][j] - mx); sc[cb][j] = e; sum += e; }
	v_max_f32_e32 v169, v169, v172
	v_mul_f32_e32 v175, 0xbfb8aa3b, v169
	v_mov_b32_e32 v170, 0
	v_mov_b32_e32 v171, 0
	v_fma_f32 v2, v2, s46, v175
	v_fma_f32 v3, v3, s46, v175
	v_fma_f32 v4, v4, s46, v175
	v_fma_f32 v5, v5, s46, v175
	v_exp_f32_e32 v2, v2
	v_exp_f32_e32 v3, v3
	v_exp_f32_e32 v4, v4
	v_exp_f32_e32 v5, v5
	v_fma_f32 v6, v6, s46, v175
	v_fma_f32 v7, v7, s46, v175
	v_fma_f32 v8, v8, s46, v175
	v_fma_f32 v9, v9, s46, v175
	v_exp_f32_e32 v6, v6
	v_exp_f32_e32 v7, v7
	v_exp_f32_e32 v8, v8
	v_exp_f32_e32 v9, v9
	v_add_f32_e32 v171, v171, v2
	v_add_f32_e32 v170, v170, v3
	v_add_f32_e32 v171, v171, v4
	v_add_f32_e32 v170, v170, v5
	v_fma_f32 v10, v10, s46, v175
	v_fma_f32 v11, v11, s46, v175
	v_fma_f32 v12, v12, s46, v175
	v_fma_f32 v13, v13, s46, v175
	v_exp_f32_e32 v10, v10
	v_exp_f32_e32 v11, v11
	v_exp_f32_e32 v12, v12
	v_exp_f32_e32 v13, v13
	v_add_f32_e32 v171, v171, v6
	v_add_f32_e32 v170, v170, v7
	v_add_f32_e32 v171, v171, v8
	v_add_f32_e32 v170, v170, v9
	v_fma_f32 v14, v14, s46, v175
	v_fma_f32 v15, v15, s46, v175
	v_fma_f32 v16, v16, s46, v175
	v_fma_f32 v17, v17, s46, v175
	v_exp_f32_e32 v14, v14
	v_exp_f32_e32 v15, v15
	v_exp_f32_e32 v16, v16
	v_exp_f32_e32 v17, v17
	v_add_f32_e32 v171, v171, v10
	v_add_f32_e32 v170, v170, v11
	v_add_f32_e32 v171, v171, v12
	v_add_f32_e32 v170, v170, v13
	v_fma_f32 v18, v18, s46, v175
	v_fma_f32 v19, v19, s46, v175
	v_fma_f32 v20, v20, s46, v175
	v_fma_f32 v21, v21, s46, v175
	v_exp_f32_e32 v18, v18
	v_exp_f32_e32 v19, v19
	v_exp_f32_e32 v20, v20
	v_exp_f32_e32 v21, v21
	v_add_f32_e32 v171, v171, v14
	v_add_f32_e32 v170, v170, v15
	v_add_f32_e32 v171, v171, v16
	v_add_f32_e32 v170, v170, v17
	v_fma_f32 v22, v22, s46, v175
	v_fma_f32 v23, v23, s46, v175
	v_fma_f32 v24, v24, s46, v175
	v_fma_f32 v25, v25, s46, v175
	v_exp_f32_e32 v22, v22
	v_exp_f32_e32 v23, v23
	v_exp_f32_e32 v24, v24
	v_exp_f32_e32 v25, v25
	v_add_f32_e32 v171, v171, v18
	v_add_f32_e32 v170, v170, v19
	v_add_f32_e32 v171, v171, v20
	v_add_f32_e32 v170, v170, v21
	v_fma_f32 v26, v26, s46, v175
	v_fma_f32 v27, v27, s46, v175
	v_fma_f32 v28, v28, s46, v175
	v_fma_f32 v29, v29, s46, v175
	v_exp_f32_e32 v26, v26
	v_exp_f32_e32 v27, v27
	v_exp_f32_e32 v28, v28
	v_exp_f32_e32 v29, v29
	v_add_f32_e32 v171, v171, v22
	v_add_f32_e32 v170, v170, v23
	v_add_f32_e32 v171, v171, v24
	v_add_f32_e32 v170, v170, v25
	v_fma_f32 v30, v30, s46, v175
	v_fma_f32 v31, v31, s46, v175
	v_fma_f32 v32, v32, s46, v175
	v_fma_f32 v33, v33, s46, v175
	v_exp_f32_e32 v30, v30
	v_exp_f32_e32 v31, v31
	v_exp_f32_e32 v32, v32
	v_exp_f32_e32 v33, v33
	v_add_f32_e32 v171, v171, v26
	v_add_f32_e32 v170, v170, v27
	v_add_f32_e32 v171, v171, v28
	v_add_f32_e32 v170, v170, v29
	v_fma_f32 v34, v34, s46, v175
	v_fma_f32 v35, v35, s46, v175
	v_fma_f32 v36, v36, s46, v175
	v_fma_f32 v37, v37, s46, v175
	v_exp_f32_e32 v34, v34
	v_exp_f32_e32 v35, v35
	v_exp_f32_e32 v36, v36
	v_exp_f32_e32 v37, v37
	v_add_f32_e32 v171, v171, v30
	v_add_f32_e32 v170, v170, v31
	v_add_f32_e32 v171, v171, v32
	v_add_f32_e32 v170, v170, v33
	v_fma_f32 v38, v38, s46, v175
	v_fma_f32 v39, v39, s46, v175
	v_fma_f32 v40, v40, s46, v175
	v_fma_f32 v41, v41, s46, v175
	v_exp_f32_e32 v38, v38
	v_exp_f32_e32 v39, v39
	v_exp_f32_e32 v40, v40
	v_exp_f32_e32 v41, v41
	v_add_f32_e32 v171, v171, v34
	v_add_f32_e32 v170, v170, v35
	v_add_f32_e32 v171, v171, v36
	v_add_f32_e32 v170, v170, v37
	v_fma_f32 v42, v42, s46, v175
	v_fma_f32 v43, v43, s46, v175
	v_fma_f32 v44, v44, s46, v175
	v_fma_f32 v45, v45, s46, v175
	v_exp_f32_e32 v42, v42
	v_exp_f32_e32 v43, v43
	v_exp_f32_e32 v44, v44
	v_exp_f32_e32 v45, v45
	v_add_f32_e32 v171, v171, v38
	v_add_f32_e32 v170, v170, v39
	v_add_f32_e32 v171, v171, v40
	v_add_f32_e32 v170, v170, v41
	v_fma_f32 v46, v46, s46, v175
	v_fma_f32 v47, v47, s46, v175
	v_fma_f32 v48, v48, s46, v175
	v_fma_f32 v49, v49, s46, v175
	v_exp_f32_e32 v46, v46
	v_exp_f32_e32 v47, v47
	v_exp_f32_e32 v48, v48
	v_exp_f32_e32 v49, v49
	v_add_f32_e32 v171, v171, v42
	v_add_f32_e32 v170, v170, v43
	v_add_f32_e32 v171, v171, v44
	v_add_f32_e32 v170, v170, v45
	v_fma_f32 v50, v50, s46, v175
	v_fma_f32 v51, v51, s46, v175
	v_fma_f32 v52, v52, s46, v175
	v_fma_f32 v53, v53, s46, v175
	v_exp_f32_e32 v50, v50
	v_exp_f32_e32 v51, v51
	v_exp_f32_e32 v52, v52
	v_exp_f32_e32 v53, v53
	v_add_f32_e32 v171, v171, v46
	v_add_f32_e32 v170, v170, v47
	v_add_f32_e32 v171, v171, v48
	v_add_f32_e32 v170, v170, v49
	v_fma_f32 v54, v54, s46, v175
	v_fma_f32 v55, v55, s46, v175
	v_fma_f32 v56, v56, s46, v175
	v_fma_f32 v57, v57, s46, v175
	v_exp_f32_e32 v54, v54
	v_exp_f32_e32 v55, v55
	v_exp_f32_e32 v56, v56
	v_exp_f32_e32 v57, v57
	v_add_f32_e32 v171, v171, v50
	v_add_f32_e32 v170, v170, v51
	v_add_f32_e32 v171, v171, v52
	v_add_f32_e32 v170, v170, v53
	v_fma_f32 v58, v58, s46, v175
	v_fma_f32 v59, v59, s46, v175
	v_fma_f32 v60, v60, s46, v175
	v_fma_f32 v61, v61, s46, v175
	v_exp_f32_e32 v58, v58
	v_exp_f32_e32 v59, v59
	v_exp_f32_e32 v60, v60
	v_exp_f32_e32 v61, v61
	v_add_f32_e32 v171, v171, v54
	v_add_f32_e32 v170, v170, v55
	v_add_f32_e32 v171, v171, v56
	v_add_f32_e32 v170, v170, v57
	v_fma_f32 v62, v62, s46, v175
	v_fma_f32 v63, v63, s46, v175
	v_fma_f32 v64, v64, s46, v175
	v_fma_f32 v65, v65, s46, v175
	v_exp_f32_e32 v62, v62
	v_exp_f32_e32 v63, v63
	v_exp_f32_e32 v64, v64
	v_exp_f32_e32 v65, v65
	v_add_f32_e32 v171, v171, v58
	v_add_f32_e32 v170, v170, v59
	v_add_f32_e32 v171, v171, v60
	v_add_f32_e32 v170, v170, v61
	v_fma_f32 v66, v66, s46, v175
	v_fma_f32 v67, v67, s46, v175
	v_fma_f32 v68, v68, s46, v175
	v_fma_f32 v69, v69, s46, v175
	v_exp_f32_e32 v66, v66
	v_exp_f32_e32 v67, v67
; __device__ __forceinline__ unsigned cvt_pk_bf16_asm(float lo, float hi) { unsigned r; asm volatile("v_cvt_pk_bf16_f32 %0, %1, %2" : "=v"(r) : "v"(lo), "v"(hi)); return r; }
; __device__ __forceinline__ f32x4 mfma16(bf16x8 a, bf16x8 b, f32x4 c) { return __builtin_amdgcn_mfma_f32_16x16x32_bf16(a, b, c, 0, 0, 0); }
; __device__ void att_phase(int wv, const Params& p, unsigned char* lds) {
;     ...
;             for (int cb = 0; cb < 24; ++cb)
; #pragma unroll
;                 for (int j = 0; j < 4; ++j) { const float e = __expf(sc[cb][j] - mx); sc[cb][j] = e; sum += e; }
;             sum += __shfl_xor(sum, 16); sum += __shfl_xor(sum, 32);
;             sum += __expf(sink - mx);
;             const float inv = 1.0f / sum;
;             f32x4 oa[4];
; #pragma unroll
;             for (int db = 0; db < 4; ++db) oa[db] = (f32x4){0, 0, 0, 0};
; #pragma unroll
;             for (int ks = 0; ks < 12; ++ks) {
;                 union { bf16x8 v; unsigned u[4]; } pf;
;                 pf.u[0] = cvt_pk_bf16_asm(sc[2 * ks][0], sc[2 * ks][1]); pf.u[1] = cvt_pk_bf16_asm(sc[2 * ks][2], sc[2 * ks][3]);
;                 pf.u[2] = cvt_pk_bf16_asm(sc[2 * ks + 1][0], sc[2 * ks + 1][1]); pf.u[3] = cvt_pk_bf16_asm(sc[2 * ks + 1][2], sc[2 * ks + 1][3]);
; #pragma unroll
;                 for (int db = 0; db < 4; ++db) {
;                     union { bf16x8 v; u32x2 h2[2]; } vf;
;                     const bf16_t* vp = VTL + (16 * db + lr) * VP + 32 * ks + 4 * lq;
;                     vf.h2[0] = *(const u32x2*)vp; vf.h2[1] = *(const u32x2*)(vp + 16);
;                     oa[db] = mfma16(vf.v, pf.v, oa[db]); } }
	v_exp_f32_e32 v68, v68
	v_exp_f32_e32 v69, v69
	v_add_f32_e32 v171, v171, v62
	v_add_f32_e32 v170, v170, v63
	v_add_f32_e32 v171, v171, v64
	v_add_f32_e32 v170, v170, v65
	v_add_f32_e32 v171, v171, v66
	v_add_f32_e32 v170, v170, v67
	v_add_f32_e32 v171, v171, v68
	v_add_f32_e32 v170, v170, v69
	v_add_f32_e32 v170, v170, v171
	v_cvt_pk_bf16_f32 v2, v2, v3
	v_cvt_pk_bf16_f32 v3, v4, v5
	v_cvt_pk_bf16_f32 v4, v6, v7
	v_cvt_pk_bf16_f32 v5, v8, v9
	v_cvt_pk_bf16_f32 v10, v10, v11
	v_cvt_pk_bf16_f32 v11, v12, v13
	v_cvt_pk_bf16_f32 v12, v14, v15
	v_cvt_pk_bf16_f32 v13, v16, v17
	v_cvt_pk_bf16_f32 v18, v18, v19
	v_cvt_pk_bf16_f32 v19, v20, v21
	v_cvt_pk_bf16_f32 v20, v22, v23
	v_cvt_pk_bf16_f32 v21, v24, v25
	v_cvt_pk_bf16_f32 v26, v26, v27
	v_cvt_pk_bf16_f32 v27, v28, v29
	v_cvt_pk_bf16_f32 v28, v30, v31
	v_cvt_pk_bf16_f32 v29, v32, v33
	v_cvt_pk_bf16_f32 v34, v34, v35
	v_cvt_pk_bf16_f32 v35, v36, v37
	v_cvt_pk_bf16_f32 v36, v38, v39
	v_cvt_pk_bf16_f32 v37, v40, v41
	v_cvt_pk_bf16_f32 v42, v42, v43
	v_cvt_pk_bf16_f32 v43, v44, v45
	v_cvt_pk_bf16_f32 v44, v46, v47
	v_cvt_pk_bf16_f32 v45, v48, v49
	v_cvt_pk_bf16_f32 v50, v50, v51
	v_cvt_pk_bf16_f32 v51, v52, v53
	v_cvt_pk_bf16_f32 v52, v54, v55
	v_cvt_pk_bf16_f32 v53, v56, v57
	v_cvt_pk_bf16_f32 v58, v58, v59
	v_cvt_pk_bf16_f32 v59, v60, v61
	v_cvt_pk_bf16_f32 v60, v62, v63
	v_cvt_pk_bf16_f32 v61, v64, v65
	v_cvt_pk_bf16_f32 v66, v66, v67
	v_cvt_pk_bf16_f32 v67, v68, v69
	v_mov_b32_e32 v68, 0
	v_mov_b32_e32 v69, 0
	ds_bpermute_b32 v172, v1, v170
	v_sub_f32_e32 v173, v146, v169
	v_mul_f32_e32 v173, 0x3fb8aa3b, v173
	v_exp_f32_e32 v173, v173
	s_waitcnt lgkmcnt(0)
	v_add_f32_e32 v170, v170, v172
	ds_bpermute_b32 v172, v114, v170
	ds_read2_b64 v[232:235], v165 offset0:16 offset1:20
	ds_read2_b64 v[236:239], v166 offset0:16 offset1:20
	ds_read2_b64 v[240:243], v167 offset0:16 offset1:20
	ds_read2_b64 v[244:247], v168 offset0:16 offset1:20
	s_waitcnt lgkmcnt(4)
	v_mfma_f32_16x16x32_bf16 v[70:73], v[216:219], v[2:5], 0
	v_mfma_f32_16x16x32_bf16 v[74:77], v[220:223], v[2:5], 0
	v_mfma_f32_16x16x32_bf16 v[78:81], v[224:227], v[2:5], 0
	v_mfma_f32_16x16x32_bf16 v[82:85], v[228:231], v[2:5], 0
	v_add_f32_e32 v170, v170, v172
	v_add_f32_e32 v170, v170, v173
	v_rcp_f32_e32 v147, v170
	s_nop 0
	v_fma_f32 v179, -v170, v147, 1.0
	v_fmac_f32_e32 v147, v179, v147
	ds_read2_b64 v[216:219], v165 offset0:24 offset1:28
	ds_read2_b64 v[220:223], v166 offset0:24 offset1:28
	ds_read2_b64 v[224:227], v167 offset0:24 offset1:28
	ds_read2_b64 v[228:231], v168 offset0:24 offset1:28
	s_waitcnt lgkmcnt(4)
	v_mfma_f32_16x16x32_bf16 v[70:73], v[232:235], v[10:13], v[70:73]
	v_mfma_f32_16x16x32_bf16 v[74:77], v[236:239], v[10:13], v[74:77]
	v_mfma_f32_16x16x32_bf16 v[78:81], v[240:243], v[10:13], v[78:81]
	v_mfma_f32_16x16x32_bf16 v[82:85], v[244:247], v[10:13], v[82:85]
	ds_read2_b64 v[232:235], v165 offset0:32 offset1:36
	ds_read2_b64 v[236:239], v166 offset0:32 offset1:36
	ds_read2_b64 v[240:243], v167 offset0:32 offset1:36
	ds_read2_b64 v[244:247], v168 offset0:32 offset1:36
	s_waitcnt lgkmcnt(4)
	v_mfma_f32_16x16x32_bf16 v[70:73], v[216:219], v[18:21], v[70:73]
	v_mfma_f32_16x16x32_bf16 v[74:77], v[220:223], v[18:21], v[74:77]
	v_mfma_f32_16x16x32_bf16 v[78:81], v[224:227], v[18:21], v[78:81]
	v_mfma_f32_16x16x32_bf16 v[82:85], v[228:231], v[18:21], v[82:85]
	ds_read2_b64 v[216:219], v165 offset0:40 offset1:44
	ds_read2_b64 v[220:223], v166 offset0:40 offset1:44
	ds_read2_b64 v[224:227], v167 offset0:40 offset1:44
	ds_read2_b64 v[228:231], v168 offset0:40 offset1:44
	s_waitcnt lgkmcnt(4)
	v_mfma_f32_16x16x32_bf16 v[70:73], v[232:235], v[26:29], v[70:73]
	v_mfma_f32_16x16x32_bf16 v[74:77], v[236:239], v[26:29], v[74:77]
	v_mfma_f32_16x16x32_bf16 v[78:81], v[240:243], v[26:29], v[78:81]
	v_mfma_f32_16x16x32_bf16 v[82:85], v[244:247], v[26:29], v[82:85]
	ds_read2_b64 v[232:235], v165 offset0:48 offset1:52
	ds_read2_b64 v[236:239], v166 offset0:48 offset1:52
	ds_read2_b64 v[240:243], v167 offset0:48 offset1:52
	ds_read2_b64 v[244:247], v168 offset0:48 offset1:52
	s_waitcnt lgkmcnt(4)
	v_mfma_f32_16x16x32_bf16 v[70:73], v[216:219], v[34:37], v[70:73]
	v_mfma_f32_16x16x32_bf16 v[74:77], v[220:223], v[34:37], v[74:77]
	v_mfma_f32_16x16x32_bf16 v[78:81], v[224:227], v[34:37], v[78:81]
	v_mfma_f32_16x16x32_bf16 v[82:85], v[228:231], v[34:37], v[82:85]
	ds_read2_b64 v[216:219], v165 offset0:56 offset1:60
	ds_read2_b64 v[220:223], v166 offset0:56 offset1:60
	ds_read2_b64 v[224:227], v167 offset0:56 offset1:60
	ds_read2_b64 v[228:231], v168 offset0:56 offset1:60
	s_waitcnt lgkmcnt(4)
	v_mfma_f32_16x16x32_bf16 v[70:73], v[232:235], v[42:45], v[70:73]
	v_mfma_f32_16x16x32_bf16 v[74:77], v[236:239], v[42:45], v[74:77]
	v_mfma_f32_16x16x32_bf16 v[78:81], v[240:243], v[42:45], v[78:81]
	v_mfma_f32_16x16x32_bf16 v[82:85], v[244:247], v[42:45], v[82:85]
	ds_read2_b64 v[232:235], v165 offset0:64 offset1:68
	ds_read2_b64 v[236:239], v166 offset0:64 offset1:68
	ds_read2_b64 v[240:243], v167 offset0:64 offset1:68
	ds_read2_b64 v[244:247], v168 offset0:64 offset1:68
	s_waitcnt lgkmcnt(4)
	v_mfma_f32_16x16x32_bf16 v[70:73], v[216:219], v[50:53], v[70:73]
	v_mfma_f32_16x16x32_bf16 v[74:77], v[220:223], v[50:53], v[74:77]
	v_mfma_f32_16x16x32_bf16 v[78:81], v[224:227], v[50:53], v[78:81]
	v_mfma_f32_16x16x32_bf16 v[82:85], v[228:231], v[50:53], v[82:85]
	ds_read2_b64 v[216:219], v165 offset0:72 offset1:72
	ds_read2_b64 v[220:223], v166 offset0:72 offset1:72
	ds_read2_b64 v[224:227], v167 offset0:72 offset1:72
	ds_read2_b64 v[228:231], v168 offset0:72 offset1:72
	s_waitcnt lgkmcnt(4)
; __device__ void att_phase(int wv, const Params& p, unsigned char* lds) {
;     ...
;         for (int rb = 0; rb < 4; ++rb) {
;             const int qrow = 64 * (w & 1) + 16 * rb + lr;
;             const size_t tokq = (size_t)B * 128 + qrow;
;             bf16x8 qf[2];
; #pragma unroll
;             for (int kk = 0; kk < 2; ++kk) qf[kk] = *(const bf16x8*)(qkv + tokq * 1536 + 64 * h + 32 * kk + 8 * lq);
;             f32x4 sc[24];
; #pragma unroll
;             for (int cb = 0; cb < 24; ++cb) { f32x4 a = {0, 0, 0, 0};
; #pragma unroll
;                 for (int kk = 0; kk < 2; ++kk) { const bf16x8 kf = *(const bf16x8*)(KL + (16 * cb + lr) * KP + 32 * kk + 8 * lq); a = mfma16(kf, qf[kk], a); }
;                 sc[cb] = a; }
;             float mx = sink;
; #pragma unroll
;             for (int cb = 0; cb < 24; ++cb) { const int kb = B - 1 + (cb >> 3); const bool bval = (kb >= sb && kb < se);
; #pragma unroll
;                 for (int j = 0; j < 4; ++j) { const int krel = 16 * cb + 4 * lq + j - 128;
;                     int dist = qrow - krel; dist = dist < 0 ? -dist : dist;
;                     const float v = (bval && dist <= 128) ? sc[cb][j] * 0.125f - slope * (float)dist : -1e30f;
;                     sc[cb][j] = v; mx = fmaxf(mx, v); } }
;     ...
;             for (int ks = 0; ks < 12; ++ks) {
;                 union { bf16x8 v; unsigned u[4]; } pf;
;                 pf.u[0] = cvt_pk_bf16_asm(sc[2 * ks][0], sc[2 * ks][1]); pf.u[1] = cvt_pk_bf16_asm(sc[2 * ks][2], sc[2 * ks][3]);
;                 pf.u[2] = cvt_pk_bf16_asm(sc[2 * ks + 1][0], sc[2 * ks + 1][1]); pf.u[3] = cvt_pk_bf16_asm(sc[2 * ks + 1][2], sc[2 * ks + 1][3]);
; #pragma unroll
;                 for (int db = 0; db < 4; ++db) {
;                     union { bf16x8 v; u32x2 h2[2]; } vf;
;                     const bf16_t* vp = VTL + (16 * db + lr) * VP + 32 * ks + 4 * lq;
;                     vf.h2[0] = *(const u32x2*)vp; vf.h2[1] = *(const u32x2*)(vp + 16);
;                     oa[db] = mfma16(vf.v, pf.v, oa[db]); } }
; #pragma unroll
;             for (int db = 0; db < 4; ++db) { const f32x4 o = oa[db] * inv; u32x2 wv; wv.x = cvt_pk_bf16_asm(o[0], o[1]); wv.y = cvt_pk_bf16_asm(o[2], o[3]);
;                 *(u32x2*)(qkv + tokq * 1536 + 64 * h + 16 * db + 4 * lq) = wv; }
	v_mfma_f32_16x16x32_bf16 v[70:73], v[232:235], v[58:61], v[70:73]
	v_mfma_f32_16x16x32_bf16 v[74:77], v[236:239], v[58:61], v[74:77]
	v_mfma_f32_16x16x32_bf16 v[78:81], v[240:243], v[58:61], v[78:81]
	v_mfma_f32_16x16x32_bf16 v[82:85], v[244:247], v[58:61], v[82:85]
	s_waitcnt lgkmcnt(0)
	v_mfma_f32_16x16x32_bf16 v[70:73], v[216:219], v[66:69], v[70:73]
	v_mfma_f32_16x16x32_bf16 v[74:77], v[220:223], v[66:69], v[74:77]
	v_mfma_f32_16x16x32_bf16 v[78:81], v[224:227], v[66:69], v[78:81]
	v_mfma_f32_16x16x32_bf16 v[82:85], v[228:231], v[66:69], v[82:85]
	s_nop 7
	s_nop 1
	v_mul_f32_e32 v70, v70, v147
	v_mul_f32_e32 v71, v71, v147
	v_mul_f32_e32 v72, v72, v147
	v_mul_f32_e32 v73, v73, v147
	v_mul_f32_e32 v74, v74, v147
	v_mul_f32_e32 v75, v75, v147
	v_mul_f32_e32 v76, v76, v147
	v_mul_f32_e32 v77, v77, v147
	v_mul_f32_e32 v78, v78, v147
	v_mul_f32_e32 v79, v79, v147
	v_mul_f32_e32 v80, v80, v147
	v_mul_f32_e32 v81, v81, v147
	v_mul_f32_e32 v82, v82, v147
	v_mul_f32_e32 v83, v83, v147
	v_mul_f32_e32 v84, v84, v147
	v_mul_f32_e32 v85, v85, v147
	v_cvt_pk_bf16_f32 v70, v70, v71
	v_cvt_pk_bf16_f32 v71, v72, v73
	v_cvt_pk_bf16_f32 v74, v74, v75
	v_cvt_pk_bf16_f32 v75, v76, v77
	v_cvt_pk_bf16_f32 v78, v78, v79
	v_cvt_pk_bf16_f32 v79, v80, v81
	v_cvt_pk_bf16_f32 v82, v82, v83
	v_cvt_pk_bf16_f32 v83, v84, v85
	global_store_dwordx2 v[248:249], v[70:71], off offset:-64
	global_store_dwordx2 v[248:249], v[74:75], off offset:-32
	global_store_dwordx2 v[248:249], v[78:79], off
	global_store_dwordx2 v[248:249], v[82:83], off offset:32
	v_lshl_add_u64 v[248:249], v[248:249], 0, s[48:49]
	v_sub_f32_e32 v86, v94, v176
	v_sub_f32_e32 v87, v95, v176
	v_sub_f32_e32 v88, v96, v176
	v_sub_f32_e32 v89, v97, v176
	v_cmp_ge_i32_e32 vcc, 0, v108
	s_nop 1
	v_cndmask_b32_e32 v212, v252, v86, vcc
	v_cmp_ge_i32_e32 vcc, 0, v110
	s_nop 1
	v_cndmask_b32_e32 v213, v252, v87, vcc
	v_cmp_ge_i32_e32 vcc, 0, v111
	s_nop 1
	v_cndmask_b32_e32 v214, v252, v88, vcc
	v_cmp_ge_i32_e32 vcc, 0, v177
	s_nop 1
	v_cndmask_b32_e32 v215, v252, v89, vcc
	ds_read_b128 v[148:151], v164 offset:6912
	ds_read_b128 v[152:155], v164 offset:6976
	ds_read_b128 v[156:159], v164 offset:9216
	ds_read_b128 v[160:163], v164 offset:9280
	v_add_f32_e32 v90, v86, v174
	v_add_f32_e32 v91, v87, v174
	v_add_f32_e32 v92, v88, v174
	v_add_f32_e32 v93, v89, v174
	s_waitcnt lgkmcnt(2)
	v_mfma_f32_16x16x32_bf16 v[2:5], v[148:151], v[204:207], v[212:215]
	v_mfma_f32_16x16x32_bf16 v[2:5], v[152:155], v[208:211], v[2:5]
	ds_read_b128 v[148:151], v164 offset:11520
	ds_read_b128 v[152:155], v164 offset:11584
	v_add_f32_e32 v86, v90, v174
	v_add_f32_e32 v87, v91, v174
	v_add_f32_e32 v88, v92, v174
	v_add_f32_e32 v89, v93, v174
	s_waitcnt lgkmcnt(2)
	v_mfma_f32_16x16x32_bf16 v[6:9], v[156:159], v[204:207], v[90:93]
	v_mfma_f32_16x16x32_bf16 v[6:9], v[160:163], v[208:211], v[6:9]
	ds_read_b128 v[156:159], v164 offset:13824
	ds_read_b128 v[160:163], v164 offset:13888
	v_add_f32_e32 v90, v86, v174
	v_add_f32_e32 v91, v87, v174
	v_add_f32_e32 v92, v88, v174
	v_add_f32_e32 v93, v89, v174
	s_waitcnt lgkmcnt(2)
	v_mfma_f32_16x16x32_bf16 v[10:13], v[148:151], v[204:207], v[86:89]
	v_mfma_f32_16x16x32_bf16 v[10:13], v[152:155], v[208:211], v[10:13]
	ds_read_b128 v[148:151], v164 offset:16128
	ds_read_b128 v[152:155], v164 offset:16192
	v_add_f32_e32 v86, v90, v174
	v_add_f32_e32 v87, v91, v174
	v_add_f32_e32 v88, v92, v174
	v_add_f32_e32 v89, v93, v174
	s_waitcnt lgkmcnt(2)
	v_mfma_f32_16x16x32_bf16 v[14:17], v[156:159], v[204:207], v[90:93]
	v_mfma_f32_16x16x32_bf16 v[14:17], v[160:163], v[208:211], v[14:17]
	ds_read_b128 v[156:159], v164 offset:18432
	ds_read_b128 v[160:163], v164 offset:18496
	v_add_f32_e32 v90, v86, v174
	v_add_f32_e32 v91, v87, v174
	v_add_f32_e32 v92, v88, v174
	v_add_f32_e32 v93, v89, v174
	s_waitcnt lgkmcnt(2)
	v_mfma_f32_16x16x32_bf16 v[18:21], v[148:151], v[204:207], v[86:89]
	v_mfma_f32_16x16x32_bf16 v[18:21], v[152:155], v[208:211], v[18:21]
	ds_read_b128 v[148:151], v164 offset:20736
	ds_read_b128 v[152:155], v164 offset:20800
	v_add_f32_e32 v86, v90, v174
	v_add_f32_e32 v87, v91, v174
	v_add_f32_e32 v88, v92, v174
	v_add_f32_e32 v89, v93, v174
	s_waitcnt lgkmcnt(2)
	v_mfma_f32_16x16x32_bf16 v[22:25], v[156:159], v[204:207], v[90:93]
	v_mfma_f32_16x16x32_bf16 v[22:25], v[160:163], v[208:211], v[22:25]
	ds_read_b128 v[156:159], v164 offset:23040
	ds_read_b128 v[160:163], v164 offset:23104
	v_add_f32_e32 v90, v86, v174
	v_add_f32_e32 v91, v87, v174
	v_add_f32_e32 v92, v88, v174
	v_add_f32_e32 v93, v89, v174
	s_waitcnt lgkmcnt(2)
	v_mfma_f32_16x16x32_bf16 v[26:29], v[148:151], v[204:207], v[86:89]
	v_mfma_f32_16x16x32_bf16 v[26:29], v[152:155], v[208:211], v[26:29]
	ds_read_b128 v[148:151], v164 offset:25344
	ds_read_b128 v[152:155], v164 offset:25408
	s_waitcnt lgkmcnt(2)
	v_mfma_f32_16x16x32_bf16 v[30:33], v[156:159], v[204:207], v[90:93]
	v_mfma_f32_16x16x32_bf16 v[30:33], v[160:163], v[208:211], v[30:33]
	ds_read_b128 v[156:159], v164 offset:27648
	ds_read_b128 v[160:163], v164 offset:27712
	v_sub_f32_e64 v86, -v94, v174
	v_sub_f32_e64 v87, -v95, v174
	v_sub_f32_e64 v88, -v96, v174
	v_sub_f32_e64 v89, -v97, v174
	s_waitcnt lgkmcnt(2)
	v_mfma_f32_16x16x32_bf16 v[34:37], v[148:151], v[204:207], v[98:101]
	v_mfma_f32_16x16x32_bf16 v[34:37], v[152:155], v[208:211], v[34:37]
	ds_read_b128 v[148:151], v164 offset:29952
	ds_read_b128 v[152:155], v164 offset:30016
	v_sub_f32_e32 v90, v86, v174
	v_sub_f32_e32 v91, v87, v174
	v_sub_f32_e32 v92, v88, v174
	v_sub_f32_e32 v93, v89, v174
	s_waitcnt lgkmcnt(2)
; __device__ __forceinline__ f32x4 mfma16(bf16x8 a, bf16x8 b, f32x4 c) { return __builtin_amdgcn_mfma_f32_16x16x32_bf16(a, b, c, 0, 0, 0); }
; __device__ void att_phase(int wv, const Params& p, unsigned char* lds) {
;     ...
;             for (int cb = 0; cb < 24; ++cb) { f32x4 a = {0, 0, 0, 0};
; #pragma unroll
;                 for (int kk = 0; kk < 2; ++kk) { const bf16x8 kf = *(const bf16x8*)(KL + (16 * cb + lr) * KP + 32 * kk + 8 * lq); a = mfma16(kf, qf[kk], a); }
;                 sc[cb] = a; }
;             float mx = sink;
; #pragma unroll
;             for (int cb = 0; cb < 24; ++cb) { const int kb = B - 1 + (cb >> 3); const bool bval = (kb >= sb && kb < se);
; #pragma unroll
;                 for (int j = 0; j < 4; ++j) { const int krel = 16 * cb + 4 * lq + j - 128;
;                     int dist = qrow - krel; dist = dist < 0 ? -dist : dist;
;                     const float v = (bval && dist <= 128) ? sc[cb][j] * 0.125f - slope * (float)dist : -1e30f;
;                     sc[cb][j] = v; mx = fmaxf(mx, v); } }
;             mx = fmaxf(mx, __shfl_xor(mx, 16)); mx = fmaxf(mx, __shfl_xor(mx, 32));
	v_mfma_f32_16x16x32_bf16 v[38:41], v[156:159], v[204:207], v[86:89]
	v_mfma_f32_16x16x32_bf16 v[38:41], v[160:163], v[208:211], v[38:41]
	ds_read_b128 v[156:159], v164 offset:32256
	ds_read_b128 v[160:163], v164 offset:32320
	v_sub_f32_e32 v86, v90, v174
	v_sub_f32_e32 v87, v91, v174
	v_sub_f32_e32 v88, v92, v174
	v_sub_f32_e32 v89, v93, v174
	s_waitcnt lgkmcnt(2)
	v_mfma_f32_16x16x32_bf16 v[42:45], v[148:151], v[204:207], v[90:93]
	v_mfma_f32_16x16x32_bf16 v[42:45], v[152:155], v[208:211], v[42:45]
	ds_read_b128 v[148:151], v164 offset:34560
	ds_read_b128 v[152:155], v164 offset:34624
	v_sub_f32_e32 v90, v86, v174
	v_sub_f32_e32 v91, v87, v174
	v_sub_f32_e32 v92, v88, v174
	v_sub_f32_e32 v93, v89, v174
	s_waitcnt lgkmcnt(2)
	v_mfma_f32_16x16x32_bf16 v[46:49], v[156:159], v[204:207], v[86:89]
	v_mfma_f32_16x16x32_bf16 v[46:49], v[160:163], v[208:211], v[46:49]
	ds_read_b128 v[156:159], v164 offset:36864
	ds_read_b128 v[160:163], v164 offset:36928
	v_sub_f32_e32 v86, v90, v174
	v_sub_f32_e32 v87, v91, v174
	v_sub_f32_e32 v88, v92, v174
	v_sub_f32_e32 v89, v93, v174
	s_waitcnt lgkmcnt(2)
	v_mfma_f32_16x16x32_bf16 v[50:53], v[148:151], v[204:207], v[90:93]
	v_mfma_f32_16x16x32_bf16 v[50:53], v[152:155], v[208:211], v[50:53]
	ds_read_b128 v[148:151], v164 offset:39168
	ds_read_b128 v[152:155], v164 offset:39232
	v_sub_f32_e32 v90, v86, v174
	v_sub_f32_e32 v91, v87, v174
	v_sub_f32_e32 v92, v88, v174
	v_sub_f32_e32 v93, v89, v174
	s_waitcnt lgkmcnt(2)
	v_mfma_f32_16x16x32_bf16 v[54:57], v[156:159], v[204:207], v[86:89]
	v_mfma_f32_16x16x32_bf16 v[54:57], v[160:163], v[208:211], v[54:57]
	ds_read_b128 v[156:159], v164 offset:41472
	ds_read_b128 v[160:163], v164 offset:41536
	v_sub_f32_e32 v86, v90, v174
	v_sub_f32_e32 v87, v91, v174
	v_sub_f32_e32 v88, v92, v174
	v_sub_f32_e32 v89, v93, v174
	s_waitcnt lgkmcnt(2)
	v_mfma_f32_16x16x32_bf16 v[58:61], v[148:151], v[204:207], v[90:93]
	v_mfma_f32_16x16x32_bf16 v[58:61], v[152:155], v[208:211], v[58:61]
	ds_read_b128 v[148:151], v164 offset:43776
	ds_read_b128 v[152:155], v164 offset:43840
	v_sub_f32_e32 v90, v86, v174
	v_sub_f32_e32 v91, v87, v174
	v_sub_f32_e32 v92, v88, v174
	v_sub_f32_e32 v93, v89, v174
	v_cmp_le_i32_e32 vcc, 0, v108
	s_nop 1
	v_cndmask_b32_e32 v212, v252, v90, vcc
	v_cmp_le_i32_e32 vcc, 0, v110
	s_nop 1
	v_cndmask_b32_e32 v213, v252, v91, vcc
	v_cmp_le_i32_e32 vcc, 0, v111
	s_nop 1
	v_cndmask_b32_e32 v214, v252, v92, vcc
	v_cmp_le_i32_e32 vcc, 0, v177
	s_nop 1
	v_cndmask_b32_e32 v215, v252, v93, vcc
	s_waitcnt lgkmcnt(2)
	v_mfma_f32_16x16x32_bf16 v[62:65], v[156:159], v[204:207], v[86:89]
	v_mfma_f32_16x16x32_bf16 v[62:65], v[160:163], v[208:211], v[62:65]
	s_waitcnt lgkmcnt(0)
	v_mfma_f32_16x16x32_bf16 v[66:69], v[148:151], v[204:207], v[212:215]
	v_mfma_f32_16x16x32_bf16 v[66:69], v[152:155], v[208:211], v[66:69]
	ds_read2_b64 v[216:219], v165 offset0:12 offset1:16
	ds_read2_b64 v[220:223], v166 offset0:12 offset1:16
	ds_read2_b64 v[224:227], v167 offset0:12 offset1:16
	ds_read2_b64 v[228:231], v168 offset0:12 offset1:16
	v_max3_f32 v169, v2, v3, v4
	v_max3_f32 v172, v5, v6, v7
	v_max3_f32 v169, v8, v9, v169
	v_max3_f32 v172, v10, v11, v172
	v_max3_f32 v169, v12, v13, v169
	v_max3_f32 v172, v14, v15, v172
	v_max3_f32 v169, v16, v17, v169
	v_max3_f32 v172, v18, v19, v172
	v_max3_f32 v169, v20, v21, v169
	v_max3_f32 v172, v22, v23, v172
	v_max3_f32 v169, v24, v25, v169
	v_max3_f32 v172, v26, v27, v172
	v_max3_f32 v169, v28, v29, v169
	v_max3_f32 v172, v30, v31, v172
	v_max3_f32 v169, v32, v33, v169
	v_max3_f32 v172, v34, v35, v172
	v_max3_f32 v169, v36, v37, v169
	v_max3_f32 v172, v38, v39, v172
	v_max3_f32 v169, v40, v41, v169
	v_max3_f32 v172, v42, v43, v172
	v_max3_f32 v169, v44, v45, v169
	v_max3_f32 v172, v46, v47, v172
	v_max3_f32 v169, v48, v49, v169
	v_max3_f32 v172, v50, v51, v172
	v_max3_f32 v169, v52, v53, v169
	v_max3_f32 v172, v54, v55, v172
	v_max3_f32 v169, v56, v57, v169
	v_max3_f32 v172, v58, v59, v172
	v_max3_f32 v169, v60, v61, v169
	v_max3_f32 v172, v62, v63, v172
	v_max3_f32 v169, v64, v65, v169
	v_max3_f32 v172, v66, v67, v172
	v_max3_f32 v169, v68, v69, v169
	v_max_f32_e32 v169, v169, v172
	v_mul_f32_e32 v169, 0x3e000000, v169
	v_max_f32_e32 v169, v169, v146
	ds_bpermute_b32 v172, v1, v169
	s_waitcnt lgkmcnt(0)
	v_max_f32_e32 v169, v169, v172
	ds_bpermute_b32 v172, v114, v169
	s_waitcnt lgkmcnt(0)
; __device__ void att_phase(int wv, const Params& p, unsigned char* lds) {
;     ...
;             mx = fmaxf(mx, __shfl_xor(mx, 16)); mx = fmaxf(mx, __shfl_xor(mx, 32));
;             float sum = 0.f;
; #pragma unroll
;             for (int cb = 0; cb < 24; ++cb)
; #pragma unroll
;                 for (int j = 0; j < 4; ++j) { const float e = __expf(sc[cb][j] - mx); sc[cb][j] = e; sum += e; }
	v_max_f32_e32 v169, v169, v172
	v_mul_f32_e32 v175, 0xbfb8aa3b, v169
	v_mov_b32_e32 v170, 0
	v_mov_b32_e32 v171, 0
	v_fma_f32 v2, v2, s46, v175
	v_fma_f32 v3, v3, s46, v175
	v_fma_f32 v4, v4, s46, v175
	v_fma_f32 v5, v5, s46, v175
	v_exp_f32_e32 v2, v2
	v_exp_f32_e32 v3, v3
	v_exp_f32_e32 v4, v4
	v_exp_f32_e32 v5, v5
	v_fma_f32 v6, v6, s46, v175
	v_fma_f32 v7, v7, s46, v175
	v_fma_f32 v8, v8, s46, v175
	v_fma_f32 v9, v9, s46, v175
	v_exp_f32_e32 v6, v6
	v_exp_f32_e32 v7, v7
	v_exp_f32_e32 v8, v8
	v_exp_f32_e32 v9, v9
	v_add_f32_e32 v171, v171, v2
	v_add_f32_e32 v170, v170, v3
	v_add_f32_e32 v171, v171, v4
	v_add_f32_e32 v170, v170, v5
	v_fma_f32 v10, v10, s46, v175
	v_fma_f32 v11, v11, s46, v175
	v_fma_f32 v12, v12, s46, v175
	v_fma_f32 v13, v13, s46, v175
	v_exp_f32_e32 v10, v10
	v_exp_f32_e32 v11, v11
	v_exp_f32_e32 v12, v12
	v_exp_f32_e32 v13, v13
	v_add_f32_e32 v171, v171, v6
	v_add_f32_e32 v170, v170, v7
	v_add_f32_e32 v171, v171, v8
	v_add_f32_e32 v170, v170, v9
	v_fma_f32 v14, v14, s46, v175
	v_fma_f32 v15, v15, s46, v175
	v_fma_f32 v16, v16, s46, v175
	v_fma_f32 v17, v17, s46, v175
	v_exp_f32_e32 v14, v14
	v_exp_f32_e32 v15, v15
	v_exp_f32_e32 v16, v16
	v_exp_f32_e32 v17, v17
	v_add_f32_e32 v171, v171, v10
	v_add_f32_e32 v170, v170, v11
	v_add_f32_e32 v171, v171, v12
	v_add_f32_e32 v170, v170, v13
	v_fma_f32 v18, v18, s46, v175
	v_fma_f32 v19, v19, s46, v175
	v_fma_f32 v20, v20, s46, v175
	v_fma_f32 v21, v21, s46, v175
	v_exp_f32_e32 v18, v18
	v_exp_f32_e32 v19, v19
	v_exp_f32_e32 v20, v20
	v_exp_f32_e32 v21, v21
	v_add_f32_e32 v171, v171, v14
	v_add_f32_e32 v170, v170, v15
	v_add_f32_e32 v171, v171, v16
	v_add_f32_e32 v170, v170, v17
	v_fma_f32 v22, v22, s46, v175
	v_fma_f32 v23, v23, s46, v175
	v_fma_f32 v24, v24, s46, v175
	v_fma_f32 v25, v25, s46, v175
	v_exp_f32_e32 v22, v22
	v_exp_f32_e32 v23, v23
	v_exp_f32_e32 v24, v24
	v_exp_f32_e32 v25, v25
	v_add_f32_e32 v171, v171, v18
	v_add_f32_e32 v170, v170, v19
	v_add_f32_e32 v171, v171, v20
	v_add_f32_e32 v170, v170, v21
	v_fma_f32 v26, v26, s46, v175
	v_fma_f32 v27, v27, s46, v175
	v_fma_f32 v28, v28, s46, v175
	v_fma_f32 v29, v29, s46, v175
	v_exp_f32_e32 v26, v26
	v_exp_f32_e32 v27, v27
	v_exp_f32_e32 v28, v28
	v_exp_f32_e32 v29, v29
	v_add_f32_e32 v171, v171, v22
	v_add_f32_e32 v170, v170, v23
	v_add_f32_e32 v171, v171, v24
	v_add_f32_e32 v170, v170, v25
	v_fma_f32 v30, v30, s46, v175
	v_fma_f32 v31, v31, s46, v175
	v_fma_f32 v32, v32, s46, v175
	v_fma_f32 v33, v33, s46, v175
	v_exp_f32_e32 v30, v30
	v_exp_f32_e32 v31, v31
	v_exp_f32_e32 v32, v32
	v_exp_f32_e32 v33, v33
	v_add_f32_e32 v171, v171, v26
	v_add_f32_e32 v170, v170, v27
	v_add_f32_e32 v171, v171, v28
	v_add_f32_e32 v170, v170, v29
	v_fma_f32 v34, v34, s46, v175
	v_fma_f32 v35, v35, s46, v175
	v_fma_f32 v36, v36, s46, v175
	v_fma_f32 v37, v37, s46, v175
	v_exp_f32_e32 v34, v34
	v_exp_f32_e32 v35, v35
	v_exp_f32_e32 v36, v36
	v_exp_f32_e32 v37, v37
	v_add_f32_e32 v171, v171, v30
	v_add_f32_e32 v170, v170, v31
	v_add_f32_e32 v171, v171, v32
	v_add_f32_e32 v170, v170, v33
	v_fma_f32 v38, v38, s46, v175
	v_fma_f32 v39, v39, s46, v175
	v_fma_f32 v40, v40, s46, v175
	v_fma_f32 v41, v41, s46, v175
	v_exp_f32_e32 v38, v38
	v_exp_f32_e32 v39, v39
	v_exp_f32_e32 v40, v40
	v_exp_f32_e32 v41, v41
	v_add_f32_e32 v171, v171, v34
	v_add_f32_e32 v170, v170, v35
	v_add_f32_e32 v171, v171, v36
	v_add_f32_e32 v170, v170, v37
	v_fma_f32 v42, v42, s46, v175
	v_fma_f32 v43, v43, s46, v175
	v_fma_f32 v44, v44, s46, v175
	v_fma_f32 v45, v45, s46, v175
	v_exp_f32_e32 v42, v42
	v_exp_f32_e32 v43, v43
	v_exp_f32_e32 v44, v44
	v_exp_f32_e32 v45, v45
	v_add_f32_e32 v171, v171, v38
	v_add_f32_e32 v170, v170, v39
	v_add_f32_e32 v171, v171, v40
	v_add_f32_e32 v170, v170, v41
	v_fma_f32 v46, v46, s46, v175
	v_fma_f32 v47, v47, s46, v175
	v_fma_f32 v48, v48, s46, v175
	v_fma_f32 v49, v49, s46, v175
	v_exp_f32_e32 v46, v46
	v_exp_f32_e32 v47, v47
	v_exp_f32_e32 v48, v48
	v_exp_f32_e32 v49, v49
	v_add_f32_e32 v171, v171, v42
	v_add_f32_e32 v170, v170, v43
	v_add_f32_e32 v171, v171, v44
	v_add_f32_e32 v170, v170, v45
	v_fma_f32 v50, v50, s46, v175
	v_fma_f32 v51, v51, s46, v175
	v_fma_f32 v52, v52, s46, v175
	v_fma_f32 v53, v53, s46, v175
	v_exp_f32_e32 v50, v50
	v_exp_f32_e32 v51, v51
	v_exp_f32_e32 v52, v52
	v_exp_f32_e32 v53, v53
	v_add_f32_e32 v171, v171, v46
	v_add_f32_e32 v170, v170, v47
	v_add_f32_e32 v171, v171, v48
	v_add_f32_e32 v170, v170, v49
	v_fma_f32 v54, v54, s46, v175
	v_fma_f32 v55, v55, s46, v175
	v_fma_f32 v56, v56, s46, v175
	v_fma_f32 v57, v57, s46, v175
	v_exp_f32_e32 v54, v54
	v_exp_f32_e32 v55, v55
	v_exp_f32_e32 v56, v56
	v_exp_f32_e32 v57, v57
	v_add_f32_e32 v171, v171, v50
	v_add_f32_e32 v170, v170, v51
	v_add_f32_e32 v171, v171, v52
	v_add_f32_e32 v170, v170, v53
	v_fma_f32 v58, v58, s46, v175
	v_fma_f32 v59, v59, s46, v175
	v_fma_f32 v60, v60, s46, v175
	v_fma_f32 v61, v61, s46, v175
	v_exp_f32_e32 v58, v58
	v_exp_f32_e32 v59, v59
	v_exp_f32_e32 v60, v60
	v_exp_f32_e32 v61, v61
	v_add_f32_e32 v171, v171, v54
	v_add_f32_e32 v170, v170, v55
	v_add_f32_e32 v171, v171, v56
	v_add_f32_e32 v170, v170, v57
	v_fma_f32 v62, v62, s46, v175
	v_fma_f32 v63, v63, s46, v175
	v_fma_f32 v64, v64, s46, v175
	v_fma_f32 v65, v65, s46, v175
	v_exp_f32_e32 v62, v62
	v_exp_f32_e32 v63, v63
	v_exp_f32_e32 v64, v64
	v_exp_f32_e32 v65, v65
	v_add_f32_e32 v171, v171, v58
	v_add_f32_e32 v170, v170, v59
	v_add_f32_e32 v171, v171, v60
	v_add_f32_e32 v170, v170, v61
	v_fma_f32 v66, v66, s46, v175
	v_fma_f32 v67, v67, s46, v175
	v_fma_f32 v68, v68, s46, v175
	v_fma_f32 v69, v69, s46, v175
	v_exp_f32_e32 v66, v66
	v_exp_f32_e32 v67, v67
; __device__ __forceinline__ unsigned cvt_pk_bf16_asm(float lo, float hi) { unsigned r; asm volatile("v_cvt_pk_bf16_f32 %0, %1, %2" : "=v"(r) : "v"(lo), "v"(hi)); return r; }
; __device__ __forceinline__ f32x4 mfma16(bf16x8 a, bf16x8 b, f32x4 c) { return __builtin_amdgcn_mfma_f32_16x16x32_bf16(a, b, c, 0, 0, 0); }
; __device__ void att_phase(int wv, const Params& p, unsigned char* lds) {
;     ...
;                 for (int j = 0; j < 4; ++j) { const float e = __expf(sc[cb][j] - mx); sc[cb][j] = e; sum += e; }
;             sum += __shfl_xor(sum, 16); sum += __shfl_xor(sum, 32);
;             sum += __expf(sink - mx);
;             const float inv = 1.0f / sum;
;             f32x4 oa[4];
; #pragma unroll
;             for (int db = 0; db < 4; ++db) oa[db] = (f32x4){0, 0, 0, 0};
; #pragma unroll
;             for (int ks = 0; ks < 12; ++ks) {
;                 union { bf16x8 v; unsigned u[4]; } pf;
;                 pf.u[0] = cvt_pk_bf16_asm(sc[2 * ks][0], sc[2 * ks][1]); pf.u[1] = cvt_pk_bf16_asm(sc[2 * ks][2], sc[2 * ks][3]);
;                 pf.u[2] = cvt_pk_bf16_asm(sc[2 * ks + 1][0], sc[2 * ks + 1][1]); pf.u[3] = cvt_pk_bf16_asm(sc[2 * ks + 1][2], sc[2 * ks + 1][3]);
; #pragma unroll
;                 for (int db = 0; db < 4; ++db) {
;                     union { bf16x8 v; u32x2 h2[2]; } vf;
;                     const bf16_t* vp = VTL + (16 * db + lr) * VP + 32 * ks + 4 * lq;
;                     vf.h2[0] = *(const u32x2*)vp; vf.h2[1] = *(const u32x2*)(vp + 16);
;                     oa[db] = mfma16(vf.v, pf.v, oa[db]); } }
	v_exp_f32_e32 v68, v68
	v_exp_f32_e32 v69, v69
	v_add_f32_e32 v171, v171, v62
	v_add_f32_e32 v170, v170, v63
	v_add_f32_e32 v171, v171, v64
	v_add_f32_e32 v170, v170, v65
	v_add_f32_e32 v171, v171, v66
	v_add_f32_e32 v170, v170, v67
	v_add_f32_e32 v171, v171, v68
	v_add_f32_e32 v170, v170, v69
	v_add_f32_e32 v170, v170, v171
	v_cvt_pk_bf16_f32 v2, v2, v3
	v_cvt_pk_bf16_f32 v3, v4, v5
	v_cvt_pk_bf16_f32 v4, v6, v7
	v_cvt_pk_bf16_f32 v5, v8, v9
	v_cvt_pk_bf16_f32 v10, v10, v11
	v_cvt_pk_bf16_f32 v11, v12, v13
	v_cvt_pk_bf16_f32 v12, v14, v15
	v_cvt_pk_bf16_f32 v13, v16, v17
	v_cvt_pk_bf16_f32 v18, v18, v19
	v_cvt_pk_bf16_f32 v19, v20, v21
	v_cvt_pk_bf16_f32 v20, v22, v23
	v_cvt_pk_bf16_f32 v21, v24, v25
	v_cvt_pk_bf16_f32 v26, v26, v27
	v_cvt_pk_bf16_f32 v27, v28, v29
	v_cvt_pk_bf16_f32 v28, v30, v31
	v_cvt_pk_bf16_f32 v29, v32, v33
	v_cvt_pk_bf16_f32 v34, v34, v35
	v_cvt_pk_bf16_f32 v35, v36, v37
	v_cvt_pk_bf16_f32 v36, v38, v39
	v_cvt_pk_bf16_f32 v37, v40, v41
	v_cvt_pk_bf16_f32 v42, v42, v43
	v_cvt_pk_bf16_f32 v43, v44, v45
	v_cvt_pk_bf16_f32 v44, v46, v47
	v_cvt_pk_bf16_f32 v45, v48, v49
	v_cvt_pk_bf16_f32 v50, v50, v51
	v_cvt_pk_bf16_f32 v51, v52, v53
	v_cvt_pk_bf16_f32 v52, v54, v55
	v_cvt_pk_bf16_f32 v53, v56, v57
	v_cvt_pk_bf16_f32 v58, v58, v59
	v_cvt_pk_bf16_f32 v59, v60, v61
	v_cvt_pk_bf16_f32 v60, v62, v63
	v_cvt_pk_bf16_f32 v61, v64, v65
	v_cvt_pk_bf16_f32 v66, v66, v67
	v_cvt_pk_bf16_f32 v67, v68, v69
	v_mov_b32_e32 v68, 0
	v_mov_b32_e32 v69, 0
	ds_bpermute_b32 v172, v1, v170
	v_sub_f32_e32 v173, v146, v169
	v_mul_f32_e32 v173, 0x3fb8aa3b, v173
	v_exp_f32_e32 v173, v173
	s_waitcnt lgkmcnt(0)
	v_add_f32_e32 v170, v170, v172
	ds_bpermute_b32 v172, v114, v170
	ds_read2_b64 v[232:235], v165 offset0:20 offset1:24
	ds_read2_b64 v[236:239], v166 offset0:20 offset1:24
	ds_read2_b64 v[240:243], v167 offset0:20 offset1:24
	ds_read2_b64 v[244:247], v168 offset0:20 offset1:24
	s_waitcnt lgkmcnt(4)
	v_mfma_f32_16x16x32_bf16 v[70:73], v[216:219], v[2:5], 0
	v_mfma_f32_16x16x32_bf16 v[74:77], v[220:223], v[2:5], 0
	v_mfma_f32_16x16x32_bf16 v[78:81], v[224:227], v[2:5], 0
	v_mfma_f32_16x16x32_bf16 v[82:85], v[228:231], v[2:5], 0
	v_add_f32_e32 v170, v170, v172
	v_add_f32_e32 v170, v170, v173
	v_rcp_f32_e32 v147, v170
	s_nop 0
	v_fma_f32 v179, -v170, v147, 1.0
	v_fmac_f32_e32 v147, v179, v147
	ds_read2_b64 v[216:219], v165 offset0:28 offset1:32
	ds_read2_b64 v[220:223], v166 offset0:28 offset1:32
	ds_read2_b64 v[224:227], v167 offset0:28 offset1:32
	ds_read2_b64 v[228:231], v168 offset0:28 offset1:32
	s_waitcnt lgkmcnt(4)
	v_mfma_f32_16x16x32_bf16 v[70:73], v[232:235], v[10:13], v[70:73]
	v_mfma_f32_16x16x32_bf16 v[74:77], v[236:239], v[10:13], v[74:77]
	v_mfma_f32_16x16x32_bf16 v[78:81], v[240:243], v[10:13], v[78:81]
	v_mfma_f32_16x16x32_bf16 v[82:85], v[244:247], v[10:13], v[82:85]
	ds_read2_b64 v[232:235], v165 offset0:36 offset1:40
	ds_read2_b64 v[236:239], v166 offset0:36 offset1:40
	ds_read2_b64 v[240:243], v167 offset0:36 offset1:40
	ds_read2_b64 v[244:247], v168 offset0:36 offset1:40
	s_waitcnt lgkmcnt(4)
	v_mfma_f32_16x16x32_bf16 v[70:73], v[216:219], v[18:21], v[70:73]
	v_mfma_f32_16x16x32_bf16 v[74:77], v[220:223], v[18:21], v[74:77]
	v_mfma_f32_16x16x32_bf16 v[78:81], v[224:227], v[18:21], v[78:81]
	v_mfma_f32_16x16x32_bf16 v[82:85], v[228:231], v[18:21], v[82:85]
	ds_read2_b64 v[216:219], v165 offset0:44 offset1:48
	ds_read2_b64 v[220:223], v166 offset0:44 offset1:48
	ds_read2_b64 v[224:227], v167 offset0:44 offset1:48
	ds_read2_b64 v[228:231], v168 offset0:44 offset1:48
	s_waitcnt lgkmcnt(4)
	v_mfma_f32_16x16x32_bf16 v[70:73], v[232:235], v[26:29], v[70:73]
	v_mfma_f32_16x16x32_bf16 v[74:77], v[236:239], v[26:29], v[74:77]
	v_mfma_f32_16x16x32_bf16 v[78:81], v[240:243], v[26:29], v[78:81]
	v_mfma_f32_16x16x32_bf16 v[82:85], v[244:247], v[26:29], v[82:85]
	ds_read2_b64 v[232:235], v165 offset0:52 offset1:56
	ds_read2_b64 v[236:239], v166 offset0:52 offset1:56
	ds_read2_b64 v[240:243], v167 offset0:52 offset1:56
	ds_read2_b64 v[244:247], v168 offset0:52 offset1:56
	s_waitcnt lgkmcnt(4)
	v_mfma_f32_16x16x32_bf16 v[70:73], v[216:219], v[34:37], v[70:73]
	v_mfma_f32_16x16x32_bf16 v[74:77], v[220:223], v[34:37], v[74:77]
	v_mfma_f32_16x16x32_bf16 v[78:81], v[224:227], v[34:37], v[78:81]
	v_mfma_f32_16x16x32_bf16 v[82:85], v[228:231], v[34:37], v[82:85]
	ds_read2_b64 v[216:219], v165 offset0:60 offset1:64
	ds_read2_b64 v[220:223], v166 offset0:60 offset1:64
	ds_read2_b64 v[224:227], v167 offset0:60 offset1:64
	ds_read2_b64 v[228:231], v168 offset0:60 offset1:64
	s_waitcnt lgkmcnt(4)
	v_mfma_f32_16x16x32_bf16 v[70:73], v[232:235], v[42:45], v[70:73]
	v_mfma_f32_16x16x32_bf16 v[74:77], v[236:239], v[42:45], v[74:77]
	v_mfma_f32_16x16x32_bf16 v[78:81], v[240:243], v[42:45], v[78:81]
	v_mfma_f32_16x16x32_bf16 v[82:85], v[244:247], v[42:45], v[82:85]
	ds_read2_b64 v[232:235], v165 offset0:68 offset1:72
	ds_read2_b64 v[236:239], v166 offset0:68 offset1:72
	ds_read2_b64 v[240:243], v167 offset0:68 offset1:72
	ds_read2_b64 v[244:247], v168 offset0:68 offset1:72
	s_waitcnt lgkmcnt(4)
	v_mfma_f32_16x16x32_bf16 v[70:73], v[216:219], v[50:53], v[70:73]
	v_mfma_f32_16x16x32_bf16 v[74:77], v[220:223], v[50:53], v[74:77]
	v_mfma_f32_16x16x32_bf16 v[78:81], v[224:227], v[50:53], v[78:81]
	v_mfma_f32_16x16x32_bf16 v[82:85], v[228:231], v[50:53], v[82:85]
	ds_read2_b64 v[216:219], v165 offset0:76 offset1:76
	ds_read2_b64 v[220:223], v166 offset0:76 offset1:76
	ds_read2_b64 v[224:227], v167 offset0:76 offset1:76
	ds_read2_b64 v[228:231], v168 offset0:76 offset1:76
	s_waitcnt lgkmcnt(4)
; __device__ __forceinline__ unsigned cvt_pk_bf16_asm(float lo, float hi) { unsigned r; asm volatile("v_cvt_pk_bf16_f32 %0, %1, %2" : "=v"(r) : "v"(lo), "v"(hi)); return r; }
; __device__ __forceinline__ f32x4 mfma16(bf16x8 a, bf16x8 b, f32x4 c) { return __builtin_amdgcn_mfma_f32_16x16x32_bf16(a, b, c, 0, 0, 0); }
; __device__ void att_phase(int wv, const Params& p, unsigned char* lds) {
;     ...
;             const int qrow = 64 * (w & 1) + 16 * rb + lr;
;             const size_t tokq = (size_t)B * 128 + qrow;
;             bf16x8 qf[2];
; #pragma unroll
;             for (int kk = 0; kk < 2; ++kk) qf[kk] = *(const bf16x8*)(qkv + tokq * 1536 + 64 * h + 32 * kk + 8 * lq);
;             f32x4 sc[24];
; #pragma unroll
;             for (int cb = 0; cb < 24; ++cb) { f32x4 a = {0, 0, 0, 0};
; #pragma unroll
;                 for (int kk = 0; kk < 2; ++kk) { const bf16x8 kf = *(const bf16x8*)(KL + (16 * cb + lr) * KP + 32 * kk + 8 * lq); a = mfma16(kf, qf[kk], a); }
;     ...
;                     oa[db] = mfma16(vf.v, pf.v, oa[db]); } }
; #pragma unroll
;             for (int db = 0; db < 4; ++db) { const f32x4 o = oa[db] * inv; u32x2 wv; wv.x = cvt_pk_bf16_asm(o[0], o[1]); wv.y = cvt_pk_bf16_asm(o[2], o[3]);
;                 *(u32x2*)(qkv + tokq * 1536 + 64 * h + 16 * db + 4 * lq) = wv; }
	v_mfma_f32_16x16x32_bf16 v[70:73], v[232:235], v[58:61], v[70:73]
	v_mfma_f32_16x16x32_bf16 v[74:77], v[236:239], v[58:61], v[74:77]
	v_mfma_f32_16x16x32_bf16 v[78:81], v[240:243], v[58:61], v[78:81]
	v_mfma_f32_16x16x32_bf16 v[82:85], v[244:247], v[58:61], v[82:85]
	s_waitcnt lgkmcnt(0)
	v_mfma_f32_16x16x32_bf16 v[70:73], v[216:219], v[66:69], v[70:73]
	v_mfma_f32_16x16x32_bf16 v[74:77], v[220:223], v[66:69], v[74:77]
	v_mfma_f32_16x16x32_bf16 v[78:81], v[224:227], v[66:69], v[78:81]
	v_mfma_f32_16x16x32_bf16 v[82:85], v[228:231], v[66:69], v[82:85]
	s_nop 7
	s_nop 1
	v_mul_f32_e32 v70, v70, v147
	v_mul_f32_e32 v71, v71, v147
	v_mul_f32_e32 v72, v72, v147
	v_mul_f32_e32 v73, v73, v147
	v_mul_f32_e32 v74, v74, v147
	v_mul_f32_e32 v75, v75, v147
	v_mul_f32_e32 v76, v76, v147
	v_mul_f32_e32 v77, v77, v147
	v_mul_f32_e32 v78, v78, v147
	v_mul_f32_e32 v79, v79, v147
	v_mul_f32_e32 v80, v80, v147
	v_mul_f32_e32 v81, v81, v147
	v_mul_f32_e32 v82, v82, v147
	v_mul_f32_e32 v83, v83, v147
	v_mul_f32_e32 v84, v84, v147
	v_mul_f32_e32 v85, v85, v147
	v_cvt_pk_bf16_f32 v70, v70, v71
	v_cvt_pk_bf16_f32 v71, v72, v73
	v_cvt_pk_bf16_f32 v74, v74, v75
	v_cvt_pk_bf16_f32 v75, v76, v77
	v_cvt_pk_bf16_f32 v78, v78, v79
	v_cvt_pk_bf16_f32 v79, v80, v81
	v_cvt_pk_bf16_f32 v82, v82, v83
	v_cvt_pk_bf16_f32 v83, v84, v85
	global_store_dwordx2 v[248:249], v[70:71], off offset:-64
	global_store_dwordx2 v[248:249], v[74:75], off offset:-32
	global_store_dwordx2 v[248:249], v[78:79], off
	global_store_dwordx2 v[248:249], v[82:83], off offset:32
	s_branch .Latt_done
.LBB0_306:
	ds_read_b128 v[6:9], v141
	ds_read_b128 v[10:13], v141 offset:64
	s_cmp_eq_u32 s22, 0
	s_cbranch_scc0 .Latt_q_ready
	s_waitcnt vmcnt(0)
.Latt_q_ready:
	v_mov_b32_e32 v98, v180
	v_mov_b32_e32 v99, v181
	v_mov_b32_e32 v100, v182
	v_mov_b32_e32 v101, v183
	v_mov_b32_e32 v2, v184
	v_mov_b32_e32 v3, v185
	v_mov_b32_e32 v4, v186
	v_mov_b32_e32 v5, v187
	v_mov_b32_e32 v180, v188
	v_mov_b32_e32 v181, v189
	v_mov_b32_e32 v182, v190
	v_mov_b32_e32 v183, v191
	v_mov_b32_e32 v184, v192
	v_mov_b32_e32 v185, v193
	v_mov_b32_e32 v186, v194
	v_mov_b32_e32 v187, v195
	v_mov_b32_e32 v188, v196
	v_mov_b32_e32 v189, v197
	v_mov_b32_e32 v190, v198
	v_mov_b32_e32 v191, v199
	v_mov_b32_e32 v192, v200
	v_mov_b32_e32 v193, v201
	v_mov_b32_e32 v194, v202
	v_mov_b32_e32 v195, v203
	v_mov_b32_e32 v196, v204
	v_mov_b32_e32 v197, v205
	v_mov_b32_e32 v198, v206
	v_mov_b32_e32 v199, v207
	v_mov_b32_e32 v200, v208
	v_mov_b32_e32 v201, v209
	v_mov_b32_e32 v202, v210
	v_mov_b32_e32 v203, v211
	s_waitcnt lgkmcnt(1)
	v_mfma_f32_16x16x32_bf16 v[6:9], v[6:9], v[98:101], 0
	ds_read_b128 v[148:151], v141 offset:50752
	s_waitcnt lgkmcnt(1)
	v_mfma_f32_16x16x32_bf16 v[94:97], v[10:13], v[2:5], v[6:9]
	ds_read_b128 v[10:13], v141 offset:2368
	s_nop 3
	ds_read_b128 v[6:9], v141 offset:2304
	s_waitcnt lgkmcnt(0)
	v_mfma_f32_16x16x32_bf16 v[6:9], v[6:9], v[98:101], 0
	v_mov_b32_e32 v108, v94
	v_mfma_f32_16x16x32_bf16 v[90:93], v[10:13], v[2:5], v[6:9]
	ds_read_b128 v[10:13], v141 offset:4672
	s_nop 4
	ds_read_b128 v[6:9], v141 offset:4608
	s_waitcnt lgkmcnt(0)
	v_mfma_f32_16x16x32_bf16 v[6:9], v[6:9], v[98:101], 0
	v_mfma_f32_16x16x32_bf16 v[86:89], v[10:13], v[2:5], v[6:9]
	ds_read_b128 v[10:13], v141 offset:6976
	s_nop 5
	ds_read_b128 v[6:9], v141 offset:6912
	s_waitcnt lgkmcnt(0)
	v_mfma_f32_16x16x32_bf16 v[6:9], v[6:9], v[98:101], 0
	v_mfma_f32_16x16x32_bf16 v[82:85], v[10:13], v[2:5], v[6:9]
	ds_read_b128 v[10:13], v141 offset:9280
	s_nop 5
	ds_read_b128 v[6:9], v141 offset:9216
	s_waitcnt lgkmcnt(0)
	v_mfma_f32_16x16x32_bf16 v[6:9], v[6:9], v[98:101], 0
	v_mfma_f32_16x16x32_bf16 v[78:81], v[10:13], v[2:5], v[6:9]
	ds_read_b128 v[10:13], v141 offset:11584
	s_nop 5
	ds_read_b128 v[6:9], v141 offset:11520
	s_waitcnt lgkmcnt(0)
	v_mfma_f32_16x16x32_bf16 v[6:9], v[6:9], v[98:101], 0
	v_mfma_f32_16x16x32_bf16 v[74:77], v[10:13], v[2:5], v[6:9]
	ds_read_b128 v[10:13], v141 offset:13888
	s_nop 5
	ds_read_b128 v[6:9], v141 offset:13824
	s_waitcnt lgkmcnt(0)
	v_mfma_f32_16x16x32_bf16 v[6:9], v[6:9], v[98:101], 0
	v_mfma_f32_16x16x32_bf16 v[70:73], v[10:13], v[2:5], v[6:9]
	ds_read_b128 v[10:13], v141 offset:16192
	s_nop 5
	ds_read_b128 v[6:9], v141 offset:16128
	s_waitcnt lgkmcnt(0)
	v_mfma_f32_16x16x32_bf16 v[6:9], v[6:9], v[98:101], 0
	v_mfma_f32_16x16x32_bf16 v[66:69], v[10:13], v[2:5], v[6:9]
	ds_read_b128 v[10:13], v141 offset:18496
	s_nop 5
	ds_read_b128 v[6:9], v141 offset:18432
	s_waitcnt lgkmcnt(0)
	v_mfma_f32_16x16x32_bf16 v[6:9], v[6:9], v[98:101], 0
	v_mfma_f32_16x16x32_bf16 v[62:65], v[10:13], v[2:5], v[6:9]
	ds_read_b128 v[10:13], v141 offset:20800
	s_nop 5
	ds_read_b128 v[6:9], v141 offset:20736
	s_waitcnt lgkmcnt(0)
	v_mfma_f32_16x16x32_bf16 v[6:9], v[6:9], v[98:101], 0
	v_mfma_f32_16x16x32_bf16 v[58:61], v[10:13], v[2:5], v[6:9]
	ds_read_b128 v[10:13], v141 offset:23104
	s_nop 5
	ds_read_b128 v[6:9], v141 offset:23040
	s_waitcnt lgkmcnt(0)
	v_mfma_f32_16x16x32_bf16 v[6:9], v[6:9], v[98:101], 0
	v_mfma_f32_16x16x32_bf16 v[54:57], v[10:13], v[2:5], v[6:9]
	ds_read_b128 v[10:13], v141 offset:25408
	s_nop 5
	ds_read_b128 v[6:9], v141 offset:25344
	s_waitcnt lgkmcnt(0)
	v_mfma_f32_16x16x32_bf16 v[6:9], v[6:9], v[98:101], 0
	v_mfma_f32_16x16x32_bf16 v[50:53], v[10:13], v[2:5], v[6:9]
	ds_read_b128 v[10:13], v141 offset:27712
	s_nop 5
	ds_read_b128 v[6:9], v141 offset:27648
	s_waitcnt lgkmcnt(0)
	v_mfma_f32_16x16x32_bf16 v[6:9], v[6:9], v[98:101], 0
	v_mfma_f32_16x16x32_bf16 v[46:49], v[10:13], v[2:5], v[6:9]
	ds_read_b128 v[10:13], v141 offset:30016
	s_nop 5
	ds_read_b128 v[6:9], v141 offset:29952
	s_waitcnt lgkmcnt(0)
; __device__ __forceinline__ f32x4 mfma16(bf16x8 a, bf16x8 b, f32x4 c) { return __builtin_amdgcn_mfma_f32_16x16x32_bf16(a, b, c, 0, 0, 0); }
; __device__ void att_phase(int wv, const Params& p, unsigned char* lds) {
;     ...
;             for (int cb = 0; cb < 24; ++cb) { f32x4 a = {0, 0, 0, 0};
; #pragma unroll
;                 for (int kk = 0; kk < 2; ++kk) { const bf16x8 kf = *(const bf16x8*)(KL + (16 * cb + lr) * KP + 32 * kk + 8 * lq); a = mfma16(kf, qf[kk], a); }
;                 sc[cb] = a; }
;             float mx = sink;
; #pragma unroll
;             for (int cb = 0; cb < 24; ++cb) { const int kb = B - 1 + (cb >> 3); const bool bval = (kb >= sb && kb < se);
; #pragma unroll
;                 for (int j = 0; j < 4; ++j) { const int krel = 16 * cb + 4 * lq + j - 128;
;                     int dist = qrow - krel; dist = dist < 0 ? -dist : dist;
;                     const float v = (bval && dist <= 128) ? sc[cb][j] * 0.125f - slope * (float)dist : -1e30f;
	v_mfma_f32_16x16x32_bf16 v[6:9], v[6:9], v[98:101], 0
	v_mfma_f32_16x16x32_bf16 v[42:45], v[10:13], v[2:5], v[6:9]
	ds_read_b128 v[10:13], v141 offset:32320
	s_nop 5
	ds_read_b128 v[6:9], v141 offset:32256
	s_waitcnt lgkmcnt(0)
	v_mfma_f32_16x16x32_bf16 v[6:9], v[6:9], v[98:101], 0
	v_mfma_f32_16x16x32_bf16 v[38:41], v[10:13], v[2:5], v[6:9]
	ds_read_b128 v[10:13], v141 offset:34624
	s_nop 5
	ds_read_b128 v[6:9], v141 offset:34560
	s_waitcnt lgkmcnt(0)
	v_mfma_f32_16x16x32_bf16 v[6:9], v[6:9], v[98:101], 0
	v_mfma_f32_16x16x32_bf16 v[34:37], v[10:13], v[2:5], v[6:9]
	ds_read_b128 v[10:13], v141 offset:36928
	s_nop 5
	ds_read_b128 v[6:9], v141 offset:36864
	s_waitcnt lgkmcnt(0)
	v_mfma_f32_16x16x32_bf16 v[6:9], v[6:9], v[98:101], 0
	v_mfma_f32_16x16x32_bf16 v[30:33], v[10:13], v[2:5], v[6:9]
	ds_read_b128 v[10:13], v141 offset:39232
	s_nop 5
	ds_read_b128 v[6:9], v141 offset:39168
	s_waitcnt lgkmcnt(0)
	v_mfma_f32_16x16x32_bf16 v[6:9], v[6:9], v[98:101], 0
	v_mfma_f32_16x16x32_bf16 v[26:29], v[10:13], v[2:5], v[6:9]
	ds_read_b128 v[10:13], v141 offset:41536
	s_nop 5
	ds_read_b128 v[6:9], v141 offset:41472
	s_waitcnt lgkmcnt(0)
	v_mfma_f32_16x16x32_bf16 v[6:9], v[6:9], v[98:101], 0
	v_mfma_f32_16x16x32_bf16 v[22:25], v[10:13], v[2:5], v[6:9]
	ds_read_b128 v[10:13], v141 offset:43840
	s_nop 5
	ds_read_b128 v[6:9], v141 offset:43776
	s_waitcnt lgkmcnt(0)
	v_mfma_f32_16x16x32_bf16 v[6:9], v[6:9], v[98:101], 0
	v_mfma_f32_16x16x32_bf16 v[18:21], v[10:13], v[2:5], v[6:9]
	ds_read_b128 v[10:13], v141 offset:46144
	s_nop 5
	ds_read_b128 v[6:9], v141 offset:46080
	s_waitcnt lgkmcnt(0)
	v_mfma_f32_16x16x32_bf16 v[6:9], v[6:9], v[98:101], 0
	v_mfma_f32_16x16x32_bf16 v[14:17], v[10:13], v[2:5], v[6:9]
	ds_read_b128 v[10:13], v141 offset:48448
	s_nop 5
	ds_read_b128 v[6:9], v141 offset:48384
	s_waitcnt lgkmcnt(0)
	v_mfma_f32_16x16x32_bf16 v[6:9], v[6:9], v[98:101], 0
	v_mfma_f32_16x16x32_bf16 v[10:13], v[10:13], v[2:5], v[6:9]
	s_nop 6
	ds_read_b128 v[6:9], v141 offset:50688
	s_waitcnt lgkmcnt(0)
	v_mfma_f32_16x16x32_bf16 v[6:9], v[6:9], v[98:101], 0
	v_mfma_f32_16x16x32_bf16 v[6:9], v[148:151], v[2:5], v[6:9]
	ds_read_b128 v[148:151], v141 offset:52992
	s_waitcnt lgkmcnt(0)
	v_mfma_f32_16x16x32_bf16 v[98:101], v[148:151], v[98:101], 0
	ds_read_b128 v[148:151], v141 offset:53056
	s_waitcnt lgkmcnt(0)
	v_mfma_f32_16x16x32_bf16 v[2:5], v[148:151], v[2:5], v[98:101]
	s_nop 4
	v_add_u32_e32 v98, s22, v127
	v_add_u32_e32 v99, 0x80, v98
	v_cvt_f32_u32_e32 v179, v99
	v_cmp_gt_u32_e32 vcc, s43, v99
	v_add_u32_e32 v99, 0x7f, v98
	s_and_b64 vcc, s[6:7], vcc
	v_pk_mul_f32 v[100:101], v[108:109], v[178:179]
	v_cvt_f32_u32_e32 v179, v99
	v_mov_b32_e32 v108, v95
	v_sub_f32_e32 v94, v100, v101
	v_cndmask_b32_e32 v94, v252, v94, vcc
	v_pk_mul_f32 v[100:101], v[108:109], v[178:179]
	v_cmp_gt_u32_e32 vcc, s43, v99
	v_sub_f32_e32 v95, v100, v101
	v_add_u32_e32 v100, 0x7e, v98
	v_cvt_f32_u32_e32 v179, v100
	s_and_b64 vcc, s[6:7], vcc
	v_mov_b32_e32 v108, v96
	v_cndmask_b32_e32 v95, v252, v95, vcc
	v_cmp_gt_u32_e32 vcc, s43, v100
	v_pk_mul_f32 v[100:101], v[108:109], v[178:179]
	s_and_b64 vcc, s[6:7], vcc
	v_sub_f32_e32 v96, v100, v101
	v_add_u32_e32 v100, 0x7d, v98
	v_cvt_f32_u32_e32 v179, v100
	v_mov_b32_e32 v108, v97
	v_cndmask_b32_e32 v96, v252, v96, vcc
	v_cmp_gt_u32_e32 vcc, s43, v100
	v_pk_mul_f32 v[100:101], v[108:109], v[178:179]
	s_and_b64 vcc, s[6:7], vcc
	v_sub_f32_e32 v97, v100, v101
	v_add_u32_e32 v100, 0x70, v98
	v_cvt_f32_u32_e32 v179, v100
	v_mov_b32_e32 v108, v90
	v_cndmask_b32_e32 v97, v252, v97, vcc
	v_cmp_gt_u32_e32 vcc, s43, v100
	v_pk_mul_f32 v[100:101], v[108:109], v[178:179]
	s_and_b64 vcc, s[6:7], vcc
	v_sub_f32_e32 v90, v100, v101
	v_add_u32_e32 v100, 0x6f, v98
	v_cvt_f32_u32_e32 v179, v100
	v_mov_b32_e32 v108, v91
	v_cndmask_b32_e32 v90, v252, v90, vcc
	v_cmp_gt_u32_e32 vcc, s43, v100
	v_pk_mul_f32 v[100:101], v[108:109], v[178:179]
	s_and_b64 vcc, s[6:7], vcc
	v_sub_f32_e32 v91, v100, v101
	v_add_u32_e32 v100, 0x6e, v98
	v_cvt_f32_u32_e32 v179, v100
	v_mov_b32_e32 v108, v92
	v_cndmask_b32_e32 v91, v252, v91, vcc
	v_cmp_gt_u32_e32 vcc, s43, v100
	v_pk_mul_f32 v[100:101], v[108:109], v[178:179]
	s_and_b64 vcc, s[6:7], vcc
	v_sub_f32_e32 v92, v100, v101
	v_add_u32_e32 v100, 0x6d, v98
	v_cvt_f32_u32_e32 v179, v100
	v_mov_b32_e32 v108, v93
	v_cndmask_b32_e32 v92, v252, v92, vcc
	v_cmp_gt_u32_e32 vcc, s43, v100
	v_pk_mul_f32 v[100:101], v[108:109], v[178:179]
	s_and_b64 vcc, s[6:7], vcc
	v_sub_f32_e32 v93, v100, v101
	v_add_u32_e32 v100, 0x60, v98
	v_cvt_f32_u32_e32 v179, v100
	v_mov_b32_e32 v108, v86
	v_cndmask_b32_e32 v93, v252, v93, vcc
	v_cmp_gt_u32_e32 vcc, s43, v100
	v_pk_mul_f32 v[100:101], v[108:109], v[178:179]
	s_and_b64 vcc, s[6:7], vcc
	v_sub_f32_e32 v86, v100, v101
	v_add_u32_e32 v100, 0x5f, v98
	v_cvt_f32_u32_e32 v179, v100
	v_mov_b32_e32 v108, v87
	v_cndmask_b32_e32 v86, v252, v86, vcc
	v_cmp_gt_u32_e32 vcc, s43, v100
	v_pk_mul_f32 v[100:101], v[108:109], v[178:179]
	s_and_b64 vcc, s[6:7], vcc
	v_sub_f32_e32 v87, v100, v101
	v_add_u32_e32 v100, 0x5e, v98
	v_cvt_f32_u32_e32 v179, v100
	v_mov_b32_e32 v108, v88
	v_cndmask_b32_e32 v87, v252, v87, vcc
	v_cmp_gt_u32_e32 vcc, s43, v100
	v_pk_mul_f32 v[100:101], v[108:109], v[178:179]
	s_and_b64 vcc, s[6:7], vcc
	v_sub_f32_e32 v88, v100, v101
	v_add_u32_e32 v100, 0x5d, v98
	v_cvt_f32_u32_e32 v179, v100
	v_mov_b32_e32 v108, v89
	v_cndmask_b32_e32 v88, v252, v88, vcc
	v_cmp_gt_u32_e32 vcc, s43, v100
	v_pk_mul_f32 v[100:101], v[108:109], v[178:179]
	s_and_b64 vcc, s[6:7], vcc
	v_sub_f32_e32 v89, v100, v101
	v_add_u32_e32 v100, 0x50, v98
	v_cvt_f32_u32_e32 v179, v100
	v_mov_b32_e32 v108, v82
; __device__ void att_phase(int wv, const Params& p, unsigned char* lds) {
;     ...
;             for (int cb = 0; cb < 24; ++cb) { const int kb = B - 1 + (cb >> 3); const bool bval = (kb >= sb && kb < se);
; #pragma unroll
;                 for (int j = 0; j < 4; ++j) { const int krel = 16 * cb + 4 * lq + j - 128;
;                     int dist = qrow - krel; dist = dist < 0 ? -dist : dist;
;                     const float v = (bval && dist <= 128) ? sc[cb][j] * 0.125f - slope * (float)dist : -1e30f;
;                     sc[cb][j] = v; mx = fmaxf(mx, v); } }
	v_cndmask_b32_e32 v89, v252, v89, vcc
	v_cmp_gt_u32_e32 vcc, s43, v100
	v_pk_mul_f32 v[100:101], v[108:109], v[178:179]
	s_and_b64 vcc, s[6:7], vcc
	v_sub_f32_e32 v82, v100, v101
	v_add_u32_e32 v100, 0x4f, v98
	v_cvt_f32_u32_e32 v179, v100
	v_mov_b32_e32 v108, v83
	v_cndmask_b32_e32 v82, v252, v82, vcc
	v_cmp_gt_u32_e32 vcc, s43, v100
	v_pk_mul_f32 v[100:101], v[108:109], v[178:179]
	s_and_b64 vcc, s[6:7], vcc
	v_sub_f32_e32 v83, v100, v101
	v_add_u32_e32 v100, 0x4e, v98
	v_cvt_f32_u32_e32 v179, v100
	v_mov_b32_e32 v108, v84
	v_cndmask_b32_e32 v83, v252, v83, vcc
	v_cmp_gt_u32_e32 vcc, s43, v100
	v_pk_mul_f32 v[100:101], v[108:109], v[178:179]
	s_and_b64 vcc, s[6:7], vcc
	v_sub_f32_e32 v84, v100, v101
	v_add_u32_e32 v100, 0x4d, v98
	v_cvt_f32_u32_e32 v179, v100
	v_mov_b32_e32 v108, v85
	v_cndmask_b32_e32 v84, v252, v84, vcc
	v_cmp_gt_u32_e32 vcc, s43, v100
	v_pk_mul_f32 v[100:101], v[108:109], v[178:179]
	s_and_b64 vcc, s[6:7], vcc
	v_sub_f32_e32 v85, v100, v101
	v_add_u32_e32 v100, 64, v98
	v_cvt_f32_u32_e32 v179, v100
	v_mov_b32_e32 v108, v78
	v_cndmask_b32_e32 v85, v252, v85, vcc
	v_cmp_gt_u32_e32 vcc, s43, v100
	v_pk_mul_f32 v[100:101], v[108:109], v[178:179]
	s_and_b64 vcc, s[6:7], vcc
	v_sub_f32_e32 v78, v100, v101
	v_add_u32_e32 v100, 63, v98
	v_cvt_f32_u32_e32 v179, v100
	v_mov_b32_e32 v108, v79
	v_cndmask_b32_e32 v78, v252, v78, vcc
	v_cmp_gt_u32_e32 vcc, s43, v100
	v_pk_mul_f32 v[100:101], v[108:109], v[178:179]
	s_and_b64 vcc, s[6:7], vcc
	v_sub_f32_e32 v79, v100, v101
	v_add_u32_e32 v100, 62, v98
	v_cvt_f32_u32_e32 v179, v100
	v_mov_b32_e32 v108, v80
	v_cndmask_b32_e32 v79, v252, v79, vcc
	v_cmp_gt_u32_e32 vcc, s43, v100
	v_pk_mul_f32 v[100:101], v[108:109], v[178:179]
	s_and_b64 vcc, s[6:7], vcc
	v_sub_f32_e32 v80, v100, v101
	v_add_u32_e32 v100, 61, v98
	v_cvt_f32_u32_e32 v179, v100
	v_mov_b32_e32 v108, v81
	v_cndmask_b32_e32 v80, v252, v80, vcc
	v_cmp_gt_u32_e32 vcc, s43, v100
	v_pk_mul_f32 v[100:101], v[108:109], v[178:179]
	s_and_b64 vcc, s[6:7], vcc
	v_sub_f32_e32 v81, v100, v101
	v_add_u32_e32 v100, 48, v98
	v_cvt_f32_u32_e32 v179, v100
	v_mov_b32_e32 v108, v74
	v_cndmask_b32_e32 v81, v252, v81, vcc
	v_cmp_gt_u32_e32 vcc, s43, v100
	v_pk_mul_f32 v[100:101], v[108:109], v[178:179]
	s_and_b64 vcc, s[6:7], vcc
	v_sub_f32_e32 v74, v100, v101
	v_add_u32_e32 v100, 47, v98
	v_cvt_f32_u32_e32 v179, v100
	v_mov_b32_e32 v108, v75
	v_cndmask_b32_e32 v74, v252, v74, vcc
	v_cmp_gt_u32_e32 vcc, s43, v100
	v_pk_mul_f32 v[100:101], v[108:109], v[178:179]
	s_and_b64 vcc, s[6:7], vcc
	v_sub_f32_e32 v75, v100, v101
	v_add_u32_e32 v100, 46, v98
	v_cvt_f32_u32_e32 v179, v100
	v_mov_b32_e32 v108, v76
	v_cndmask_b32_e32 v75, v252, v75, vcc
	v_cmp_gt_u32_e32 vcc, s43, v100
	v_pk_mul_f32 v[100:101], v[108:109], v[178:179]
	s_and_b64 vcc, s[6:7], vcc
	v_sub_f32_e32 v76, v100, v101
	v_add_u32_e32 v100, 45, v98
	v_cvt_f32_u32_e32 v179, v100
	v_mov_b32_e32 v108, v77
	v_cndmask_b32_e32 v76, v252, v76, vcc
	v_cmp_gt_u32_e32 vcc, s43, v100
	v_pk_mul_f32 v[100:101], v[108:109], v[178:179]
	s_and_b64 vcc, s[6:7], vcc
	v_sub_f32_e32 v77, v100, v101
	v_add_u32_e32 v100, 32, v98
	v_cvt_f32_u32_e32 v179, v100
	v_mov_b32_e32 v108, v70
	v_cndmask_b32_e32 v77, v252, v77, vcc
	v_cmp_gt_u32_e32 vcc, s43, v100
	v_pk_mul_f32 v[100:101], v[108:109], v[178:179]
	s_and_b64 vcc, s[6:7], vcc
	v_sub_f32_e32 v70, v100, v101
	v_add_u32_e32 v100, 31, v98
	v_cvt_f32_u32_e32 v179, v100
	v_mov_b32_e32 v108, v71
	v_cndmask_b32_e32 v70, v252, v70, vcc
	v_cmp_gt_u32_e32 vcc, s43, v100
	v_pk_mul_f32 v[100:101], v[108:109], v[178:179]
	s_and_b64 vcc, s[6:7], vcc
	v_sub_f32_e32 v71, v100, v101
	v_add_u32_e32 v100, 30, v98
	v_cvt_f32_u32_e32 v179, v100
	v_mov_b32_e32 v108, v72
	v_cndmask_b32_e32 v71, v252, v71, vcc
	v_cmp_gt_u32_e32 vcc, s43, v100
	v_pk_mul_f32 v[100:101], v[108:109], v[178:179]
	s_and_b64 vcc, s[6:7], vcc
	v_sub_f32_e32 v72, v100, v101
	v_add_u32_e32 v100, 29, v98
	v_cvt_f32_u32_e32 v179, v100
	v_mov_b32_e32 v108, v73
	v_cndmask_b32_e32 v72, v252, v72, vcc
	v_cmp_gt_u32_e32 vcc, s43, v100
	v_pk_mul_f32 v[100:101], v[108:109], v[178:179]
	s_and_b64 vcc, s[6:7], vcc
	v_sub_f32_e32 v73, v100, v101
	v_add_u32_e32 v100, 16, v98
	v_cvt_f32_u32_e32 v179, v100
	v_mov_b32_e32 v108, v66
	v_cndmask_b32_e32 v73, v252, v73, vcc
	v_cmp_gt_u32_e32 vcc, s43, v100
	v_pk_mul_f32 v[100:101], v[108:109], v[178:179]
	s_and_b64 vcc, s[6:7], vcc
	v_sub_f32_e32 v66, v100, v101
	v_add_u32_e32 v100, 15, v98
	v_cvt_f32_u32_e32 v179, v100
	v_mov_b32_e32 v108, v67
	v_cndmask_b32_e32 v66, v252, v66, vcc
	v_cmp_gt_u32_e32 vcc, s43, v100
	v_pk_mul_f32 v[100:101], v[108:109], v[178:179]
	s_and_b64 vcc, s[6:7], vcc
	v_sub_f32_e32 v67, v100, v101
	v_add_u32_e32 v100, 14, v98
	v_cvt_f32_u32_e32 v179, v100
	v_mov_b32_e32 v108, v68
	v_cndmask_b32_e32 v67, v252, v67, vcc
	v_cmp_gt_u32_e32 vcc, s43, v100
	v_pk_mul_f32 v[100:101], v[108:109], v[178:179]
	s_and_b64 vcc, s[6:7], vcc
	v_sub_f32_e32 v68, v100, v101
	v_add_u32_e32 v100, 13, v98
	v_cvt_f32_u32_e32 v179, v100
	v_mov_b32_e32 v108, v69
	v_cndmask_b32_e32 v68, v252, v68, vcc
	v_cmp_gt_u32_e32 vcc, s43, v100
	v_pk_mul_f32 v[100:101], v[108:109], v[178:179]
	s_and_b64 vcc, s[6:7], vcc
	v_sub_f32_e32 v69, v100, v101
	v_sub_u32_e32 v100, 0, v98
	v_max_i32_e32 v100, v98, v100
	v_cvt_f32_u32_e32 v179, v100
	v_mov_b32_e32 v108, v62
	v_cndmask_b32_e32 v69, v252, v69, vcc
	v_cmp_gt_u32_e32 vcc, s43, v100
	v_pk_mul_f32 v[100:101], v[108:109], v[178:179]
	s_and_b64 vcc, s[14:15], vcc
	v_sub_f32_e32 v62, v100, v101
	v_add_u32_e32 v100, -1, v98
	v_sub_u32_e32 v101, 1, v98
	v_max_i32_e32 v100, v100, v101
	v_cvt_f32_u32_e32 v179, v100
	v_mov_b32_e32 v108, v63
; __device__ void att_phase(int wv, const Params& p, unsigned char* lds) {
;     ...
;             for (int cb = 0; cb < 24; ++cb) { const int kb = B - 1 + (cb >> 3); const bool bval = (kb >= sb && kb < se);
; #pragma unroll
;                 for (int j = 0; j < 4; ++j) { const int krel = 16 * cb + 4 * lq + j - 128;
;                     int dist = qrow - krel; dist = dist < 0 ? -dist : dist;
;                     const float v = (bval && dist <= 128) ? sc[cb][j] * 0.125f - slope * (float)dist : -1e30f;
;                     sc[cb][j] = v; mx = fmaxf(mx, v); } }
	v_cndmask_b32_e32 v62, v252, v62, vcc
	v_cmp_gt_u32_e32 vcc, s43, v100
	v_pk_mul_f32 v[100:101], v[108:109], v[178:179]
	s_and_b64 vcc, s[14:15], vcc
	v_sub_f32_e32 v63, v100, v101
	v_add_u32_e32 v100, -2, v98
	v_sub_u32_e32 v101, 2, v98
	v_max_i32_e32 v100, v100, v101
	v_cvt_f32_u32_e32 v179, v100
	v_mov_b32_e32 v108, v64
	v_cndmask_b32_e32 v63, v252, v63, vcc
	v_cmp_gt_u32_e32 vcc, s43, v100
	v_pk_mul_f32 v[100:101], v[108:109], v[178:179]
	s_and_b64 vcc, s[14:15], vcc
	v_sub_f32_e32 v64, v100, v101
	v_add_u32_e32 v100, -3, v98
	v_sub_u32_e32 v101, 3, v98
	v_max_i32_e32 v100, v100, v101
	v_cvt_f32_u32_e32 v179, v100
	v_mov_b32_e32 v108, v65
	v_cndmask_b32_e32 v64, v252, v64, vcc
	v_cmp_gt_u32_e32 vcc, s43, v100
	v_pk_mul_f32 v[100:101], v[108:109], v[178:179]
	s_and_b64 vcc, s[14:15], vcc
	v_sub_f32_e32 v65, v100, v101
	v_add_u32_e32 v100, -16, v98
	v_sub_u32_e32 v101, 16, v98
	v_max_i32_e32 v100, v100, v101
	v_cvt_f32_u32_e32 v179, v100
	v_mov_b32_e32 v108, v58
	v_cndmask_b32_e32 v65, v252, v65, vcc
	v_cmp_gt_u32_e32 vcc, s43, v100
	v_pk_mul_f32 v[100:101], v[108:109], v[178:179]
	s_and_b64 vcc, s[14:15], vcc
	v_sub_f32_e32 v58, v100, v101
	v_subrev_u32_e32 v100, 17, v98
	v_sub_u32_e32 v101, 17, v98
	v_max_i32_e32 v100, v100, v101
	v_cvt_f32_u32_e32 v179, v100
	v_mov_b32_e32 v108, v59
	v_cndmask_b32_e32 v58, v252, v58, vcc
	v_cmp_gt_u32_e32 vcc, s43, v100
	v_pk_mul_f32 v[100:101], v[108:109], v[178:179]
	s_and_b64 vcc, s[14:15], vcc
	v_sub_f32_e32 v59, v100, v101
	v_subrev_u32_e32 v100, 18, v98
	v_sub_u32_e32 v101, 18, v98
	v_max_i32_e32 v100, v100, v101
	v_cvt_f32_u32_e32 v179, v100
	v_mov_b32_e32 v108, v60
	v_cndmask_b32_e32 v59, v252, v59, vcc
	v_cmp_gt_u32_e32 vcc, s43, v100
	v_pk_mul_f32 v[100:101], v[108:109], v[178:179]
	s_and_b64 vcc, s[14:15], vcc
	v_sub_f32_e32 v60, v100, v101
	v_subrev_u32_e32 v100, 19, v98
	v_sub_u32_e32 v101, 19, v98
	v_max_i32_e32 v100, v100, v101
	v_cvt_f32_u32_e32 v179, v100
	v_mov_b32_e32 v108, v61
	v_cndmask_b32_e32 v60, v252, v60, vcc
	v_cmp_gt_u32_e32 vcc, s43, v100
	v_pk_mul_f32 v[100:101], v[108:109], v[178:179]
	s_and_b64 vcc, s[14:15], vcc
	v_sub_f32_e32 v61, v100, v101
	v_subrev_u32_e32 v100, 32, v98
	v_sub_u32_e32 v101, 32, v98
	v_max_i32_e32 v100, v100, v101
	v_cvt_f32_u32_e32 v179, v100
	v_mov_b32_e32 v108, v54
	v_cndmask_b32_e32 v61, v252, v61, vcc
	v_cmp_gt_u32_e32 vcc, s43, v100
	v_pk_mul_f32 v[100:101], v[108:109], v[178:179]
	s_and_b64 vcc, s[14:15], vcc
	v_sub_f32_e32 v54, v100, v101
	v_subrev_u32_e32 v100, 33, v98
	v_sub_u32_e32 v101, 33, v98
	v_max_i32_e32 v100, v100, v101
	v_cvt_f32_u32_e32 v179, v100
	v_mov_b32_e32 v108, v55
	v_cndmask_b32_e32 v54, v252, v54, vcc
	v_cmp_gt_u32_e32 vcc, s43, v100
	v_pk_mul_f32 v[100:101], v[108:109], v[178:179]
	s_and_b64 vcc, s[14:15], vcc
	v_sub_f32_e32 v55, v100, v101
	v_subrev_u32_e32 v100, 34, v98
	v_sub_u32_e32 v101, 34, v98
	v_max_i32_e32 v100, v100, v101
	v_cvt_f32_u32_e32 v179, v100
	v_mov_b32_e32 v108, v56
	v_cndmask_b32_e32 v55, v252, v55, vcc
	v_cmp_gt_u32_e32 vcc, s43, v100
	v_pk_mul_f32 v[100:101], v[108:109], v[178:179]
	s_and_b64 vcc, s[14:15], vcc
	v_sub_f32_e32 v56, v100, v101
	v_subrev_u32_e32 v100, 35, v98
	v_sub_u32_e32 v101, 35, v98
	v_max_i32_e32 v100, v100, v101
	v_cvt_f32_u32_e32 v179, v100
	v_mov_b32_e32 v108, v57
	v_cndmask_b32_e32 v56, v252, v56, vcc
	v_cmp_gt_u32_e32 vcc, s43, v100
	v_pk_mul_f32 v[100:101], v[108:109], v[178:179]
	s_and_b64 vcc, s[14:15], vcc
	v_sub_f32_e32 v57, v100, v101
	v_subrev_u32_e32 v100, 48, v98
	v_sub_u32_e32 v101, 48, v98
	v_max_i32_e32 v100, v100, v101
	v_cvt_f32_u32_e32 v179, v100
	v_mov_b32_e32 v108, v50
	v_cndmask_b32_e32 v57, v252, v57, vcc
	v_cmp_gt_u32_e32 vcc, s43, v100
	v_pk_mul_f32 v[100:101], v[108:109], v[178:179]
	s_and_b64 vcc, s[14:15], vcc
	v_sub_f32_e32 v50, v100, v101
	v_subrev_u32_e32 v100, 49, v98
	v_sub_u32_e32 v101, 49, v98
	v_max_i32_e32 v100, v100, v101
	v_cvt_f32_u32_e32 v179, v100
	v_mov_b32_e32 v108, v51
	v_cndmask_b32_e32 v50, v252, v50, vcc
	v_cmp_gt_u32_e32 vcc, s43, v100
	v_pk_mul_f32 v[100:101], v[108:109], v[178:179]
	s_and_b64 vcc, s[14:15], vcc
	v_sub_f32_e32 v51, v100, v101
	v_subrev_u32_e32 v100, 50, v98
	v_sub_u32_e32 v101, 50, v98
	v_max_i32_e32 v100, v100, v101
	v_cvt_f32_u32_e32 v179, v100
	v_mov_b32_e32 v108, v52
	v_cndmask_b32_e32 v51, v252, v51, vcc
	v_cmp_gt_u32_e32 vcc, s43, v100
	v_pk_mul_f32 v[100:101], v[108:109], v[178:179]
	s_and_b64 vcc, s[14:15], vcc
	v_sub_f32_e32 v52, v100, v101
	v_subrev_u32_e32 v100, 51, v98
	v_sub_u32_e32 v101, 51, v98
	v_max_i32_e32 v100, v100, v101
	v_cvt_f32_u32_e32 v179, v100
	v_mov_b32_e32 v108, v53
	v_cndmask_b32_e32 v52, v252, v52, vcc
	v_cmp_gt_u32_e32 vcc, s43, v100
	v_pk_mul_f32 v[100:101], v[108:109], v[178:179]
	s_and_b64 vcc, s[14:15], vcc
	v_sub_f32_e32 v53, v100, v101
	v_subrev_u32_e32 v100, 64, v98
	v_sub_u32_e32 v101, 64, v98
	v_max_i32_e32 v100, v100, v101
	v_cvt_f32_u32_e32 v179, v100
	v_mov_b32_e32 v108, v46
	v_cndmask_b32_e32 v53, v252, v53, vcc
	v_cmp_gt_u32_e32 vcc, s43, v100
	v_pk_mul_f32 v[100:101], v[108:109], v[178:179]
	s_and_b64 vcc, s[14:15], vcc
	v_sub_f32_e32 v46, v100, v101
	v_add_u32_e32 v100, 0xffffffbf, v98
	v_sub_u32_e32 v101, 0x41, v98
	v_max_i32_e32 v100, v100, v101
	v_cvt_f32_u32_e32 v179, v100
	v_mov_b32_e32 v108, v47
	v_cndmask_b32_e32 v46, v252, v46, vcc
	v_cmp_gt_u32_e32 vcc, s43, v100
	v_pk_mul_f32 v[100:101], v[108:109], v[178:179]
	s_and_b64 vcc, s[14:15], vcc
	v_sub_f32_e32 v47, v100, v101
	v_add_u32_e32 v100, 0xffffffbe, v98
	v_sub_u32_e32 v101, 0x42, v98
	v_max_i32_e32 v100, v100, v101
	v_cvt_f32_u32_e32 v179, v100
	v_mov_b32_e32 v108, v48
	v_cndmask_b32_e32 v47, v252, v47, vcc
; __device__ void att_phase(int wv, const Params& p, unsigned char* lds) {
;     ...
;             for (int cb = 0; cb < 24; ++cb) { const int kb = B - 1 + (cb >> 3); const bool bval = (kb >= sb && kb < se);
; #pragma unroll
;                 for (int j = 0; j < 4; ++j) { const int krel = 16 * cb + 4 * lq + j - 128;
;                     int dist = qrow - krel; dist = dist < 0 ? -dist : dist;
;                     const float v = (bval && dist <= 128) ? sc[cb][j] * 0.125f - slope * (float)dist : -1e30f;
;                     sc[cb][j] = v; mx = fmaxf(mx, v); } }
	v_cmp_gt_u32_e32 vcc, s43, v100
	v_pk_mul_f32 v[100:101], v[108:109], v[178:179]
	s_and_b64 vcc, s[14:15], vcc
	v_sub_f32_e32 v48, v100, v101
	v_add_u32_e32 v100, 0xffffffbd, v98
	v_sub_u32_e32 v101, 0x43, v98
	v_max_i32_e32 v100, v100, v101
	v_cvt_f32_u32_e32 v179, v100
	v_mov_b32_e32 v108, v49
	v_cndmask_b32_e32 v48, v252, v48, vcc
	v_cmp_gt_u32_e32 vcc, s43, v100
	v_pk_mul_f32 v[100:101], v[108:109], v[178:179]
	s_and_b64 vcc, s[14:15], vcc
	v_sub_f32_e32 v49, v100, v101
	v_add_u32_e32 v100, 0xffffffb0, v98
	v_sub_u32_e32 v101, 0x50, v98
	v_max_i32_e32 v100, v100, v101
	v_cvt_f32_u32_e32 v179, v100
	v_mov_b32_e32 v108, v42
	v_cndmask_b32_e32 v49, v252, v49, vcc
	v_cmp_gt_u32_e32 vcc, s43, v100
	v_pk_mul_f32 v[100:101], v[108:109], v[178:179]
	s_and_b64 vcc, s[14:15], vcc
	v_sub_f32_e32 v42, v100, v101
	v_add_u32_e32 v100, 0xffffffaf, v98
	v_sub_u32_e32 v101, 0x51, v98
	v_max_i32_e32 v100, v100, v101
	v_cvt_f32_u32_e32 v179, v100
	v_mov_b32_e32 v108, v43
	v_cndmask_b32_e32 v42, v252, v42, vcc
	v_cmp_gt_u32_e32 vcc, s43, v100
	v_pk_mul_f32 v[100:101], v[108:109], v[178:179]
	s_and_b64 vcc, s[14:15], vcc
	v_sub_f32_e32 v43, v100, v101
	v_add_u32_e32 v100, 0xffffffae, v98
	v_sub_u32_e32 v101, 0x52, v98
	v_max_i32_e32 v100, v100, v101
	v_cvt_f32_u32_e32 v179, v100
	v_mov_b32_e32 v108, v44
	v_cndmask_b32_e32 v43, v252, v43, vcc
	v_cmp_gt_u32_e32 vcc, s43, v100
	v_pk_mul_f32 v[100:101], v[108:109], v[178:179]
	s_and_b64 vcc, s[14:15], vcc
	v_sub_f32_e32 v44, v100, v101
	v_add_u32_e32 v100, 0xffffffad, v98
	v_sub_u32_e32 v101, 0x53, v98
	v_max_i32_e32 v100, v100, v101
	v_cvt_f32_u32_e32 v179, v100
	v_mov_b32_e32 v108, v45
	v_cndmask_b32_e32 v44, v252, v44, vcc
	v_cmp_gt_u32_e32 vcc, s43, v100
	v_pk_mul_f32 v[100:101], v[108:109], v[178:179]
	s_and_b64 vcc, s[14:15], vcc
	v_sub_f32_e32 v45, v100, v101
	v_add_u32_e32 v100, 0xffffffa0, v98
	v_sub_u32_e32 v101, 0x60, v98
	v_max_i32_e32 v100, v100, v101
	v_cvt_f32_u32_e32 v179, v100
	v_mov_b32_e32 v108, v38
	v_cndmask_b32_e32 v45, v252, v45, vcc
	v_cmp_gt_u32_e32 vcc, s43, v100
	v_pk_mul_f32 v[100:101], v[108:109], v[178:179]
	s_and_b64 vcc, s[14:15], vcc
	v_sub_f32_e32 v38, v100, v101
	v_add_u32_e32 v100, 0xffffff9f, v98
	v_sub_u32_e32 v101, 0x61, v98
	v_max_i32_e32 v100, v100, v101
	v_cvt_f32_u32_e32 v179, v100
	v_mov_b32_e32 v108, v39
	v_cndmask_b32_e32 v38, v252, v38, vcc
	v_cmp_gt_u32_e32 vcc, s43, v100
	v_pk_mul_f32 v[100:101], v[108:109], v[178:179]
	v_max3_f32 v99, v146, v94, v95
	v_sub_f32_e32 v39, v100, v101
	v_add_u32_e32 v100, 0xffffff9e, v98
	v_sub_u32_e32 v101, 0x62, v98
	v_max3_f32 v99, v99, v96, v97
	v_max_i32_e32 v100, v100, v101
	v_max3_f32 v99, v99, v90, v91
	v_cvt_f32_u32_e32 v179, v100
	v_max3_f32 v99, v99, v92, v93
	v_max3_f32 v99, v99, v86, v87
	v_max3_f32 v99, v99, v88, v89
	s_and_b64 vcc, s[14:15], vcc
	v_mov_b32_e32 v108, v40
	v_max3_f32 v99, v99, v82, v83
	v_cndmask_b32_e32 v39, v252, v39, vcc
	v_cmp_gt_u32_e32 vcc, s43, v100
	v_pk_mul_f32 v[100:101], v[108:109], v[178:179]
	v_max3_f32 v99, v99, v84, v85
	v_sub_f32_e32 v40, v100, v101
	v_add_u32_e32 v100, 0xffffff9d, v98
	v_sub_u32_e32 v101, 0x63, v98
	v_max3_f32 v99, v99, v78, v79
	v_max_i32_e32 v100, v100, v101
	v_max3_f32 v99, v99, v80, v81
	v_cvt_f32_u32_e32 v179, v100
	v_max3_f32 v99, v99, v74, v75
	v_max3_f32 v99, v99, v76, v77
	v_max3_f32 v99, v99, v70, v71
	s_and_b64 vcc, s[14:15], vcc
	v_mov_b32_e32 v108, v41
	v_max3_f32 v99, v99, v72, v73
	v_cndmask_b32_e32 v40, v252, v40, vcc
	v_cmp_gt_u32_e32 vcc, s43, v100
	v_pk_mul_f32 v[100:101], v[108:109], v[178:179]
	v_max3_f32 v99, v99, v66, v67
	v_sub_f32_e32 v41, v100, v101
	v_add_u32_e32 v100, 0xffffff90, v98
	v_sub_u32_e32 v101, 0x70, v98
	v_max3_f32 v99, v99, v68, v69
	v_max_i32_e32 v100, v100, v101
	v_max3_f32 v99, v99, v62, v63
	v_cvt_f32_u32_e32 v179, v100
	v_max3_f32 v99, v99, v64, v65
	v_max3_f32 v99, v99, v58, v59
	v_max3_f32 v99, v99, v60, v61
	s_and_b64 vcc, s[14:15], vcc
	v_mov_b32_e32 v108, v34
	v_max3_f32 v99, v99, v54, v55
	v_cndmask_b32_e32 v41, v252, v41, vcc
	v_cmp_gt_u32_e32 vcc, s43, v100
	v_pk_mul_f32 v[100:101], v[108:109], v[178:179]
	v_max3_f32 v99, v99, v56, v57
	v_sub_f32_e32 v34, v100, v101
	v_add_u32_e32 v100, 0xffffff8f, v98
	v_sub_u32_e32 v101, 0x71, v98
	v_max3_f32 v99, v99, v50, v51
	v_max_i32_e32 v100, v100, v101
	v_max3_f32 v99, v99, v52, v53
	v_cvt_f32_u32_e32 v179, v100
	v_max3_f32 v99, v99, v46, v47
	v_max3_f32 v99, v99, v48, v49
	v_max3_f32 v99, v99, v42, v43
	s_and_b64 vcc, s[14:15], vcc
	v_mov_b32_e32 v108, v35
	v_max3_f32 v99, v99, v44, v45
	v_cndmask_b32_e32 v34, v252, v34, vcc
	v_cmp_gt_u32_e32 vcc, s43, v100
	v_pk_mul_f32 v[100:101], v[108:109], v[178:179]
	v_max3_f32 v99, v99, v38, v39
	s_and_b64 vcc, s[14:15], vcc
	v_sub_f32_e32 v35, v100, v101
	v_max3_f32 v99, v99, v40, v41
	v_cndmask_b32_e32 v35, v252, v35, vcc
	v_max3_f32 v148, v99, v34, v35
	v_add_u32_e32 v99, 0xffffff8e, v98
	v_sub_u32_e32 v100, 0x72, v98
	v_max_i32_e32 v99, v99, v100
	v_cvt_f32_u32_e32 v179, v99
	v_cmp_gt_u32_e32 vcc, s43, v99
	v_add_u32_e32 v99, 0xffffff8d, v98
	v_sub_u32_e32 v98, 0x73, v98
	v_mov_b32_e32 v108, v36
	v_max_i32_e32 v98, v99, v98
	v_pk_mul_f32 v[100:101], v[108:109], v[178:179]
	v_cvt_f32_u32_e32 v179, v98
	s_and_b64 vcc, s[14:15], vcc
	v_sub_f32_e32 v36, v100, v101
	v_mov_b32_e32 v108, v37
	v_cndmask_b32_e32 v36, v252, v36, vcc
	v_cmp_gt_u32_e32 vcc, s43, v98
	v_pk_mul_f32 v[98:99], v[108:109], v[178:179]
	s_and_b64 vcc, s[14:15], vcc
	v_sub_f32_e32 v37, v98, v99
	v_add_u32_e32 v99, 0xffffff8d, v147
	v_cvt_f32_u32_e32 v179, v99
	v_cndmask_b32_e32 v37, v252, v37, vcc
	v_cmp_gt_u32_e32 vcc, s43, v99
	v_mov_b32_e32 v108, v30
; __device__ void att_phase(int wv, const Params& p, unsigned char* lds) {
;     ...
;             for (int cb = 0; cb < 24; ++cb) { const int kb = B - 1 + (cb >> 3); const bool bval = (kb >= sb && kb < se);
; #pragma unroll
;                 for (int j = 0; j < 4; ++j) { const int krel = 16 * cb + 4 * lq + j - 128;
;                     int dist = qrow - krel; dist = dist < 0 ? -dist : dist;
;                     const float v = (bval && dist <= 128) ? sc[cb][j] * 0.125f - slope * (float)dist : -1e30f;
;                     sc[cb][j] = v; mx = fmaxf(mx, v); } }
	v_add_u32_e32 v99, 0xffffff8e, v147
	v_pk_mul_f32 v[100:101], v[108:109], v[178:179]
	v_cvt_f32_u32_e32 v179, v99
	s_and_b64 vcc, s[10:11], vcc
	v_sub_f32_e32 v30, v100, v101
	v_mov_b32_e32 v108, v31
	v_cndmask_b32_e32 v30, v252, v30, vcc
	v_cmp_gt_u32_e32 vcc, s43, v99
	v_pk_mul_f32 v[100:101], v[108:109], v[178:179]
	s_and_b64 vcc, s[10:11], vcc
	v_sub_f32_e32 v31, v100, v101
	v_max3_f32 v98, v148, v36, v37
	v_cndmask_b32_e32 v31, v252, v31, vcc
	v_max3_f32 v100, v98, v30, v31
	v_add_u32_e32 v98, 0xffffff8f, v147
	v_cvt_f32_u32_e32 v179, v98
	v_mov_b32_e32 v108, v32
	v_cmp_gt_u32_e32 vcc, s43, v98
	s_and_b64 vcc, s[10:11], vcc
	v_pk_mul_f32 v[98:99], v[108:109], v[178:179]
	v_mov_b32_e32 v108, v33
	v_sub_f32_e32 v32, v98, v99
	v_add_u32_e32 v98, 0xffffff90, v147
	v_cvt_f32_u32_e32 v179, v98
	v_cndmask_b32_e32 v32, v252, v32, vcc
	v_cmp_gt_u32_e32 vcc, s43, v98
	s_and_b64 vcc, s[10:11], vcc
	v_pk_mul_f32 v[98:99], v[108:109], v[178:179]
	v_mov_b32_e32 v108, v26
	v_sub_f32_e32 v33, v98, v99
	v_add_u32_e32 v99, 0xffffff9d, v147
	v_cvt_f32_u32_e32 v179, v99
	v_cndmask_b32_e32 v98, v252, v33, vcc
	v_max3_f32 v33, v100, v32, v98
	v_cmp_gt_u32_e32 vcc, s43, v99
	v_pk_mul_f32 v[100:101], v[108:109], v[178:179]
	s_and_b64 vcc, s[10:11], vcc
	v_sub_f32_e32 v26, v100, v101
	v_cndmask_b32_e32 v99, v252, v26, vcc
	v_add_u32_e32 v26, 0xffffff9e, v147
	v_cvt_f32_u32_e32 v179, v26
	v_mov_b32_e32 v108, v27
	v_cmp_gt_u32_e32 vcc, s43, v26
	s_and_b64 vcc, s[10:11], vcc
	v_pk_mul_f32 v[26:27], v[108:109], v[178:179]
	v_mov_b32_e32 v108, v28
	v_sub_f32_e32 v26, v26, v27
	v_cndmask_b32_e32 v100, v252, v26, vcc
	v_add_u32_e32 v26, 0xffffff9f, v147
	v_cvt_f32_u32_e32 v179, v26
	v_cmp_gt_u32_e32 vcc, s43, v26
	s_and_b64 vcc, s[10:11], vcc
	v_max3_f32 v33, v33, v99, v100
	v_pk_mul_f32 v[26:27], v[108:109], v[178:179]
	v_mov_b32_e32 v108, v29
	v_sub_f32_e32 v26, v26, v27
	v_cndmask_b32_e32 v101, v252, v26, vcc
	v_add_u32_e32 v26, 0xffffffa0, v147
	v_cvt_f32_u32_e32 v179, v26
	v_cmp_gt_u32_e32 vcc, s43, v26
	s_and_b64 vcc, s[10:11], vcc
	s_add_i32 s22, s22, 16
	v_pk_mul_f32 v[26:27], v[108:109], v[178:179]
	v_mov_b32_e32 v108, v22
	v_sub_f32_e32 v26, v26, v27
	v_cndmask_b32_e32 v148, v252, v26, vcc
	v_add_u32_e32 v26, 0xffffffad, v147
	v_cvt_f32_u32_e32 v179, v26
	v_cmp_gt_u32_e32 vcc, s43, v26
	s_and_b64 vcc, s[10:11], vcc
	v_max3_f32 v28, v33, v101, v148
	v_pk_mul_f32 v[26:27], v[108:109], v[178:179]
	v_mov_b32_e32 v108, v23
	v_sub_f32_e32 v22, v26, v27
	v_cndmask_b32_e32 v149, v252, v22, vcc
	v_add_u32_e32 v22, 0xffffffae, v147
	v_cvt_f32_u32_e32 v179, v22
	v_cmp_gt_u32_e32 vcc, s43, v22
	s_and_b64 vcc, s[10:11], vcc
	v_pk_mul_f32 v[22:23], v[108:109], v[178:179]
	s_nop 0
	v_sub_f32_e32 v22, v22, v23
	v_cndmask_b32_e32 v150, v252, v22, vcc
	v_add_u32_e32 v22, 0xffffffaf, v147
	v_cvt_f32_u32_e32 v179, v22
	v_mov_b32_e32 v108, v24
	v_cmp_gt_u32_e32 vcc, s43, v22
	s_and_b64 vcc, s[10:11], vcc
	v_pk_mul_f32 v[22:23], v[108:109], v[178:179]
	v_mov_b32_e32 v108, v25
	v_sub_f32_e32 v22, v22, v23
	v_cndmask_b32_e32 v151, v252, v22, vcc
	v_add_u32_e32 v22, 0xffffffb0, v147
	v_cvt_f32_u32_e32 v179, v22
	v_cmp_gt_u32_e32 vcc, s43, v22
	s_and_b64 vcc, s[10:11], vcc
	v_max3_f32 v26, v28, v149, v150
	v_pk_mul_f32 v[22:23], v[108:109], v[178:179]
	v_mov_b32_e32 v108, v18
	v_sub_f32_e32 v22, v22, v23
	v_cndmask_b32_e32 v152, v252, v22, vcc
	v_add_u32_e32 v22, 0xffffffbd, v147
	v_cvt_f32_u32_e32 v179, v22
	v_cmp_gt_u32_e32 vcc, s43, v22
	s_and_b64 vcc, s[10:11], vcc
	v_max3_f32 v24, v26, v151, v152
	v_pk_mul_f32 v[22:23], v[108:109], v[178:179]
	v_mov_b32_e32 v108, v19
	v_sub_f32_e32 v18, v22, v23
	v_cndmask_b32_e32 v153, v252, v18, vcc
	v_add_u32_e32 v18, 0xffffffbe, v147
	v_cvt_f32_u32_e32 v179, v18
	v_cmp_gt_u32_e32 vcc, s43, v18
	s_and_b64 vcc, s[10:11], vcc
	v_pk_mul_f32 v[18:19], v[108:109], v[178:179]
	s_nop 0
	v_sub_f32_e32 v18, v18, v19
	v_cndmask_b32_e32 v154, v252, v18, vcc
	v_add_u32_e32 v18, 0xffffffbf, v147
	v_cvt_f32_u32_e32 v179, v18
	v_mov_b32_e32 v108, v20
	v_cmp_gt_u32_e32 vcc, s43, v18
	s_and_b64 vcc, s[10:11], vcc
	v_pk_mul_f32 v[18:19], v[108:109], v[178:179]
	v_mov_b32_e32 v108, v21
	v_sub_f32_e32 v18, v18, v19
	v_cndmask_b32_e32 v155, v252, v18, vcc
	v_subrev_u32_e32 v18, 64, v147
	v_cvt_f32_u32_e32 v179, v18
	v_cmp_gt_u32_e32 vcc, s43, v18
	s_and_b64 vcc, s[10:11], vcc
	v_max3_f32 v22, v24, v153, v154
	v_pk_mul_f32 v[18:19], v[108:109], v[178:179]
	v_mov_b32_e32 v108, v14
	v_sub_f32_e32 v18, v18, v19
	v_cndmask_b32_e32 v156, v252, v18, vcc
	v_subrev_u32_e32 v18, 51, v147
	v_cvt_f32_u32_e32 v179, v18
	v_cmp_gt_u32_e32 vcc, s43, v18
	s_and_b64 vcc, s[10:11], vcc
	v_max3_f32 v20, v22, v155, v156
	v_pk_mul_f32 v[18:19], v[108:109], v[178:179]
	v_mov_b32_e32 v108, v15
	v_sub_f32_e32 v14, v18, v19
	v_cndmask_b32_e32 v157, v252, v14, vcc
	v_subrev_u32_e32 v14, 50, v147
	v_cvt_f32_u32_e32 v179, v14
	v_cmp_gt_u32_e32 vcc, s43, v14
	s_and_b64 vcc, s[10:11], vcc
	v_add_u32_e32 v19, -16, v147
	v_pk_mul_f32 v[14:15], v[108:109], v[178:179]
	v_mov_b32_e32 v108, v16
	v_sub_f32_e32 v14, v14, v15
	v_cndmask_b32_e32 v158, v252, v14, vcc
	v_subrev_u32_e32 v14, 49, v147
	v_cvt_f32_u32_e32 v179, v14
	v_cmp_gt_u32_e32 vcc, s43, v14
	s_and_b64 vcc, s[10:11], vcc
	v_max3_f32 v18, v20, v157, v158
	v_pk_mul_f32 v[14:15], v[108:109], v[178:179]
	v_mov_b32_e32 v108, v17
	v_sub_f32_e32 v14, v14, v15
	v_cndmask_b32_e32 v159, v252, v14, vcc
	v_subrev_u32_e32 v14, 48, v147
	v_cvt_f32_u32_e32 v179, v14
	v_cmp_gt_u32_e32 vcc, s43, v14
	s_and_b64 vcc, s[10:11], vcc
	v_pk_mul_f32 v[14:15], v[108:109], v[178:179]
	s_nop 0
	v_sub_f32_e32 v14, v14, v15
	v_cndmask_b32_e32 v160, v252, v14, vcc
; __device__ void att_phase(int wv, const Params& p, unsigned char* lds) {
;     ...
;             for (int cb = 0; cb < 24; ++cb) { const int kb = B - 1 + (cb >> 3); const bool bval = (kb >= sb && kb < se);
; #pragma unroll
;                 for (int j = 0; j < 4; ++j) { const int krel = 16 * cb + 4 * lq + j - 128;
;                     int dist = qrow - krel; dist = dist < 0 ? -dist : dist;
;                     const float v = (bval && dist <= 128) ? sc[cb][j] * 0.125f - slope * (float)dist : -1e30f;
;                     sc[cb][j] = v; mx = fmaxf(mx, v); } }
;             mx = fmaxf(mx, __shfl_xor(mx, 16)); mx = fmaxf(mx, __shfl_xor(mx, 32));
;             float sum = 0.f;
; #pragma unroll
;             for (int cb = 0; cb < 24; ++cb)
; #pragma unroll
;                 for (int j = 0; j < 4; ++j) { const float e = __expf(sc[cb][j] - mx); sc[cb][j] = e; sum += e; }
	v_subrev_u32_e32 v14, 35, v147
	v_cvt_f32_u32_e32 v179, v14
	v_mov_b32_e32 v108, v10
	v_cmp_gt_u32_e32 vcc, s43, v14
	s_and_b64 vcc, s[10:11], vcc
	v_pk_mul_f32 v[14:15], v[108:109], v[178:179]
	v_mov_b32_e32 v108, v11
	v_sub_f32_e32 v10, v14, v15
	v_cndmask_b32_e32 v161, v252, v10, vcc
	v_subrev_u32_e32 v10, 34, v147
	v_cvt_f32_u32_e32 v179, v10
	v_cmp_gt_u32_e32 vcc, s43, v10
	s_and_b64 vcc, s[10:11], vcc
	v_max3_f32 v16, v18, v159, v160
	v_pk_mul_f32 v[10:11], v[108:109], v[178:179]
	v_mov_b32_e32 v108, v12
	v_sub_f32_e32 v10, v10, v11
	v_cndmask_b32_e32 v162, v252, v10, vcc
	v_subrev_u32_e32 v10, 33, v147
	v_cvt_f32_u32_e32 v179, v10
	v_cmp_gt_u32_e32 vcc, s43, v10
	s_and_b64 vcc, s[10:11], vcc
	v_max3_f32 v14, v16, v161, v162
	v_pk_mul_f32 v[10:11], v[108:109], v[178:179]
	v_mov_b32_e32 v108, v13
	v_sub_f32_e32 v10, v10, v11
	v_cndmask_b32_e32 v163, v252, v10, vcc
	v_subrev_u32_e32 v10, 32, v147
	v_cvt_f32_u32_e32 v179, v10
	v_cmp_gt_u32_e32 vcc, s43, v10
	s_and_b64 vcc, s[10:11], vcc
	v_pk_mul_f32 v[10:11], v[108:109], v[178:179]
	s_nop 0
	v_sub_f32_e32 v10, v10, v11
	v_cndmask_b32_e32 v164, v252, v10, vcc
	v_subrev_u32_e32 v10, 19, v147
	v_cvt_f32_u32_e32 v179, v10
	v_mov_b32_e32 v108, v6
	v_cmp_gt_u32_e32 vcc, s43, v10
	s_and_b64 vcc, s[10:11], vcc
	v_pk_mul_f32 v[10:11], v[108:109], v[178:179]
	v_mov_b32_e32 v108, v7
	v_sub_f32_e32 v6, v10, v11
	v_cndmask_b32_e32 v165, v252, v6, vcc
	v_subrev_u32_e32 v6, 18, v147
	v_cvt_f32_u32_e32 v179, v6
	v_cmp_gt_u32_e32 vcc, s43, v6
	s_and_b64 vcc, s[10:11], vcc
	v_max3_f32 v12, v14, v163, v164
	v_pk_mul_f32 v[6:7], v[108:109], v[178:179]
	v_mov_b32_e32 v108, v8
	v_sub_f32_e32 v6, v6, v7
	v_cndmask_b32_e32 v166, v252, v6, vcc
	v_subrev_u32_e32 v6, 17, v147
	v_cvt_f32_u32_e32 v179, v6
	v_cmp_gt_u32_e32 vcc, s43, v6
	s_and_b64 vcc, s[10:11], vcc
	v_max3_f32 v10, v12, v165, v166
	v_pk_mul_f32 v[6:7], v[108:109], v[178:179]
	v_cvt_f32_u32_e32 v179, v19
	v_sub_f32_e32 v6, v6, v7
	v_mov_b32_e32 v108, v9
	v_cndmask_b32_e32 v167, v252, v6, vcc
	v_cmp_gt_u32_e32 vcc, s43, v19
	v_pk_mul_f32 v[6:7], v[108:109], v[178:179]
	s_and_b64 vcc, s[10:11], vcc
	v_sub_f32_e32 v6, v6, v7
	v_cndmask_b32_e32 v168, v252, v6, vcc
	v_add_u32_e32 v6, -3, v147
	v_cvt_f32_u32_e32 v179, v6
	v_mov_b32_e32 v108, v2
	v_cmp_gt_u32_e32 vcc, s43, v6
	s_and_b64 vcc, s[10:11], vcc
	v_pk_mul_f32 v[6:7], v[108:109], v[178:179]
	v_mov_b32_e32 v108, v3
	v_sub_f32_e32 v2, v6, v7
	v_cndmask_b32_e32 v169, v252, v2, vcc
	v_add_u32_e32 v2, -2, v147
	v_cvt_f32_u32_e32 v179, v2
	v_cmp_gt_u32_e32 vcc, s43, v2
	s_and_b64 vcc, s[10:11], vcc
	v_max3_f32 v8, v10, v167, v168
	v_pk_mul_f32 v[2:3], v[108:109], v[178:179]
	v_mov_b32_e32 v108, v4
	v_sub_f32_e32 v2, v2, v3
	v_cndmask_b32_e32 v170, v252, v2, vcc
	v_add_u32_e32 v2, -1, v147
	v_cvt_f32_u32_e32 v179, v2
	v_cmp_gt_u32_e32 vcc, s43, v2
	s_and_b64 vcc, s[10:11], vcc
	v_max3_f32 v6, v8, v169, v170
	v_pk_mul_f32 v[2:3], v[108:109], v[178:179]
	v_cvt_f32_u32_e32 v179, v147
	v_sub_f32_e32 v2, v2, v3
	v_mov_b32_e32 v108, v5
	v_cndmask_b32_e32 v4, v252, v2, vcc
	v_cmp_gt_u32_e32 vcc, s43, v147
	v_pk_mul_f32 v[2:3], v[108:109], v[178:179]
	s_and_b64 vcc, s[10:11], vcc
	v_sub_f32_e32 v2, v2, v3
	v_cndmask_b32_e32 v2, v252, v2, vcc
	v_max3_f32 v3, v6, v4, v2
	ds_bpermute_b32 v5, v1, v3
	s_cmp_eq_u32 s22, 64
	s_waitcnt lgkmcnt(0)
	v_max_f32_e32 v5, v5, v5
	v_max_f32_e32 v3, v3, v5
	ds_bpermute_b32 v5, v114, v3
	s_waitcnt lgkmcnt(0)
	v_max_f32_e32 v5, v5, v5
	v_max_f32_e32 v3, v3, v5
	v_sub_f32_e32 v7, v95, v3
	v_mul_f32_e32 v7, 0x3fb8aa3b, v7
	v_exp_f32_e32 v108, v7
	v_sub_f32_e32 v7, v96, v3
	v_mul_f32_e32 v7, 0x3fb8aa3b, v7
	v_exp_f32_e32 v96, v7
	v_sub_f32_e32 v7, v97, v3
	v_sub_f32_e32 v5, v94, v3
	v_mul_f32_e32 v7, 0x3fb8aa3b, v7
	v_mul_f32_e32 v5, 0x3fb8aa3b, v5
	v_exp_f32_e32 v97, v7
	v_sub_f32_e32 v7, v90, v3
	v_exp_f32_e32 v5, v5
	v_mul_f32_e32 v7, 0x3fb8aa3b, v7
	v_exp_f32_e32 v147, v7
	v_sub_f32_e32 v7, v91, v3
	v_mul_f32_e32 v7, 0x3fb8aa3b, v7
	v_exp_f32_e32 v171, v7
	v_sub_f32_e32 v7, v92, v3
	v_add_f32_e32 v6, 0, v5
	v_mul_f32_e32 v7, 0x3fb8aa3b, v7
	v_add_f32_e32 v6, v108, v6
	v_exp_f32_e32 v172, v7
	v_sub_f32_e32 v7, v93, v3
	v_add_f32_e32 v6, v96, v6
	v_mul_f32_e32 v7, 0x3fb8aa3b, v7
	v_add_f32_e32 v6, v97, v6
	v_exp_f32_e32 v173, v7
	v_add_f32_e32 v6, v147, v6
	v_add_f32_e32 v6, v171, v6
	v_add_f32_e32 v6, v172, v6
	v_add_f32_e32 v7, v173, v6
	v_sub_f32_e32 v6, v86, v3
	v_mul_f32_e32 v6, 0x3fb8aa3b, v6
	v_exp_f32_e32 v6, v6
	v_sub_f32_e32 v13, v84, v3
	v_mul_f32_e32 v13, 0x3fb8aa3b, v13
	v_sub_f32_e32 v14, v85, v3
	v_add_f32_e32 v8, v6, v7
	v_sub_f32_e32 v7, v87, v3
	v_mul_f32_e32 v7, 0x3fb8aa3b, v7
	v_exp_f32_e32 v7, v7
	v_exp_f32_e32 v13, v13
	v_mul_f32_e32 v14, 0x3fb8aa3b, v14
	v_exp_f32_e32 v15, v14
	v_add_f32_e32 v9, v7, v8
	v_sub_f32_e32 v8, v88, v3
	v_mul_f32_e32 v8, 0x3fb8aa3b, v8
	v_exp_f32_e32 v8, v8
	v_sub_f32_e32 v22, v76, v3
	v_mul_f32_e32 v22, 0x3fb8aa3b, v22
	v_sub_f32_e32 v23, v77, v3
	v_add_f32_e32 v10, v8, v9
	v_sub_f32_e32 v9, v89, v3
	v_mul_f32_e32 v9, 0x3fb8aa3b, v9
	v_exp_f32_e32 v9, v9
	v_exp_f32_e32 v22, v22
	v_mul_f32_e32 v23, 0x3fb8aa3b, v23
	v_exp_f32_e32 v24, v23
	v_add_f32_e32 v11, v9, v10
	v_sub_f32_e32 v10, v82, v3
	v_mul_f32_e32 v10, 0x3fb8aa3b, v10
	v_exp_f32_e32 v10, v10
	v_sub_f32_e32 v33, v68, v3
	v_mul_f32_e32 v33, 0x3fb8aa3b, v33
	v_exp_f32_e32 v33, v33
	v_add_f32_e32 v12, v10, v11
	v_sub_f32_e32 v11, v83, v3
	v_mul_f32_e32 v11, 0x3fb8aa3b, v11
	v_exp_f32_e32 v11, v11
	v_sub_f32_e32 v58, v58, v3
	v_mul_f32_e32 v58, 0x3fb8aa3b, v58
	v_sub_f32_e32 v59, v59, v3
	v_add_f32_e32 v12, v11, v12
	v_add_f32_e32 v12, v13, v12
	v_add_f32_e32 v14, v15, v12
; __device__ void att_phase(int wv, const Params& p, unsigned char* lds) {
;     ...
;             float sum = 0.f;
; #pragma unroll
;             for (int cb = 0; cb < 24; ++cb)
; #pragma unroll
;                 for (int j = 0; j < 4; ++j) { const float e = __expf(sc[cb][j] - mx); sc[cb][j] = e; sum += e; }
	v_sub_f32_e32 v12, v78, v3
	v_mul_f32_e32 v12, 0x3fb8aa3b, v12
	v_exp_f32_e32 v12, v12
	v_exp_f32_e32 v58, v58
	v_mul_f32_e32 v59, 0x3fb8aa3b, v59
	v_sub_f32_e32 v60, v60, v3
	v_add_f32_e32 v16, v12, v14
	v_sub_f32_e32 v14, v79, v3
	v_mul_f32_e32 v14, 0x3fb8aa3b, v14
	v_exp_f32_e32 v14, v14
	v_exp_f32_e32 v59, v59
	v_mul_f32_e32 v60, 0x3fb8aa3b, v60
	v_sub_f32_e32 v61, v61, v3
	v_add_f32_e32 v17, v14, v16
	v_sub_f32_e32 v16, v80, v3
	v_mul_f32_e32 v16, 0x3fb8aa3b, v16
	v_exp_f32_e32 v16, v16
	v_exp_f32_e32 v60, v60
	v_mul_f32_e32 v61, 0x3fb8aa3b, v61
	v_sub_f32_e32 v54, v54, v3
	v_add_f32_e32 v18, v16, v17
	v_sub_f32_e32 v17, v81, v3
	v_mul_f32_e32 v17, 0x3fb8aa3b, v17
	v_exp_f32_e32 v17, v17
	v_exp_f32_e32 v61, v61
	v_mul_f32_e32 v54, 0x3fb8aa3b, v54
	v_sub_f32_e32 v55, v55, v3
	v_add_f32_e32 v20, v17, v18
	v_sub_f32_e32 v18, v74, v3
	v_mul_f32_e32 v18, 0x3fb8aa3b, v18
	v_exp_f32_e32 v18, v18
	v_exp_f32_e32 v54, v54
	v_mul_f32_e32 v55, 0x3fb8aa3b, v55
	v_sub_f32_e32 v56, v56, v3
	v_add_f32_e32 v21, v18, v20
	v_sub_f32_e32 v20, v75, v3
	v_mul_f32_e32 v20, 0x3fb8aa3b, v20
	v_exp_f32_e32 v20, v20
	v_exp_f32_e32 v55, v55
	v_mul_f32_e32 v56, 0x3fb8aa3b, v56
	v_sub_f32_e32 v57, v57, v3
	v_add_f32_e32 v21, v20, v21
	v_add_f32_e32 v21, v22, v21
	v_add_f32_e32 v23, v24, v21
	v_sub_f32_e32 v21, v70, v3
	v_mul_f32_e32 v21, 0x3fb8aa3b, v21
	v_exp_f32_e32 v21, v21
	v_exp_f32_e32 v56, v56
	v_mul_f32_e32 v57, 0x3fb8aa3b, v57
	v_sub_f32_e32 v50, v50, v3
	v_add_f32_e32 v25, v21, v23
	v_sub_f32_e32 v23, v71, v3
	v_mul_f32_e32 v23, 0x3fb8aa3b, v23
	v_exp_f32_e32 v23, v23
	v_exp_f32_e32 v57, v57
	v_mul_f32_e32 v50, 0x3fb8aa3b, v50
	v_sub_f32_e32 v51, v51, v3
	v_add_f32_e32 v26, v23, v25
	v_sub_f32_e32 v25, v72, v3
	v_mul_f32_e32 v25, 0x3fb8aa3b, v25
	v_exp_f32_e32 v25, v25
	v_exp_f32_e32 v50, v50
	v_mul_f32_e32 v51, 0x3fb8aa3b, v51
	v_sub_f32_e32 v52, v52, v3
	v_add_f32_e32 v27, v25, v26
	v_sub_f32_e32 v26, v73, v3
	v_mul_f32_e32 v26, 0x3fb8aa3b, v26
	v_exp_f32_e32 v26, v26
	v_exp_f32_e32 v51, v51
	v_mul_f32_e32 v52, 0x3fb8aa3b, v52
	v_sub_f32_e32 v53, v53, v3
	v_add_f32_e32 v28, v26, v27
	v_sub_f32_e32 v27, v66, v3
	v_mul_f32_e32 v27, 0x3fb8aa3b, v27
	v_exp_f32_e32 v27, v27
	v_sub_f32_e32 v66, v69, v3
	v_mul_f32_e32 v66, 0x3fb8aa3b, v66
	v_exp_f32_e32 v66, v66
	v_add_f32_e32 v29, v27, v28
	v_sub_f32_e32 v28, v67, v3
	v_mul_f32_e32 v28, 0x3fb8aa3b, v28
	v_exp_f32_e32 v28, v28
	v_exp_f32_e32 v52, v52
	v_mul_f32_e32 v53, 0x3fb8aa3b, v53
	v_sub_f32_e32 v46, v46, v3
	v_add_f32_e32 v29, v28, v29
	v_add_f32_e32 v29, v33, v29
	v_add_f32_e32 v67, v66, v29
	v_sub_f32_e32 v29, v62, v3
	v_mul_f32_e32 v29, 0x3fb8aa3b, v29
	v_sub_f32_e32 v62, v63, v3
	v_exp_f32_e32 v29, v29
	v_mul_f32_e32 v62, 0x3fb8aa3b, v62
	v_sub_f32_e32 v63, v64, v3
	v_exp_f32_e32 v62, v62
	v_mul_f32_e32 v63, 0x3fb8aa3b, v63
	v_sub_f32_e32 v64, v65, v3
	v_exp_f32_e32 v63, v63
	v_mul_f32_e32 v64, 0x3fb8aa3b, v64
	v_exp_f32_e32 v64, v64
	v_add_f32_e32 v67, v29, v67
	v_add_f32_e32 v67, v62, v67
	v_add_f32_e32 v67, v63, v67
	v_add_f32_e32 v65, v64, v67
	v_add_f32_e32 v65, v58, v65
	v_add_f32_e32 v65, v59, v65
	v_add_f32_e32 v65, v60, v65
	v_add_f32_e32 v65, v61, v65
	v_add_f32_e32 v65, v54, v65
	v_add_f32_e32 v65, v55, v65
	v_add_f32_e32 v65, v56, v65
	v_add_f32_e32 v65, v57, v65
	v_exp_f32_e32 v53, v53
	v_mul_f32_e32 v46, 0x3fb8aa3b, v46
	v_sub_f32_e32 v47, v47, v3
	v_add_f32_e32 v65, v50, v65
	v_exp_f32_e32 v46, v46
	v_mul_f32_e32 v47, 0x3fb8aa3b, v47
	v_sub_f32_e32 v48, v48, v3
	v_add_f32_e32 v65, v51, v65
	v_exp_f32_e32 v47, v47
	v_mul_f32_e32 v48, 0x3fb8aa3b, v48
	v_sub_f32_e32 v49, v49, v3
	v_add_f32_e32 v65, v52, v65
	v_exp_f32_e32 v48, v48
	v_mul_f32_e32 v49, 0x3fb8aa3b, v49
	v_sub_f32_e32 v42, v42, v3
	v_add_f32_e32 v65, v53, v65
	v_exp_f32_e32 v49, v49
	v_mul_f32_e32 v42, 0x3fb8aa3b, v42
	v_sub_f32_e32 v43, v43, v3
	v_add_f32_e32 v65, v46, v65
	v_exp_f32_e32 v42, v42
	v_mul_f32_e32 v43, 0x3fb8aa3b, v43
	v_sub_f32_e32 v44, v44, v3
	v_add_f32_e32 v65, v47, v65
	v_exp_f32_e32 v43, v43
	v_mul_f32_e32 v44, 0x3fb8aa3b, v44
	v_sub_f32_e32 v45, v45, v3
	v_add_f32_e32 v65, v48, v65
	v_exp_f32_e32 v44, v44
	v_mul_f32_e32 v45, 0x3fb8aa3b, v45
	v_sub_f32_e32 v38, v38, v3
	v_add_f32_e32 v65, v49, v65
	v_exp_f32_e32 v45, v45
	v_mul_f32_e32 v38, 0x3fb8aa3b, v38
	v_sub_f32_e32 v39, v39, v3
	v_add_f32_e32 v65, v42, v65
	v_exp_f32_e32 v38, v38
	v_mul_f32_e32 v39, 0x3fb8aa3b, v39
	v_sub_f32_e32 v40, v40, v3
	v_add_f32_e32 v65, v43, v65
	v_exp_f32_e32 v39, v39
	v_mul_f32_e32 v40, 0x3fb8aa3b, v40
	v_sub_f32_e32 v41, v41, v3
	v_add_f32_e32 v65, v44, v65
	v_exp_f32_e32 v40, v40
	v_mul_f32_e32 v41, 0x3fb8aa3b, v41
	v_sub_f32_e32 v34, v34, v3
	v_add_f32_e32 v65, v45, v65
	v_exp_f32_e32 v41, v41
	v_mul_f32_e32 v34, 0x3fb8aa3b, v34
	v_sub_f32_e32 v35, v35, v3
	v_add_f32_e32 v65, v38, v65
	v_exp_f32_e32 v34, v34
	v_mul_f32_e32 v35, 0x3fb8aa3b, v35
	v_sub_f32_e32 v36, v36, v3
	v_add_f32_e32 v65, v39, v65
	v_exp_f32_e32 v35, v35
	v_mul_f32_e32 v36, 0x3fb8aa3b, v36
	v_sub_f32_e32 v37, v37, v3
	v_add_f32_e32 v65, v40, v65
	v_exp_f32_e32 v36, v36
	v_mul_f32_e32 v37, 0x3fb8aa3b, v37
	v_sub_f32_e32 v30, v30, v3
	v_add_f32_e32 v65, v41, v65
	v_exp_f32_e32 v37, v37
	v_mul_f32_e32 v30, 0x3fb8aa3b, v30
	v_sub_f32_e32 v31, v31, v3
	v_add_f32_e32 v65, v34, v65
	v_exp_f32_e32 v30, v30
	v_mul_f32_e32 v31, 0x3fb8aa3b, v31
	v_sub_f32_e32 v32, v32, v3
	v_add_f32_e32 v65, v35, v65
	v_exp_f32_e32 v31, v31
	v_mul_f32_e32 v32, 0x3fb8aa3b, v32
	v_add_f32_e32 v65, v36, v65
	v_exp_f32_e32 v32, v32
	v_add_f32_e32 v65, v37, v65
	v_add_f32_e32 v65, v30, v65
	v_add_f32_e32 v65, v31, v65
	v_add_f32_e32 v67, v32, v65
	v_sub_f32_e32 v65, v98, v3
; __device__ __forceinline__ unsigned cvt_pk_bf16_asm(float lo, float hi) { unsigned r; asm volatile("v_cvt_pk_bf16_f32 %0, %1, %2" : "=v"(r) : "v"(lo), "v"(hi)); return r; }
; __device__ __forceinline__ f32x4 mfma16(bf16x8 a, bf16x8 b, f32x4 c) { return __builtin_amdgcn_mfma_f32_16x16x32_bf16(a, b, c, 0, 0, 0); }
; __device__ void att_phase(int wv, const Params& p, unsigned char* lds) {
;     ...
;             for (int cb = 0; cb < 24; ++cb)
; #pragma unroll
;                 for (int j = 0; j < 4; ++j) { const float e = __expf(sc[cb][j] - mx); sc[cb][j] = e; sum += e; }
;             sum += __shfl_xor(sum, 16); sum += __shfl_xor(sum, 32);
;             sum += __expf(sink - mx);
;             const float inv = 1.0f / sum;
;             f32x4 oa[4];
; #pragma unroll
;             for (int db = 0; db < 4; ++db) oa[db] = (f32x4){0, 0, 0, 0};
; #pragma unroll
;             for (int ks = 0; ks < 12; ++ks) {
;                 union { bf16x8 v; unsigned u[4]; } pf;
;                 pf.u[0] = cvt_pk_bf16_asm(sc[2 * ks][0], sc[2 * ks][1]); pf.u[1] = cvt_pk_bf16_asm(sc[2 * ks][2], sc[2 * ks][3]);
;                 pf.u[2] = cvt_pk_bf16_asm(sc[2 * ks + 1][0], sc[2 * ks + 1][1]); pf.u[3] = cvt_pk_bf16_asm(sc[2 * ks + 1][2], sc[2 * ks + 1][3]);
; #pragma unroll
;                 for (int db = 0; db < 4; ++db) {
;                     union { bf16x8 v; u32x2 h2[2]; } vf;
;                     const bf16_t* vp = VTL + (16 * db + lr) * VP + 32 * ks + 4 * lq;
;                     vf.h2[0] = *(const u32x2*)vp; vf.h2[1] = *(const u32x2*)(vp + 16);
;                     oa[db] = mfma16(vf.v, pf.v, oa[db]); } }
; #pragma unroll
;             for (int db = 0; db < 4; ++db) { const f32x4 o = oa[db] * inv; u32x2 wv; wv.x = cvt_pk_bf16_asm(o[0], o[1]); wv.y = cvt_pk_bf16_asm(o[2], o[3]);
;                 *(u32x2*)(qkv + tokq * 1536 + 64 * h + 16 * db + 4 * lq) = wv; }
;         }
;         __syncthreads();
;     }
	v_mul_f32_e32 v65, 0x3fb8aa3b, v65
	v_exp_f32_e32 v65, v65
	v_sub_f32_e32 v70, v101, v3
	v_mul_f32_e32 v70, 0x3fb8aa3b, v70
	v_sub_f32_e32 v71, v148, v3
	v_add_f32_e32 v68, v65, v67
	v_sub_f32_e32 v67, v99, v3
	v_mul_f32_e32 v67, 0x3fb8aa3b, v67
	v_exp_f32_e32 v67, v67
	v_exp_f32_e32 v70, v70
	v_mul_f32_e32 v71, 0x3fb8aa3b, v71
	v_exp_f32_e32 v72, v71
	v_add_f32_e32 v69, v67, v68
	v_sub_f32_e32 v68, v100, v3
	v_mul_f32_e32 v68, 0x3fb8aa3b, v68
	v_exp_f32_e32 v68, v68
	v_sub_f32_e32 v78, v155, v3
	v_mul_f32_e32 v78, 0x3fb8aa3b, v78
	v_sub_f32_e32 v79, v156, v3
	v_add_f32_e32 v69, v68, v69
	v_add_f32_e32 v69, v70, v69
	v_add_f32_e32 v71, v72, v69
	v_sub_f32_e32 v69, v149, v3
	v_mul_f32_e32 v69, 0x3fb8aa3b, v69
	v_exp_f32_e32 v69, v69
	v_exp_f32_e32 v78, v78
	v_mul_f32_e32 v79, 0x3fb8aa3b, v79
	v_exp_f32_e32 v80, v79
	v_add_f32_e32 v73, v69, v71
	v_sub_f32_e32 v71, v150, v3
	v_mul_f32_e32 v71, 0x3fb8aa3b, v71
	v_exp_f32_e32 v71, v71
	v_sub_f32_e32 v86, v163, v3
	v_mul_f32_e32 v86, 0x3fb8aa3b, v86
	v_sub_f32_e32 v87, v164, v3
	v_add_f32_e32 v74, v71, v73
	v_sub_f32_e32 v73, v151, v3
	v_mul_f32_e32 v73, 0x3fb8aa3b, v73
	v_exp_f32_e32 v73, v73
	v_exp_f32_e32 v86, v86
	v_mul_f32_e32 v87, 0x3fb8aa3b, v87
	v_exp_f32_e32 v88, v87
	v_add_f32_e32 v75, v73, v74
	v_sub_f32_e32 v74, v152, v3
	v_mul_f32_e32 v74, 0x3fb8aa3b, v74
	v_exp_f32_e32 v74, v74
	v_sub_f32_e32 v93, v170, v3
	v_mul_f32_e32 v93, 0x3fb8aa3b, v93
	v_sub_f32_e32 v4, v4, v3
	v_add_f32_e32 v76, v74, v75
	v_sub_f32_e32 v75, v153, v3
	v_mul_f32_e32 v75, 0x3fb8aa3b, v75
	v_exp_f32_e32 v75, v75
	v_exp_f32_e32 v93, v93
	v_mul_f32_e32 v4, 0x3fb8aa3b, v4
	v_sub_f32_e32 v2, v2, v3
	v_add_f32_e32 v77, v75, v76
	v_sub_f32_e32 v76, v154, v3
	v_mul_f32_e32 v76, 0x3fb8aa3b, v76
	v_exp_f32_e32 v76, v76
	v_exp_f32_e32 v94, v4
	v_mul_f32_e32 v2, 0x3fb8aa3b, v2
	v_exp_f32_e32 v95, v2
	v_add_f32_e32 v77, v76, v77
	v_add_f32_e32 v77, v78, v77
	v_add_f32_e32 v79, v80, v77
	v_sub_f32_e32 v77, v157, v3
	v_mul_f32_e32 v77, 0x3fb8aa3b, v77
	v_exp_f32_e32 v77, v77
	v_add_u32_e32 v100, 0xd800, v142
	v_add_u32_e32 v101, 0xd800, v143
	v_add_f32_e32 v81, v77, v79
	v_sub_f32_e32 v79, v158, v3
	v_mul_f32_e32 v79, 0x3fb8aa3b, v79
	v_exp_f32_e32 v79, v79
	s_nop 0
	v_add_f32_e32 v82, v79, v81
	v_sub_f32_e32 v81, v159, v3
	v_mul_f32_e32 v81, 0x3fb8aa3b, v81
	v_exp_f32_e32 v81, v81
	s_nop 0
	v_add_f32_e32 v83, v81, v82
	v_sub_f32_e32 v82, v160, v3
	v_mul_f32_e32 v82, 0x3fb8aa3b, v82
	v_exp_f32_e32 v82, v82
	s_nop 0
	v_add_f32_e32 v84, v82, v83
	v_sub_f32_e32 v83, v161, v3
	v_mul_f32_e32 v83, 0x3fb8aa3b, v83
	v_exp_f32_e32 v83, v83
	s_nop 0
	v_add_f32_e32 v85, v83, v84
	v_sub_f32_e32 v84, v162, v3
	v_mul_f32_e32 v84, 0x3fb8aa3b, v84
	v_exp_f32_e32 v84, v84
	s_nop 0
	v_add_f32_e32 v85, v84, v85
	v_add_f32_e32 v85, v86, v85
	v_add_f32_e32 v87, v88, v85
	v_sub_f32_e32 v85, v165, v3
	v_mul_f32_e32 v85, 0x3fb8aa3b, v85
	v_exp_f32_e32 v85, v85
	s_nop 0
	v_add_f32_e32 v89, v85, v87
	v_sub_f32_e32 v87, v166, v3
	v_mul_f32_e32 v87, 0x3fb8aa3b, v87
	v_exp_f32_e32 v87, v87
	s_nop 0
	v_add_f32_e32 v90, v87, v89
	v_sub_f32_e32 v89, v167, v3
	v_mul_f32_e32 v89, 0x3fb8aa3b, v89
	v_exp_f32_e32 v89, v89
	s_nop 0
	v_add_f32_e32 v91, v89, v90
	v_sub_f32_e32 v90, v168, v3
	v_mul_f32_e32 v90, 0x3fb8aa3b, v90
	v_exp_f32_e32 v90, v90
	s_nop 0
	v_add_f32_e32 v92, v90, v91
	v_sub_f32_e32 v91, v169, v3
	v_mul_f32_e32 v91, 0x3fb8aa3b, v91
	v_exp_f32_e32 v91, v91
	v_sub_f32_e32 v3, v146, v3
	v_mul_f32_e32 v3, 0x3fb8aa3b, v3
	v_exp_f32_e32 v3, v3
	v_add_f32_e32 v92, v91, v92
	v_add_f32_e32 v92, v93, v92
	v_add_f32_e32 v4, v94, v92
	v_add_f32_e32 v2, v95, v4
	ds_bpermute_b32 v4, v1, v2
	s_waitcnt lgkmcnt(0)
	v_add_f32_e32 v2, v2, v4
	ds_bpermute_b32 v4, v114, v2
	s_waitcnt lgkmcnt(0)
	v_add_f32_e32 v2, v2, v4
	v_add_f32_e32 v92, v3, v2
	v_cvt_pk_bf16_f32 v2, v5, v108
	v_cvt_pk_bf16_f32 v3, v96, v97
	v_cvt_pk_bf16_f32 v4, v147, v171
	v_add_u32_e32 v108, 0xd800, v144
	v_add_u32_e32 v147, 0xd800, v145
	v_cvt_pk_bf16_f32 v5, v172, v173
	ds_read2_b64 v[96:99], v100 offset1:4
	ds_read2_b64 v[148:151], v101 offset1:4
	ds_read2_b64 v[152:155], v108 offset1:4
	ds_read2_b64 v[156:159], v147 offset1:4
	s_waitcnt lgkmcnt(3)
	v_mfma_f32_16x16x32_bf16 v[96:99], v[96:99], v[2:5], 0
	v_cvt_pk_bf16_f32 v6, v6, v7
	v_cvt_pk_bf16_f32 v7, v8, v9
	v_cvt_pk_bf16_f32 v8, v10, v11
	s_waitcnt lgkmcnt(2)
	v_mfma_f32_16x16x32_bf16 v[148:151], v[148:151], v[2:5], 0
	v_cvt_pk_bf16_f32 v9, v13, v15
	s_waitcnt lgkmcnt(1)
	v_mfma_f32_16x16x32_bf16 v[152:155], v[152:155], v[2:5], 0
	s_waitcnt lgkmcnt(0)
	v_mfma_f32_16x16x32_bf16 v[2:5], v[156:159], v[2:5], 0
	ds_read2_b64 v[156:159], v100 offset0:8 offset1:12
	s_waitcnt lgkmcnt(0)
	v_mfma_f32_16x16x32_bf16 v[96:99], v[156:159], v[6:9], v[96:99]
	ds_read2_b64 v[156:159], v101 offset0:8 offset1:12
	s_waitcnt lgkmcnt(0)
	v_mfma_f32_16x16x32_bf16 v[148:151], v[156:159], v[6:9], v[148:151]
	ds_read2_b64 v[156:159], v108 offset0:8 offset1:12
	s_waitcnt lgkmcnt(0)
	v_mfma_f32_16x16x32_bf16 v[152:155], v[156:159], v[6:9], v[152:155]
	ds_read2_b64 v[156:159], v147 offset0:8 offset1:12
	s_waitcnt lgkmcnt(0)
	v_mfma_f32_16x16x32_bf16 v[2:5], v[156:159], v[6:9], v[2:5]
	v_cvt_pk_bf16_f32 v6, v12, v14
	v_cvt_pk_bf16_f32 v7, v16, v17
	v_cvt_pk_bf16_f32 v8, v18, v20
	v_cvt_pk_bf16_f32 v9, v22, v24
	ds_read2_b64 v[10:13], v100 offset0:16 offset1:20
	ds_read2_b64 v[14:17], v101 offset0:16 offset1:20
	s_waitcnt lgkmcnt(1)
	v_mfma_f32_16x16x32_bf16 v[10:13], v[10:13], v[6:9], v[96:99]
	s_nop 2
	ds_read2_b64 v[96:99], v108 offset0:16 offset1:20
	v_div_scale_f32 v18, s[46:47], v92, v92, 1.0
	s_waitcnt lgkmcnt(1)
; __device__ __forceinline__ unsigned cvt_pk_bf16_asm(float lo, float hi) { unsigned r; asm volatile("v_cvt_pk_bf16_f32 %0, %1, %2" : "=v"(r) : "v"(lo), "v"(hi)); return r; }
; __device__ __forceinline__ f32x4 mfma16(bf16x8 a, bf16x8 b, f32x4 c) { return __builtin_amdgcn_mfma_f32_16x16x32_bf16(a, b, c, 0, 0, 0); }
; __device__ void att_phase(int wv, const Params& p, unsigned char* lds) {
;     ...
;             for (int ks = 0; ks < 12; ++ks) {
;                 union { bf16x8 v; unsigned u[4]; } pf;
;                 pf.u[0] = cvt_pk_bf16_asm(sc[2 * ks][0], sc[2 * ks][1]); pf.u[1] = cvt_pk_bf16_asm(sc[2 * ks][2], sc[2 * ks][3]);
;                 pf.u[2] = cvt_pk_bf16_asm(sc[2 * ks + 1][0], sc[2 * ks + 1][1]); pf.u[3] = cvt_pk_bf16_asm(sc[2 * ks + 1][2], sc[2 * ks + 1][3]);
; #pragma unroll
;                 for (int db = 0; db < 4; ++db) {
;                     union { bf16x8 v; u32x2 h2[2]; } vf;
;                     const bf16_t* vp = VTL + (16 * db + lr) * VP + 32 * ks + 4 * lq;
;                     vf.h2[0] = *(const u32x2*)vp; vf.h2[1] = *(const u32x2*)(vp + 16);
;                     oa[db] = mfma16(vf.v, pf.v, oa[db]); } }
	v_mfma_f32_16x16x32_bf16 v[14:17], v[14:17], v[6:9], v[148:151]
	s_nop 2
	ds_read2_b64 v[148:151], v147 offset0:16 offset1:20
	s_waitcnt lgkmcnt(1)
	v_mfma_f32_16x16x32_bf16 v[96:99], v[96:99], v[6:9], v[152:155]
	s_waitcnt lgkmcnt(0)
	v_mfma_f32_16x16x32_bf16 v[2:5], v[148:151], v[6:9], v[2:5]
	v_cvt_pk_bf16_f32 v6, v21, v23
	v_cvt_pk_bf16_f32 v7, v25, v26
	v_cvt_pk_bf16_f32 v8, v27, v28
	v_cvt_pk_bf16_f32 v9, v33, v66
	ds_read2_b64 v[20:23], v100 offset0:24 offset1:28
	s_waitcnt lgkmcnt(0)
	v_mfma_f32_16x16x32_bf16 v[10:13], v[20:23], v[6:9], v[10:13]
	ds_read2_b64 v[20:23], v101 offset0:24 offset1:28
	ds_read2_b64 v[24:27], v147 offset0:24 offset1:28
	s_waitcnt lgkmcnt(1)
	v_mfma_f32_16x16x32_bf16 v[14:17], v[20:23], v[6:9], v[14:17]
	ds_read2_b64 v[20:23], v108 offset0:24 offset1:28
	s_waitcnt lgkmcnt(0)
	v_mfma_f32_16x16x32_bf16 v[20:23], v[20:23], v[6:9], v[96:99]
	v_mfma_f32_16x16x32_bf16 v[2:5], v[24:27], v[6:9], v[2:5]
	v_cvt_pk_bf16_f32 v6, v29, v62
	v_cvt_pk_bf16_f32 v7, v63, v64
	v_cvt_pk_bf16_f32 v8, v58, v59
	v_cvt_pk_bf16_f32 v9, v60, v61
	ds_read2_b64 v[24:27], v100 offset0:32 offset1:36
	s_waitcnt lgkmcnt(0)
	v_mfma_f32_16x16x32_bf16 v[10:13], v[24:27], v[6:9], v[10:13]
	ds_read2_b64 v[24:27], v101 offset0:32 offset1:36
	s_waitcnt lgkmcnt(0)
	v_mfma_f32_16x16x32_bf16 v[14:17], v[24:27], v[6:9], v[14:17]
	ds_read2_b64 v[24:27], v108 offset0:32 offset1:36
	s_waitcnt lgkmcnt(0)
	v_mfma_f32_16x16x32_bf16 v[20:23], v[24:27], v[6:9], v[20:23]
	ds_read2_b64 v[24:27], v147 offset0:32 offset1:36
	s_waitcnt lgkmcnt(0)
	v_mfma_f32_16x16x32_bf16 v[2:5], v[24:27], v[6:9], v[2:5]
	v_cvt_pk_bf16_f32 v6, v54, v55
	v_cvt_pk_bf16_f32 v7, v56, v57
	v_cvt_pk_bf16_f32 v8, v50, v51
	v_cvt_pk_bf16_f32 v9, v52, v53
	ds_read2_b64 v[24:27], v100 offset0:40 offset1:44
	s_waitcnt lgkmcnt(0)
	v_mfma_f32_16x16x32_bf16 v[10:13], v[24:27], v[6:9], v[10:13]
	ds_read2_b64 v[24:27], v101 offset0:40 offset1:44
	s_waitcnt lgkmcnt(0)
	v_mfma_f32_16x16x32_bf16 v[14:17], v[24:27], v[6:9], v[14:17]
	ds_read2_b64 v[24:27], v108 offset0:40 offset1:44
	s_waitcnt lgkmcnt(0)
	v_mfma_f32_16x16x32_bf16 v[20:23], v[24:27], v[6:9], v[20:23]
	ds_read2_b64 v[24:27], v147 offset0:40 offset1:44
	s_waitcnt lgkmcnt(0)
	v_mfma_f32_16x16x32_bf16 v[2:5], v[24:27], v[6:9], v[2:5]
	v_cvt_pk_bf16_f32 v6, v46, v47
	v_cvt_pk_bf16_f32 v7, v48, v49
	v_cvt_pk_bf16_f32 v8, v42, v43
	v_cvt_pk_bf16_f32 v9, v44, v45
	ds_read2_b64 v[24:27], v100 offset0:48 offset1:52
	s_waitcnt lgkmcnt(0)
	v_mfma_f32_16x16x32_bf16 v[10:13], v[24:27], v[6:9], v[10:13]
	ds_read2_b64 v[24:27], v101 offset0:48 offset1:52
	s_waitcnt lgkmcnt(0)
	v_mfma_f32_16x16x32_bf16 v[14:17], v[24:27], v[6:9], v[14:17]
	ds_read2_b64 v[24:27], v108 offset0:48 offset1:52
	s_waitcnt lgkmcnt(0)
	v_mfma_f32_16x16x32_bf16 v[20:23], v[24:27], v[6:9], v[20:23]
	ds_read2_b64 v[24:27], v147 offset0:48 offset1:52
	s_waitcnt lgkmcnt(0)
	v_mfma_f32_16x16x32_bf16 v[2:5], v[24:27], v[6:9], v[2:5]
	v_cvt_pk_bf16_f32 v6, v38, v39
	v_cvt_pk_bf16_f32 v7, v40, v41
	v_cvt_pk_bf16_f32 v8, v34, v35
	v_cvt_pk_bf16_f32 v9, v36, v37
	ds_read2_b64 v[24:27], v100 offset0:56 offset1:60
	s_waitcnt lgkmcnt(0)
	v_mfma_f32_16x16x32_bf16 v[10:13], v[24:27], v[6:9], v[10:13]
	ds_read2_b64 v[24:27], v101 offset0:56 offset1:60
	s_waitcnt lgkmcnt(0)
	v_mfma_f32_16x16x32_bf16 v[14:17], v[24:27], v[6:9], v[14:17]
	ds_read2_b64 v[24:27], v108 offset0:56 offset1:60
	s_waitcnt lgkmcnt(0)
	v_mfma_f32_16x16x32_bf16 v[20:23], v[24:27], v[6:9], v[20:23]
	ds_read2_b64 v[24:27], v147 offset0:56 offset1:60
	s_waitcnt lgkmcnt(0)
	v_mfma_f32_16x16x32_bf16 v[2:5], v[24:27], v[6:9], v[2:5]
	v_cvt_pk_bf16_f32 v6, v30, v31
	v_cvt_pk_bf16_f32 v7, v32, v65
	v_cvt_pk_bf16_f32 v8, v67, v68
	v_cvt_pk_bf16_f32 v9, v70, v72
	ds_read2_b64 v[24:27], v100 offset0:64 offset1:68
	s_waitcnt lgkmcnt(0)
	v_mfma_f32_16x16x32_bf16 v[10:13], v[24:27], v[6:9], v[10:13]
	ds_read2_b64 v[24:27], v101 offset0:64 offset1:68
	s_waitcnt lgkmcnt(0)
; __device__ __forceinline__ unsigned cvt_pk_bf16_asm(float lo, float hi) { unsigned r; asm volatile("v_cvt_pk_bf16_f32 %0, %1, %2" : "=v"(r) : "v"(lo), "v"(hi)); return r; }
; __device__ __forceinline__ f32x4 mfma16(bf16x8 a, bf16x8 b, f32x4 c) { return __builtin_amdgcn_mfma_f32_16x16x32_bf16(a, b, c, 0, 0, 0); }
; __device__ void att_phase(int wv, const Params& p, unsigned char* lds) {
;     ...
;             const float inv = 1.0f / sum;
;             f32x4 oa[4];
; #pragma unroll
;             for (int db = 0; db < 4; ++db) oa[db] = (f32x4){0, 0, 0, 0};
; #pragma unroll
;             for (int ks = 0; ks < 12; ++ks) {
;                 union { bf16x8 v; unsigned u[4]; } pf;
;                 pf.u[0] = cvt_pk_bf16_asm(sc[2 * ks][0], sc[2 * ks][1]); pf.u[1] = cvt_pk_bf16_asm(sc[2 * ks][2], sc[2 * ks][3]);
;                 pf.u[2] = cvt_pk_bf16_asm(sc[2 * ks + 1][0], sc[2 * ks + 1][1]); pf.u[3] = cvt_pk_bf16_asm(sc[2 * ks + 1][2], sc[2 * ks + 1][3]);
; #pragma unroll
;                 for (int db = 0; db < 4; ++db) {
;                     union { bf16x8 v; u32x2 h2[2]; } vf;
;                     const bf16_t* vp = VTL + (16 * db + lr) * VP + 32 * ks + 4 * lq;
;                     vf.h2[0] = *(const u32x2*)vp; vf.h2[1] = *(const u32x2*)(vp + 16);
;                     oa[db] = mfma16(vf.v, pf.v, oa[db]); } }
; #pragma unroll
;             for (int db = 0; db < 4; ++db) { const f32x4 o = oa[db] * inv; u32x2 wv; wv.x = cvt_pk_bf16_asm(o[0], o[1]); wv.y = cvt_pk_bf16_asm(o[2], o[3]);
;                 *(u32x2*)(qkv + tokq * 1536 + 64 * h + 16 * db + 4 * lq) = wv; }
;         }
;         __syncthreads();
;     }
	v_mfma_f32_16x16x32_bf16 v[14:17], v[24:27], v[6:9], v[14:17]
	ds_read2_b64 v[24:27], v108 offset0:64 offset1:68
	s_waitcnt lgkmcnt(0)
	v_mfma_f32_16x16x32_bf16 v[20:23], v[24:27], v[6:9], v[20:23]
	ds_read2_b64 v[24:27], v147 offset0:64 offset1:68
	s_waitcnt lgkmcnt(0)
	v_mfma_f32_16x16x32_bf16 v[2:5], v[24:27], v[6:9], v[2:5]
	v_cvt_pk_bf16_f32 v6, v69, v71
	v_cvt_pk_bf16_f32 v7, v73, v74
	v_cvt_pk_bf16_f32 v8, v75, v76
	v_cvt_pk_bf16_f32 v9, v78, v80
	ds_read2_b64 v[24:27], v100 offset0:72 offset1:76
	s_waitcnt lgkmcnt(0)
	v_mfma_f32_16x16x32_bf16 v[10:13], v[24:27], v[6:9], v[10:13]
	ds_read2_b64 v[24:27], v101 offset0:72 offset1:76
	s_waitcnt lgkmcnt(0)
	v_mfma_f32_16x16x32_bf16 v[14:17], v[24:27], v[6:9], v[14:17]
	ds_read2_b64 v[24:27], v108 offset0:72 offset1:76
	s_waitcnt lgkmcnt(0)
	v_mfma_f32_16x16x32_bf16 v[20:23], v[24:27], v[6:9], v[20:23]
	ds_read2_b64 v[24:27], v147 offset0:72 offset1:76
	s_waitcnt lgkmcnt(0)
	v_mfma_f32_16x16x32_bf16 v[2:5], v[24:27], v[6:9], v[2:5]
	v_cvt_pk_bf16_f32 v6, v77, v79
	v_cvt_pk_bf16_f32 v7, v81, v82
	v_cvt_pk_bf16_f32 v8, v83, v84
	v_cvt_pk_bf16_f32 v9, v86, v88
	ds_read2_b64 v[24:27], v100 offset0:80 offset1:84
	s_waitcnt lgkmcnt(0)
	v_mfma_f32_16x16x32_bf16 v[10:13], v[24:27], v[6:9], v[10:13]
	ds_read2_b64 v[24:27], v101 offset0:80 offset1:84
	s_waitcnt lgkmcnt(0)
	v_mfma_f32_16x16x32_bf16 v[24:27], v[24:27], v[6:9], v[14:17]
	s_nop 2
	ds_read2_b64 v[14:17], v108 offset0:80 offset1:84
	s_waitcnt lgkmcnt(0)
	v_mfma_f32_16x16x32_bf16 v[20:23], v[14:17], v[6:9], v[20:23]
	ds_read2_b64 v[14:17], v147 offset0:80 offset1:84
	v_cvt_pk_bf16_f32 v28, v85, v87
	v_cvt_pk_bf16_f32 v29, v89, v90
	s_waitcnt lgkmcnt(0)
	v_mfma_f32_16x16x32_bf16 v[2:5], v[14:17], v[6:9], v[2:5]
	v_cvt_pk_bf16_f32 v30, v91, v93
	v_cvt_pk_bf16_f32 v31, v94, v95
	ds_read2_b64 v[6:9], v100 offset0:88 offset1:92
	s_waitcnt lgkmcnt(0)
	v_mfma_f32_16x16x32_bf16 v[14:17], v[6:9], v[28:31], v[10:13]
	ds_read2_b64 v[6:9], v101 offset0:88 offset1:92
	s_waitcnt lgkmcnt(0)
	v_mfma_f32_16x16x32_bf16 v[10:13], v[6:9], v[28:31], v[24:27]
	ds_read2_b64 v[6:9], v108 offset0:88 offset1:92
	s_waitcnt lgkmcnt(0)
	v_mfma_f32_16x16x32_bf16 v[6:9], v[6:9], v[28:31], v[20:23]
	s_nop 2
	ds_read2_b64 v[20:23], v147 offset0:88 offset1:92
	v_mov_b32_e32 v147, v19
	s_waitcnt lgkmcnt(0)
	v_mfma_f32_16x16x32_bf16 v[2:5], v[20:23], v[28:31], v[2:5]
	v_rcp_f32_e32 v20, v18
	s_nop 0
	v_fma_f32 v21, -v18, v20, 1.0
	v_fmac_f32_e32 v20, v21, v20
	v_div_scale_f32 v21, vcc, 1.0, v92, 1.0
	v_mul_f32_e32 v22, v21, v20
	v_fma_f32 v23, -v18, v22, v21
	v_fmac_f32_e32 v22, v23, v20
	v_fma_f32 v18, -v18, v22, v21
	v_div_fmas_f32 v18, v18, v20, v22
	v_div_fixup_f32 v18, v18, v92, 1.0
	v_lshl_add_u64 v[20:21], v[112:113], 0, s[0:1]
	v_pk_mul_f32 v[14:15], v[18:19], v[14:15] op_sel_hi:[0,1]
	v_pk_mul_f32 v[10:11], v[18:19], v[10:11] op_sel_hi:[0,1]
	v_pk_mul_f32 v[6:7], v[18:19], v[6:7] op_sel_hi:[0,1]
	v_pk_mul_f32 v[2:3], v[18:19], v[2:3] op_sel_hi:[0,1]
	v_lshl_add_u64 v[112:113], v[112:113], 0, s[48:49]
	v_pk_mul_f32 v[16:17], v[18:19], v[16:17] op_sel_hi:[0,1]
	v_cvt_pk_bf16_f32 v14, v14, v15
	v_cvt_pk_bf16_f32 v15, v16, v17
	global_store_dwordx2 v[20:21], v[14:15], off offset:-64
	v_pk_mul_f32 v[12:13], v[18:19], v[12:13] op_sel_hi:[0,1]
	v_cvt_pk_bf16_f32 v10, v10, v11
	v_cvt_pk_bf16_f32 v11, v12, v13
	global_store_dwordx2 v[20:21], v[10:11], off offset:-32
	v_pk_mul_f32 v[8:9], v[18:19], v[8:9] op_sel_hi:[0,1]
	v_cvt_pk_bf16_f32 v6, v6, v7
	v_cvt_pk_bf16_f32 v7, v8, v9
	global_store_dwordx2 v[20:21], v[6:7], off
	v_pk_mul_f32 v[4:5], v[18:19], v[4:5] op_sel_hi:[0,1]
	v_cvt_pk_bf16_f32 v2, v2, v3
	v_cvt_pk_bf16_f32 v3, v4, v5
	global_store_dwordx2 v[20:21], v[2:3], off offset:32
	s_cbranch_scc0 .LBB0_306
.Latt_done:
	s_add_i32 s21, s21, s34
	s_add_i32 s20, s20, s34
	s_cmpk_gt_i32 s21, 0x3ff
	s_barrier
	s_cbranch_scc0 .LBB0_293
